# v26 with every remaining s_setprio removed (priority-free kernel)
# baseline (speedup 1.0000x reference)
.LBB0_285:
	ds_read_b128 v[154:157], v151
	ds_read_b128 v[158:161], v151 offset:1024
	ds_read_b128 v[164:167], v151 offset:2048
	ds_read_b128 v[168:171], v151 offset:3072
	ds_read_b128 v[172:175], v152
	ds_read_b128 v[176:179], v152 offset:1024
	ds_read_b128 v[180:183], v152 offset:2048
	ds_read_b128 v[184:187], v152 offset:3072
	s_add_u32 s36, s34, 0xfff80080
	s_addc_u32 s37, s35, -1
	s_cmp_eq_u32 s53, 28
	s_cselect_b32 s39, s16, s37
	s_cselect_b32 s38, s17, s36
	s_cselect_b32 s37, s18, s25
	s_cselect_b32 s36, s19, s23
	v_lshl_add_u64 v[146:147], s[34:35], 0, v[138:139]
	s_add_i32 m0, s31, 0xc000
	ds_read_b128 v[188:191], v153
	ds_read_b128 v[192:195], v153 offset:1024
	ds_read_b128 v[196:199], v153 offset:2048
	ds_read_b128 v[200:203], v153 offset:3072
	ds_read_b128 v[204:207], v153 offset:4096
	ds_read_b128 v[208:211], v153 offset:5120
	ds_read_b128 v[212:215], v153 offset:6144
	ds_read_b128 v[216:219], v153 offset:7168
	global_load_lds_dwordx4 v[146:147], off
	v_lshl_add_u64 v[146:147], s[34:35], 0, v[140:141]
	s_add_i32 m0, s31, 0xe000
	s_nop 0
	global_load_lds_dwordx4 v[146:147], off
	s_waitcnt vmcnt(8)
	s_waitcnt lgkmcnt(0)
	v_mfma_f32_16x16x32_bf16 v[126:129], v[154:157], v[188:191], v[126:129]
	v_mfma_f32_16x16x32_bf16 v[122:125], v[164:167], v[188:191], v[122:125]
	v_mfma_f32_16x16x32_bf16 v[110:113], v[154:157], v[196:199], v[110:113]
	v_mfma_f32_16x16x32_bf16 v[106:109], v[164:167], v[196:199], v[106:109]
	s_barrier
	v_mfma_f32_16x16x32_bf16 v[94:97], v[154:157], v[204:207], v[94:97]
	v_mfma_f32_16x16x32_bf16 v[90:93], v[164:167], v[204:207], v[90:93]
	v_mfma_f32_16x16x32_bf16 v[78:81], v[154:157], v[212:215], v[78:81]
	v_mfma_f32_16x16x32_bf16 v[74:77], v[164:167], v[212:215], v[74:77]
	v_mfma_f32_16x16x32_bf16 v[126:129], v[158:161], v[192:195], v[126:129]
	v_mfma_f32_16x16x32_bf16 v[122:125], v[168:171], v[192:195], v[122:125]
	v_mfma_f32_16x16x32_bf16 v[110:113], v[158:161], v[200:203], v[110:113]
	v_mfma_f32_16x16x32_bf16 v[106:109], v[168:171], v[200:203], v[106:109]
	v_mfma_f32_16x16x32_bf16 v[94:97], v[158:161], v[208:211], v[94:97]
	v_mfma_f32_16x16x32_bf16 v[90:93], v[168:171], v[208:211], v[90:93]
	v_mfma_f32_16x16x32_bf16 v[78:81], v[158:161], v[216:219], v[78:81]
	v_mfma_f32_16x16x32_bf16 v[74:77], v[168:171], v[216:219], v[74:77]
	v_mfma_f32_16x16x32_bf16 v[118:121], v[172:175], v[188:191], v[118:121]
	v_mfma_f32_16x16x32_bf16 v[114:117], v[180:183], v[188:191], v[114:117]
	v_mfma_f32_16x16x32_bf16 v[102:105], v[172:175], v[196:199], v[102:105]
	v_mfma_f32_16x16x32_bf16 v[98:101], v[180:183], v[196:199], v[98:101]
	v_mfma_f32_16x16x32_bf16 v[86:89], v[172:175], v[204:207], v[86:89]
	v_mfma_f32_16x16x32_bf16 v[82:85], v[180:183], v[204:207], v[82:85]
	v_mfma_f32_16x16x32_bf16 v[70:73], v[172:175], v[212:215], v[70:73]
	v_mfma_f32_16x16x32_bf16 v[66:69], v[180:183], v[212:215], v[66:69]
	v_mfma_f32_16x16x32_bf16 v[118:121], v[176:179], v[192:195], v[118:121]
	v_mfma_f32_16x16x32_bf16 v[114:117], v[184:187], v[192:195], v[114:117]
	v_mfma_f32_16x16x32_bf16 v[102:105], v[176:179], v[200:203], v[102:105]
	v_mfma_f32_16x16x32_bf16 v[98:101], v[184:187], v[200:203], v[98:101]
	v_mfma_f32_16x16x32_bf16 v[86:89], v[176:179], v[208:211], v[86:89]
	v_mfma_f32_16x16x32_bf16 v[82:85], v[184:187], v[208:211], v[82:85]
	v_mfma_f32_16x16x32_bf16 v[70:73], v[176:179], v[216:219], v[70:73]
	v_mfma_f32_16x16x32_bf16 v[66:69], v[184:187], v[216:219], v[66:69]
	s_barrier
	s_add_i32 s54, s15, s44
	v_lshl_add_u64 v[146:147], s[36:37], 0, v[134:135]
	s_mov_b32 m0, s54
	ds_read_b128 v[188:191], v153 offset:16384
	ds_read_b128 v[192:195], v153 offset:17408
	ds_read_b128 v[196:199], v153 offset:18432
	ds_read_b128 v[200:203], v153 offset:19456
	ds_read_b128 v[204:207], v153 offset:20480
	ds_read_b128 v[208:211], v153 offset:21504
	ds_read_b128 v[212:215], v153 offset:22528
	ds_read_b128 v[216:219], v153 offset:23552
	global_load_lds_dwordx4 v[146:147], off
	s_add_i32 m0, s54, 0x2000
	s_add_u32 s54, s36, 0x80000
	v_lshl_add_u64 v[220:221], s[36:37], 0, v[130:131]
	s_addc_u32 s55, s37, 0
	s_add_i32 s56, s51, s44
	global_load_lds_dwordx4 v[220:221], off
	v_lshl_add_u64 v[222:223], s[54:55], 0, v[134:135]
	s_mov_b32 m0, s56
	v_lshl_add_u64 v[224:225], s[38:39], 0, v[132:133]
	global_load_lds_dwordx4 v[222:223], off
	v_lshl_add_u64 v[222:223], s[54:55], 0, v[130:131]
	s_add_i32 m0, s56, 0x2000
	s_nop 0
	global_load_lds_dwordx4 v[222:223], off
	v_lshl_add_u64 v[222:223], s[38:39], 0, v[136:137]
	s_mov_b32 m0, s31
	s_nop 0
	global_load_lds_dwordx4 v[222:223], off
	s_mov_b32 m0, s47
	s_nop 0
	global_load_lds_dwordx4 v[224:225], off
	s_waitcnt vmcnt(8)
	s_waitcnt lgkmcnt(0)
	v_mfma_f32_16x16x32_bf16 v[62:65], v[154:157], v[188:191], v[62:65]
	v_mfma_f32_16x16x32_bf16 v[58:61], v[164:167], v[188:191], v[58:61]
	v_mfma_f32_16x16x32_bf16 v[46:49], v[154:157], v[196:199], v[46:49]
	v_mfma_f32_16x16x32_bf16 v[42:45], v[164:167], v[196:199], v[42:45]
	s_barrier
	v_mfma_f32_16x16x32_bf16 v[30:33], v[154:157], v[204:207], v[30:33]
	v_mfma_f32_16x16x32_bf16 v[26:29], v[164:167], v[204:207], v[26:29]
	v_mfma_f32_16x16x32_bf16 v[14:17], v[154:157], v[212:215], v[14:17]
	v_mfma_f32_16x16x32_bf16 v[10:13], v[164:167], v[212:215], v[10:13]
	v_mfma_f32_16x16x32_bf16 v[62:65], v[158:161], v[192:195], v[62:65]
	v_mfma_f32_16x16x32_bf16 v[58:61], v[168:171], v[192:195], v[58:61]
	v_mfma_f32_16x16x32_bf16 v[46:49], v[158:161], v[200:203], v[46:49]
	v_mfma_f32_16x16x32_bf16 v[42:45], v[168:171], v[200:203], v[42:45]
	v_mfma_f32_16x16x32_bf16 v[30:33], v[158:161], v[208:211], v[30:33]
	v_mfma_f32_16x16x32_bf16 v[26:29], v[168:171], v[208:211], v[26:29]
	v_mfma_f32_16x16x32_bf16 v[14:17], v[158:161], v[216:219], v[14:17]
	v_mfma_f32_16x16x32_bf16 v[10:13], v[168:171], v[216:219], v[10:13]
	v_mfma_f32_16x16x32_bf16 v[54:57], v[172:175], v[188:191], v[54:57]
	v_mfma_f32_16x16x32_bf16 v[50:53], v[180:183], v[188:191], v[50:53]
	v_mfma_f32_16x16x32_bf16 v[38:41], v[172:175], v[196:199], v[38:41]
	v_mfma_f32_16x16x32_bf16 v[34:37], v[180:183], v[196:199], v[34:37]
	v_mfma_f32_16x16x32_bf16 v[22:25], v[172:175], v[204:207], v[22:25]
	v_mfma_f32_16x16x32_bf16 v[18:21], v[180:183], v[204:207], v[18:21]
	v_mfma_f32_16x16x32_bf16 v[6:9], v[172:175], v[212:215], v[6:9]
	v_mfma_f32_16x16x32_bf16 v[2:5], v[180:183], v[212:215], v[2:5]
	v_mfma_f32_16x16x32_bf16 v[54:57], v[176:179], v[192:195], v[54:57]
	v_mfma_f32_16x16x32_bf16 v[50:53], v[184:187], v[192:195], v[50:53]
	v_mfma_f32_16x16x32_bf16 v[38:41], v[176:179], v[200:203], v[38:41]
	v_mfma_f32_16x16x32_bf16 v[34:37], v[184:187], v[200:203], v[34:37]
	v_mfma_f32_16x16x32_bf16 v[22:25], v[176:179], v[208:211], v[22:25]
	v_mfma_f32_16x16x32_bf16 v[18:21], v[184:187], v[208:211], v[18:21]
	v_mfma_f32_16x16x32_bf16 v[6:9], v[176:179], v[216:219], v[6:9]
	v_mfma_f32_16x16x32_bf16 v[2:5], v[184:187], v[216:219], v[2:5]
	s_barrier
	s_add_i32 s54, 0, 0x18000
	v_add_u32_e32 v163, s54, v149
	s_add_i32 s55, 0, 0x1c000
	ds_read_b128 v[154:157], v163
	ds_read_b128 v[158:161], v163 offset:1024
	ds_read_b128 v[164:167], v163 offset:2048
	ds_read_b128 v[168:171], v163 offset:3072
	v_add_u32_e32 v163, s55, v149
	ds_read_b128 v[172:175], v163
	ds_read_b128 v[176:179], v163 offset:1024
	ds_read_b128 v[180:183], v163 offset:2048
	ds_read_b128 v[184:187], v163 offset:3072
	s_add_u32 s38, s38, 0x80000
	s_addc_u32 s39, s39, 0
	s_mov_b32 m0, s48
	v_lshl_add_u64 v[226:227], s[38:39], 0, v[136:137]
	ds_read_b128 v[188:191], v153 offset:32768
	ds_read_b128 v[192:195], v153 offset:33792
	ds_read_b128 v[196:199], v153 offset:34816
	ds_read_b128 v[200:203], v153 offset:35840
	ds_read_b128 v[204:207], v153 offset:36864
	ds_read_b128 v[208:211], v153 offset:37888
	ds_read_b128 v[212:215], v153 offset:38912
	ds_read_b128 v[216:219], v153 offset:39936
	global_load_lds_dwordx4 v[226:227], off
	v_lshl_add_u64 v[226:227], s[38:39], 0, v[132:133]
	s_mov_b32 m0, s49
	s_nop 0
	global_load_lds_dwordx4 v[226:227], off
	s_waitcnt vmcnt(8)
	s_waitcnt lgkmcnt(0)
	v_mfma_f32_16x16x32_bf16 v[126:129], v[154:157], v[188:191], v[126:129]
	v_mfma_f32_16x16x32_bf16 v[122:125], v[164:167], v[188:191], v[122:125]
	v_mfma_f32_16x16x32_bf16 v[110:113], v[154:157], v[196:199], v[110:113]
	v_mfma_f32_16x16x32_bf16 v[106:109], v[164:167], v[196:199], v[106:109]
	s_barrier
	v_mfma_f32_16x16x32_bf16 v[94:97], v[154:157], v[204:207], v[94:97]
	v_mfma_f32_16x16x32_bf16 v[90:93], v[164:167], v[204:207], v[90:93]
	v_mfma_f32_16x16x32_bf16 v[78:81], v[154:157], v[212:215], v[78:81]
	v_mfma_f32_16x16x32_bf16 v[74:77], v[164:167], v[212:215], v[74:77]
	v_mfma_f32_16x16x32_bf16 v[126:129], v[158:161], v[192:195], v[126:129]
	v_mfma_f32_16x16x32_bf16 v[122:125], v[168:171], v[192:195], v[122:125]
	v_mfma_f32_16x16x32_bf16 v[110:113], v[158:161], v[200:203], v[110:113]
	v_mfma_f32_16x16x32_bf16 v[106:109], v[168:171], v[200:203], v[106:109]
	v_mfma_f32_16x16x32_bf16 v[94:97], v[158:161], v[208:211], v[94:97]
	v_mfma_f32_16x16x32_bf16 v[90:93], v[168:171], v[208:211], v[90:93]
	v_mfma_f32_16x16x32_bf16 v[78:81], v[158:161], v[216:219], v[78:81]
	v_mfma_f32_16x16x32_bf16 v[74:77], v[168:171], v[216:219], v[74:77]
	v_mfma_f32_16x16x32_bf16 v[118:121], v[172:175], v[188:191], v[118:121]
	v_mfma_f32_16x16x32_bf16 v[114:117], v[180:183], v[188:191], v[114:117]
	v_mfma_f32_16x16x32_bf16 v[102:105], v[172:175], v[196:199], v[102:105]
	v_mfma_f32_16x16x32_bf16 v[98:101], v[180:183], v[196:199], v[98:101]
	v_mfma_f32_16x16x32_bf16 v[86:89], v[172:175], v[204:207], v[86:89]
	v_mfma_f32_16x16x32_bf16 v[82:85], v[180:183], v[204:207], v[82:85]
	v_mfma_f32_16x16x32_bf16 v[70:73], v[172:175], v[212:215], v[70:73]
	v_mfma_f32_16x16x32_bf16 v[66:69], v[180:183], v[212:215], v[66:69]
	v_mfma_f32_16x16x32_bf16 v[118:121], v[176:179], v[192:195], v[118:121]
	v_mfma_f32_16x16x32_bf16 v[114:117], v[184:187], v[192:195], v[114:117]
	v_mfma_f32_16x16x32_bf16 v[102:105], v[176:179], v[200:203], v[102:105]
	v_mfma_f32_16x16x32_bf16 v[98:101], v[184:187], v[200:203], v[98:101]
	v_mfma_f32_16x16x32_bf16 v[86:89], v[176:179], v[208:211], v[86:89]
	v_mfma_f32_16x16x32_bf16 v[82:85], v[184:187], v[208:211], v[82:85]
	v_mfma_f32_16x16x32_bf16 v[70:73], v[176:179], v[216:219], v[70:73]
	v_mfma_f32_16x16x32_bf16 v[66:69], v[184:187], v[216:219], v[66:69]
	s_barrier
	s_add_i32 s38, s54, s44
	v_lshl_add_u64 v[146:147], v[146:147], 0, s[10:11]
	s_mov_b32 m0, s38
	ds_read_b128 v[188:191], v153 offset:49152
	ds_read_b128 v[192:195], v153 offset:50176
	ds_read_b128 v[196:199], v153 offset:51200
	ds_read_b128 v[200:203], v153 offset:52224
	ds_read_b128 v[204:207], v153 offset:53248
	ds_read_b128 v[208:211], v153 offset:54272
	ds_read_b128 v[212:215], v153 offset:55296
	ds_read_b128 v[216:219], v153 offset:56320
	global_load_lds_dwordx4 v[146:147], off
	s_add_i32 m0, s38, 0x2000
	s_add_u32 s36, s36, 0x80080
	v_lshl_add_u64 v[146:147], v[220:221], 0, s[10:11]
	s_addc_u32 s37, s37, 0
	s_add_i32 s38, s55, s44
	global_load_lds_dwordx4 v[146:147], off
	v_lshl_add_u64 v[146:147], s[36:37], 0, v[134:135]
	s_mov_b32 m0, s38
	s_nop 0
	global_load_lds_dwordx4 v[146:147], off
	v_lshl_add_u64 v[146:147], s[36:37], 0, v[130:131]
	s_add_i32 m0, s38, 0x2000
	s_nop 0
	global_load_lds_dwordx4 v[146:147], off
	v_lshl_add_u64 v[146:147], v[222:223], 0, s[10:11]
	s_mov_b32 m0, s20
	s_nop 0
	global_load_lds_dwordx4 v[146:147], off
	v_lshl_add_u64 v[146:147], v[224:225], 0, s[10:11]
	s_mov_b32 m0, s21
	s_nop 0
	global_load_lds_dwordx4 v[146:147], off
	s_waitcnt vmcnt(8)
	s_waitcnt lgkmcnt(0)
	v_mfma_f32_16x16x32_bf16 v[62:65], v[154:157], v[188:191], v[62:65]
	v_mfma_f32_16x16x32_bf16 v[58:61], v[164:167], v[188:191], v[58:61]
	v_mfma_f32_16x16x32_bf16 v[46:49], v[154:157], v[196:199], v[46:49]
	v_mfma_f32_16x16x32_bf16 v[42:45], v[164:167], v[196:199], v[42:45]
	s_barrier
	v_mfma_f32_16x16x32_bf16 v[30:33], v[154:157], v[204:207], v[30:33]
	v_mfma_f32_16x16x32_bf16 v[26:29], v[164:167], v[204:207], v[26:29]
	v_mfma_f32_16x16x32_bf16 v[14:17], v[154:157], v[212:215], v[14:17]
	v_mfma_f32_16x16x32_bf16 v[10:13], v[164:167], v[212:215], v[10:13]
	v_mfma_f32_16x16x32_bf16 v[62:65], v[158:161], v[192:195], v[62:65]
	v_mfma_f32_16x16x32_bf16 v[58:61], v[168:171], v[192:195], v[58:61]
	v_mfma_f32_16x16x32_bf16 v[46:49], v[158:161], v[200:203], v[46:49]
	v_mfma_f32_16x16x32_bf16 v[42:45], v[168:171], v[200:203], v[42:45]
	v_mfma_f32_16x16x32_bf16 v[30:33], v[158:161], v[208:211], v[30:33]
	v_mfma_f32_16x16x32_bf16 v[26:29], v[168:171], v[208:211], v[26:29]
	v_mfma_f32_16x16x32_bf16 v[14:17], v[158:161], v[216:219], v[14:17]
	v_mfma_f32_16x16x32_bf16 v[10:13], v[168:171], v[216:219], v[10:13]
	v_mfma_f32_16x16x32_bf16 v[54:57], v[172:175], v[188:191], v[54:57]
	v_mfma_f32_16x16x32_bf16 v[50:53], v[180:183], v[188:191], v[50:53]
	v_mfma_f32_16x16x32_bf16 v[38:41], v[172:175], v[196:199], v[38:41]
	v_mfma_f32_16x16x32_bf16 v[34:37], v[180:183], v[196:199], v[34:37]
	v_mfma_f32_16x16x32_bf16 v[22:25], v[172:175], v[204:207], v[22:25]
	v_mfma_f32_16x16x32_bf16 v[18:21], v[180:183], v[204:207], v[18:21]
	v_mfma_f32_16x16x32_bf16 v[6:9], v[172:175], v[212:215], v[6:9]
	v_mfma_f32_16x16x32_bf16 v[2:5], v[180:183], v[212:215], v[2:5]
	v_mfma_f32_16x16x32_bf16 v[54:57], v[176:179], v[192:195], v[54:57]
	v_mfma_f32_16x16x32_bf16 v[50:53], v[184:187], v[192:195], v[50:53]
	v_mfma_f32_16x16x32_bf16 v[38:41], v[176:179], v[200:203], v[38:41]
	v_mfma_f32_16x16x32_bf16 v[34:37], v[184:187], v[200:203], v[34:37]
	v_mfma_f32_16x16x32_bf16 v[22:25], v[176:179], v[208:211], v[22:25]
	v_mfma_f32_16x16x32_bf16 v[18:21], v[184:187], v[208:211], v[18:21]
	v_mfma_f32_16x16x32_bf16 v[6:9], v[176:179], v[216:219], v[6:9]
	v_mfma_f32_16x16x32_bf16 v[2:5], v[184:187], v[216:219], v[2:5]
	s_barrier
	s_add_i32 s53, s53, 2
	s_add_u32 s34, s34, 0x100
	s_addc_u32 s35, s35, 0
	s_add_u32 s23, s23, 0x100
	s_addc_u32 s25, s25, 0
	s_cmp_gt_u32 s53, 29
	s_cbranch_scc0 .LBB0_285
	s_and_b64 vcc, exec, s[12:13]
	s_cbranch_vccz .LBB0_288
	s_barrier

.LBB0_356:
	ds_read_b128 v[134:137], v213
	ds_read_b128 v[138:141], v213 offset:1024
	ds_read_b128 v[142:145], v213 offset:2048
	ds_read_b128 v[178:181], v213 offset:3072
	ds_read_b128 v[182:185], v214
	ds_read_b128 v[186:189], v214 offset:1024
	ds_read_b128 v[190:193], v214 offset:2048
	ds_read_b128 v[194:197], v214 offset:3072
	s_add_u32 s36, s34, 0x100
	s_addc_u32 s37, s35, 0
	s_add_u32 s16, s3, s34
	s_addc_u32 s17, s14, s35
	s_cmpk_eq_i32 s15, 0x54
	s_cselect_b32 s41, s27, s17
	s_cselect_b32 s17, 0, s36
	s_cselect_b32 s40, s26, s16
	s_cselect_b32 s16, 0, s37
	s_add_u32 s38, s8, s17
	s_addc_u32 s39, s9, s16
	s_mov_b32 m0, s63
	v_lshl_add_u64 v[244:245], v[130:131], 0, s[34:35]
	ds_read_b128 v[198:201], v215
	ds_read_b128 v[202:205], v215 offset:1024
	ds_read_b128 v[206:209], v215 offset:2048
	ds_read_b128 v[224:227], v215 offset:3072
	ds_read_b128 v[228:231], v215 offset:4096
	ds_read_b128 v[232:235], v215 offset:5120
	ds_read_b128 v[236:239], v215 offset:6144
	ds_read_b128 v[240:243], v215 offset:7168
	global_load_lds_dwordx4 v[244:245], off
	v_lshl_add_u64 v[244:245], v[132:133], 0, s[34:35]
	s_mov_b32 m0, s64
	s_nop 0
	global_load_lds_dwordx4 v[244:245], off
	s_waitcnt vmcnt(8)
	s_waitcnt lgkmcnt(0)
	v_mfma_f32_16x16x32_bf16 v[86:89], v[134:137], v[198:201], v[86:89]
	v_mfma_f32_16x16x32_bf16 v[82:85], v[142:145], v[198:201], v[82:85]
	v_mfma_f32_16x16x32_bf16 v[110:113], v[134:137], v[206:209], v[110:113]
	v_mfma_f32_16x16x32_bf16 v[106:109], v[142:145], v[206:209], v[106:109]
	s_barrier
	v_mfma_f32_16x16x32_bf16 v[118:121], v[134:137], v[228:231], v[118:121]
	v_mfma_f32_16x16x32_bf16 v[114:117], v[142:145], v[228:231], v[114:117]
	v_mfma_f32_16x16x32_bf16 v[126:129], v[134:137], v[236:239], v[126:129]
	v_mfma_f32_16x16x32_bf16 v[122:125], v[142:145], v[236:239], v[122:125]
	v_mfma_f32_16x16x32_bf16 v[86:89], v[138:141], v[202:205], v[86:89]
	v_mfma_f32_16x16x32_bf16 v[82:85], v[178:181], v[202:205], v[82:85]
	v_mfma_f32_16x16x32_bf16 v[110:113], v[138:141], v[224:227], v[110:113]
	v_mfma_f32_16x16x32_bf16 v[106:109], v[178:181], v[224:227], v[106:109]
	v_mfma_f32_16x16x32_bf16 v[118:121], v[138:141], v[232:235], v[118:121]
	v_mfma_f32_16x16x32_bf16 v[114:117], v[178:181], v[232:235], v[114:117]
	v_mfma_f32_16x16x32_bf16 v[126:129], v[138:141], v[240:243], v[126:129]
	v_mfma_f32_16x16x32_bf16 v[122:125], v[178:181], v[240:243], v[122:125]
	v_mfma_f32_16x16x32_bf16 v[26:29], v[182:185], v[198:201], v[26:29]
	v_mfma_f32_16x16x32_bf16 v[30:33], v[190:193], v[198:201], v[30:33]
	v_mfma_f32_16x16x32_bf16 v[42:45], v[182:185], v[206:209], v[42:45]
	v_mfma_f32_16x16x32_bf16 v[50:53], v[190:193], v[206:209], v[50:53]
	v_mfma_f32_16x16x32_bf16 v[66:69], v[182:185], v[228:231], v[66:69]
	v_mfma_f32_16x16x32_bf16 v[70:73], v[190:193], v[228:231], v[70:73]
	v_mfma_f32_16x16x32_bf16 v[90:93], v[182:185], v[236:239], v[90:93]
	v_mfma_f32_16x16x32_bf16 v[94:97], v[190:193], v[236:239], v[94:97]
	v_mfma_f32_16x16x32_bf16 v[26:29], v[186:189], v[202:205], v[26:29]
	v_mfma_f32_16x16x32_bf16 v[30:33], v[194:197], v[202:205], v[30:33]
	v_mfma_f32_16x16x32_bf16 v[42:45], v[186:189], v[224:227], v[42:45]
	v_mfma_f32_16x16x32_bf16 v[50:53], v[194:197], v[224:227], v[50:53]
	v_mfma_f32_16x16x32_bf16 v[66:69], v[186:189], v[232:235], v[66:69]
	v_mfma_f32_16x16x32_bf16 v[70:73], v[194:197], v[232:235], v[70:73]
	v_mfma_f32_16x16x32_bf16 v[90:93], v[186:189], v[240:243], v[90:93]
	v_mfma_f32_16x16x32_bf16 v[94:97], v[194:197], v[240:243], v[94:97]
	s_barrier
	s_mov_b32 m0, s65
	v_lshl_add_u64 v[244:245], s[38:39], 0, v[150:151]
	s_add_u32 s16, s38, 0x160000
	ds_read_b128 v[198:201], v215 offset:16384
	ds_read_b128 v[202:205], v215 offset:17408
	ds_read_b128 v[206:209], v215 offset:18432
	ds_read_b128 v[224:227], v215 offset:19456
	ds_read_b128 v[228:231], v215 offset:20480
	ds_read_b128 v[232:235], v215 offset:21504
	ds_read_b128 v[236:239], v215 offset:22528
	ds_read_b128 v[240:243], v215 offset:23552
	global_load_lds_dwordx4 v[244:245], off
	v_lshl_add_u64 v[246:247], s[38:39], 0, v[146:147]
	s_mov_b32 m0, s66
	s_addc_u32 s17, s39, 0
	global_load_lds_dwordx4 v[246:247], off
	v_lshl_add_u64 v[248:249], s[16:17], 0, v[150:151]
	s_mov_b32 m0, s67
	v_lshl_add_u64 v[250:251], s[40:41], 0, v[148:149]
	global_load_lds_dwordx4 v[248:249], off
	v_lshl_add_u64 v[248:249], s[16:17], 0, v[146:147]
	s_mov_b32 m0, s68
	s_nop 0
	global_load_lds_dwordx4 v[248:249], off
	v_lshl_add_u64 v[248:249], s[40:41], 0, v[152:153]
	s_mov_b32 m0, s51
	s_nop 0
	global_load_lds_dwordx4 v[248:249], off
	s_mov_b32 m0, s52
	s_nop 0
	global_load_lds_dwordx4 v[250:251], off
	s_waitcnt vmcnt(8)
	s_waitcnt lgkmcnt(0)
	v_mfma_f32_16x16x32_bf16 v[102:105], v[134:137], v[198:201], v[102:105]
	v_mfma_f32_16x16x32_bf16 v[98:101], v[142:145], v[198:201], v[98:101]
	v_mfma_f32_16x16x32_bf16 v[62:65], v[134:137], v[206:209], v[62:65]
	v_mfma_f32_16x16x32_bf16 v[58:61], v[142:145], v[206:209], v[58:61]
	s_barrier
	v_mfma_f32_16x16x32_bf16 v[38:41], v[134:137], v[228:231], v[38:41]
	v_mfma_f32_16x16x32_bf16 v[34:37], v[142:145], v[228:231], v[34:37]
	v_mfma_f32_16x16x32_bf16 v[14:17], v[134:137], v[236:239], v[14:17]
	v_mfma_f32_16x16x32_bf16 v[10:13], v[142:145], v[236:239], v[10:13]
	v_mfma_f32_16x16x32_bf16 v[102:105], v[138:141], v[202:205], v[102:105]
	v_mfma_f32_16x16x32_bf16 v[98:101], v[178:181], v[202:205], v[98:101]
	v_mfma_f32_16x16x32_bf16 v[62:65], v[138:141], v[224:227], v[62:65]
	v_mfma_f32_16x16x32_bf16 v[58:61], v[178:181], v[224:227], v[58:61]
	v_mfma_f32_16x16x32_bf16 v[38:41], v[138:141], v[232:235], v[38:41]
	v_mfma_f32_16x16x32_bf16 v[34:37], v[178:181], v[232:235], v[34:37]
	v_mfma_f32_16x16x32_bf16 v[14:17], v[138:141], v[240:243], v[14:17]
	v_mfma_f32_16x16x32_bf16 v[10:13], v[178:181], v[240:243], v[10:13]
	v_mfma_f32_16x16x32_bf16 v[78:81], v[182:185], v[198:201], v[78:81]
	v_mfma_f32_16x16x32_bf16 v[74:77], v[190:193], v[198:201], v[74:77]
	v_mfma_f32_16x16x32_bf16 v[54:57], v[182:185], v[206:209], v[54:57]
	v_mfma_f32_16x16x32_bf16 v[46:49], v[190:193], v[206:209], v[46:49]
	v_mfma_f32_16x16x32_bf16 v[22:25], v[182:185], v[228:231], v[22:25]
	v_mfma_f32_16x16x32_bf16 v[18:21], v[190:193], v[228:231], v[18:21]
	v_mfma_f32_16x16x32_bf16 v[6:9], v[182:185], v[236:239], v[6:9]
	v_mfma_f32_16x16x32_bf16 v[2:5], v[190:193], v[236:239], v[2:5]
	v_mfma_f32_16x16x32_bf16 v[78:81], v[186:189], v[202:205], v[78:81]
	v_mfma_f32_16x16x32_bf16 v[74:77], v[194:197], v[202:205], v[74:77]
	v_mfma_f32_16x16x32_bf16 v[54:57], v[186:189], v[224:227], v[54:57]
	v_mfma_f32_16x16x32_bf16 v[46:49], v[194:197], v[224:227], v[46:49]
	v_mfma_f32_16x16x32_bf16 v[22:25], v[186:189], v[232:235], v[22:25]
	v_mfma_f32_16x16x32_bf16 v[18:21], v[194:197], v[232:235], v[18:21]
	v_mfma_f32_16x16x32_bf16 v[6:9], v[186:189], v[240:243], v[6:9]
	v_mfma_f32_16x16x32_bf16 v[2:5], v[194:197], v[240:243], v[2:5]
	s_barrier
	ds_read_b128 v[134:137], v219
	ds_read_b128 v[138:141], v219 offset:1024
	ds_read_b128 v[142:145], v219 offset:2048
	ds_read_b128 v[178:181], v219 offset:3072
	ds_read_b128 v[182:185], v220
	ds_read_b128 v[186:189], v220 offset:1024
	ds_read_b128 v[190:193], v220 offset:2048
	ds_read_b128 v[194:197], v220 offset:3072
	s_add_u32 s16, s40, 0x160000
	s_addc_u32 s17, s41, 0
	s_mov_b32 m0, s53
	v_lshl_add_u64 v[252:253], s[16:17], 0, v[152:153]
	ds_read_b128 v[198:201], v215 offset:32768
	ds_read_b128 v[202:205], v215 offset:33792
	ds_read_b128 v[206:209], v215 offset:34816
	ds_read_b128 v[224:227], v215 offset:35840
	ds_read_b128 v[228:231], v215 offset:36864
	ds_read_b128 v[232:235], v215 offset:37888
	ds_read_b128 v[236:239], v215 offset:38912
	ds_read_b128 v[240:243], v215 offset:39936
	global_load_lds_dwordx4 v[252:253], off
	v_lshl_add_u64 v[252:253], s[16:17], 0, v[148:149]
	s_mov_b32 m0, s54
	s_nop 0
	global_load_lds_dwordx4 v[252:253], off
	s_waitcnt vmcnt(8)
	s_waitcnt lgkmcnt(0)
	v_mfma_f32_16x16x32_bf16 v[86:89], v[134:137], v[198:201], v[86:89]
	v_mfma_f32_16x16x32_bf16 v[82:85], v[142:145], v[198:201], v[82:85]
	v_mfma_f32_16x16x32_bf16 v[110:113], v[134:137], v[206:209], v[110:113]
	v_mfma_f32_16x16x32_bf16 v[106:109], v[142:145], v[206:209], v[106:109]
	s_barrier
	v_mfma_f32_16x16x32_bf16 v[118:121], v[134:137], v[228:231], v[118:121]
	v_mfma_f32_16x16x32_bf16 v[114:117], v[142:145], v[228:231], v[114:117]
	v_mfma_f32_16x16x32_bf16 v[126:129], v[134:137], v[236:239], v[126:129]
	v_mfma_f32_16x16x32_bf16 v[122:125], v[142:145], v[236:239], v[122:125]
	v_mfma_f32_16x16x32_bf16 v[86:89], v[138:141], v[202:205], v[86:89]
	v_mfma_f32_16x16x32_bf16 v[82:85], v[178:181], v[202:205], v[82:85]
	v_mfma_f32_16x16x32_bf16 v[110:113], v[138:141], v[224:227], v[110:113]
	v_mfma_f32_16x16x32_bf16 v[106:109], v[178:181], v[224:227], v[106:109]
	v_mfma_f32_16x16x32_bf16 v[118:121], v[138:141], v[232:235], v[118:121]
	v_mfma_f32_16x16x32_bf16 v[114:117], v[178:181], v[232:235], v[114:117]
	v_mfma_f32_16x16x32_bf16 v[126:129], v[138:141], v[240:243], v[126:129]
	v_mfma_f32_16x16x32_bf16 v[122:125], v[178:181], v[240:243], v[122:125]
	v_mfma_f32_16x16x32_bf16 v[26:29], v[182:185], v[198:201], v[26:29]
	v_mfma_f32_16x16x32_bf16 v[30:33], v[190:193], v[198:201], v[30:33]
	v_mfma_f32_16x16x32_bf16 v[42:45], v[182:185], v[206:209], v[42:45]
	v_mfma_f32_16x16x32_bf16 v[50:53], v[190:193], v[206:209], v[50:53]
	v_mfma_f32_16x16x32_bf16 v[66:69], v[182:185], v[228:231], v[66:69]
	v_mfma_f32_16x16x32_bf16 v[70:73], v[190:193], v[228:231], v[70:73]
	v_mfma_f32_16x16x32_bf16 v[90:93], v[182:185], v[236:239], v[90:93]
	v_mfma_f32_16x16x32_bf16 v[94:97], v[190:193], v[236:239], v[94:97]
	v_mfma_f32_16x16x32_bf16 v[26:29], v[186:189], v[202:205], v[26:29]
	v_mfma_f32_16x16x32_bf16 v[30:33], v[194:197], v[202:205], v[30:33]
	v_mfma_f32_16x16x32_bf16 v[42:45], v[186:189], v[224:227], v[42:45]
	v_mfma_f32_16x16x32_bf16 v[50:53], v[194:197], v[224:227], v[50:53]
	v_mfma_f32_16x16x32_bf16 v[66:69], v[186:189], v[232:235], v[66:69]
	v_mfma_f32_16x16x32_bf16 v[70:73], v[194:197], v[232:235], v[70:73]
	v_mfma_f32_16x16x32_bf16 v[90:93], v[186:189], v[240:243], v[90:93]
	v_mfma_f32_16x16x32_bf16 v[94:97], v[194:197], v[240:243], v[94:97]
	s_barrier
	s_mov_b32 m0, s69
	v_lshl_add_u64 v[244:245], v[244:245], 0, s[22:23]
	s_add_u32 s16, s38, 0x160080
	ds_read_b128 v[198:201], v215 offset:49152
	ds_read_b128 v[202:205], v215 offset:50176
	ds_read_b128 v[206:209], v215 offset:51200
	ds_read_b128 v[224:227], v215 offset:52224
	ds_read_b128 v[228:231], v215 offset:53248
	ds_read_b128 v[232:235], v215 offset:54272
	ds_read_b128 v[236:239], v215 offset:55296
	ds_read_b128 v[240:243], v215 offset:56320
	global_load_lds_dwordx4 v[244:245], off
	v_lshl_add_u64 v[244:245], v[246:247], 0, s[22:23]
	s_mov_b32 m0, s73
	s_addc_u32 s17, s39, 0
	global_load_lds_dwordx4 v[244:245], off
	v_lshl_add_u64 v[244:245], s[16:17], 0, v[150:151]
	s_mov_b32 m0, s74
	s_nop 0
	global_load_lds_dwordx4 v[244:245], off
	v_lshl_add_u64 v[244:245], s[16:17], 0, v[146:147]
	s_mov_b32 m0, s75
	s_nop 0
	global_load_lds_dwordx4 v[244:245], off
	v_lshl_add_u64 v[244:245], v[248:249], 0, s[22:23]
	s_mov_b32 m0, s60
	s_nop 0
	global_load_lds_dwordx4 v[244:245], off
	v_lshl_add_u64 v[244:245], v[250:251], 0, s[22:23]
	s_mov_b32 m0, s61
	s_nop 0
	global_load_lds_dwordx4 v[244:245], off
	s_waitcnt vmcnt(8)
	s_waitcnt lgkmcnt(0)
	v_mfma_f32_16x16x32_bf16 v[102:105], v[134:137], v[198:201], v[102:105]
	v_mfma_f32_16x16x32_bf16 v[98:101], v[142:145], v[198:201], v[98:101]
	v_mfma_f32_16x16x32_bf16 v[62:65], v[134:137], v[206:209], v[62:65]
	v_mfma_f32_16x16x32_bf16 v[58:61], v[142:145], v[206:209], v[58:61]
	s_barrier
	v_mfma_f32_16x16x32_bf16 v[38:41], v[134:137], v[228:231], v[38:41]
	v_mfma_f32_16x16x32_bf16 v[34:37], v[142:145], v[228:231], v[34:37]
	v_mfma_f32_16x16x32_bf16 v[14:17], v[134:137], v[236:239], v[14:17]
	v_mfma_f32_16x16x32_bf16 v[10:13], v[142:145], v[236:239], v[10:13]
	v_mfma_f32_16x16x32_bf16 v[102:105], v[138:141], v[202:205], v[102:105]
	v_mfma_f32_16x16x32_bf16 v[98:101], v[178:181], v[202:205], v[98:101]
	v_mfma_f32_16x16x32_bf16 v[62:65], v[138:141], v[224:227], v[62:65]
	v_mfma_f32_16x16x32_bf16 v[58:61], v[178:181], v[224:227], v[58:61]
	v_mfma_f32_16x16x32_bf16 v[38:41], v[138:141], v[232:235], v[38:41]
	v_mfma_f32_16x16x32_bf16 v[34:37], v[178:181], v[232:235], v[34:37]
	v_mfma_f32_16x16x32_bf16 v[14:17], v[138:141], v[240:243], v[14:17]
	v_mfma_f32_16x16x32_bf16 v[10:13], v[178:181], v[240:243], v[10:13]
	v_mfma_f32_16x16x32_bf16 v[78:81], v[182:185], v[198:201], v[78:81]
	v_mfma_f32_16x16x32_bf16 v[74:77], v[190:193], v[198:201], v[74:77]
	v_mfma_f32_16x16x32_bf16 v[54:57], v[182:185], v[206:209], v[54:57]
	v_mfma_f32_16x16x32_bf16 v[46:49], v[190:193], v[206:209], v[46:49]
	v_mfma_f32_16x16x32_bf16 v[22:25], v[182:185], v[228:231], v[22:25]
	v_mfma_f32_16x16x32_bf16 v[18:21], v[190:193], v[228:231], v[18:21]
	v_mfma_f32_16x16x32_bf16 v[6:9], v[182:185], v[236:239], v[6:9]
	v_mfma_f32_16x16x32_bf16 v[2:5], v[190:193], v[236:239], v[2:5]
	v_mfma_f32_16x16x32_bf16 v[78:81], v[186:189], v[202:205], v[78:81]
	v_mfma_f32_16x16x32_bf16 v[74:77], v[194:197], v[202:205], v[74:77]
	v_mfma_f32_16x16x32_bf16 v[54:57], v[186:189], v[224:227], v[54:57]
	v_mfma_f32_16x16x32_bf16 v[46:49], v[194:197], v[224:227], v[46:49]
	v_mfma_f32_16x16x32_bf16 v[22:25], v[186:189], v[232:235], v[22:25]
	v_mfma_f32_16x16x32_bf16 v[18:21], v[194:197], v[232:235], v[18:21]
	v_mfma_f32_16x16x32_bf16 v[6:9], v[186:189], v[240:243], v[6:9]
	v_mfma_f32_16x16x32_bf16 v[2:5], v[194:197], v[240:243], v[2:5]
	s_barrier
	s_add_i32 s15, s15, 2
	s_cmpk_gt_u32 s15, 0x55
	s_mov_b64 s[34:35], s[36:37]
	s_cbranch_scc0 .LBB0_356
	s_and_b64 vcc, exec, s[24:25]
	s_cbranch_vccz .LBB0_359
	s_barrier

.LBB0_466:
	ds_read_b128 v[130:133], v170
	ds_read_b128 v[134:137], v170 offset:1024
	ds_read_b128 v[164:167], v170 offset:2048
	ds_read_b128 v[174:177], v170 offset:3072
	ds_read_b128 v[178:181], v171
	ds_read_b128 v[182:185], v171 offset:1024
	ds_read_b128 v[186:189], v171 offset:2048
	ds_read_b128 v[190:193], v171 offset:3072
	s_add_u32 s19, s42, 0xfff80080
	s_addc_u32 s20, s43, -1
	s_cmp_eq_u32 s18, 28
	s_cselect_b32 s47, s3, s20
	s_cselect_b32 s46, s7, s19
	s_cselect_b32 s45, s14, s17
	s_cselect_b32 s44, s15, s16
	v_lshl_add_u64 v[168:169], s[42:43], 0, v[154:155]
	s_add_i32 m0, s41, 0xc000
	ds_read_b128 v[194:197], v172
	ds_read_b128 v[198:201], v172 offset:1024
	ds_read_b128 v[202:205], v172 offset:2048
	ds_read_b128 v[206:209], v172 offset:3072
	ds_read_b128 v[210:213], v172 offset:4096
	ds_read_b128 v[214:217], v172 offset:5120
	ds_read_b128 v[218:221], v172 offset:6144
	ds_read_b128 v[222:225], v172 offset:7168
	global_load_lds_dwordx4 v[168:169], off
	v_lshl_add_u64 v[168:169], s[42:43], 0, v[156:157]
	s_add_i32 m0, s41, 0xe000
	s_nop 0
	global_load_lds_dwordx4 v[168:169], off
	s_waitcnt vmcnt(8)
	s_waitcnt lgkmcnt(0)
	v_mfma_f32_16x16x32_bf16 v[126:129], v[130:133], v[194:197], v[126:129]
	v_mfma_f32_16x16x32_bf16 v[122:125], v[164:167], v[194:197], v[122:125]
	v_mfma_f32_16x16x32_bf16 v[110:113], v[130:133], v[202:205], v[110:113]
	v_mfma_f32_16x16x32_bf16 v[106:109], v[164:167], v[202:205], v[106:109]
	s_barrier
	v_mfma_f32_16x16x32_bf16 v[94:97], v[130:133], v[210:213], v[94:97]
	v_mfma_f32_16x16x32_bf16 v[90:93], v[164:167], v[210:213], v[90:93]
	v_mfma_f32_16x16x32_bf16 v[78:81], v[130:133], v[218:221], v[78:81]
	v_mfma_f32_16x16x32_bf16 v[74:77], v[164:167], v[218:221], v[74:77]
	v_mfma_f32_16x16x32_bf16 v[126:129], v[134:137], v[198:201], v[126:129]
	v_mfma_f32_16x16x32_bf16 v[122:125], v[174:177], v[198:201], v[122:125]
	v_mfma_f32_16x16x32_bf16 v[110:113], v[134:137], v[206:209], v[110:113]
	v_mfma_f32_16x16x32_bf16 v[106:109], v[174:177], v[206:209], v[106:109]
	v_mfma_f32_16x16x32_bf16 v[94:97], v[134:137], v[214:217], v[94:97]
	v_mfma_f32_16x16x32_bf16 v[90:93], v[174:177], v[214:217], v[90:93]
	v_mfma_f32_16x16x32_bf16 v[78:81], v[134:137], v[222:225], v[78:81]
	v_mfma_f32_16x16x32_bf16 v[74:77], v[174:177], v[222:225], v[74:77]
	v_mfma_f32_16x16x32_bf16 v[118:121], v[178:181], v[194:197], v[118:121]
	v_mfma_f32_16x16x32_bf16 v[114:117], v[186:189], v[194:197], v[114:117]
	v_mfma_f32_16x16x32_bf16 v[102:105], v[178:181], v[202:205], v[102:105]
	v_mfma_f32_16x16x32_bf16 v[98:101], v[186:189], v[202:205], v[98:101]
	v_mfma_f32_16x16x32_bf16 v[86:89], v[178:181], v[210:213], v[86:89]
	v_mfma_f32_16x16x32_bf16 v[82:85], v[186:189], v[210:213], v[82:85]
	v_mfma_f32_16x16x32_bf16 v[70:73], v[178:181], v[218:221], v[70:73]
	v_mfma_f32_16x16x32_bf16 v[66:69], v[186:189], v[218:221], v[66:69]
	v_mfma_f32_16x16x32_bf16 v[118:121], v[182:185], v[198:201], v[118:121]
	v_mfma_f32_16x16x32_bf16 v[114:117], v[190:193], v[198:201], v[114:117]
	v_mfma_f32_16x16x32_bf16 v[102:105], v[182:185], v[206:209], v[102:105]
	v_mfma_f32_16x16x32_bf16 v[98:101], v[190:193], v[206:209], v[98:101]
	v_mfma_f32_16x16x32_bf16 v[86:89], v[182:185], v[214:217], v[86:89]
	v_mfma_f32_16x16x32_bf16 v[82:85], v[190:193], v[214:217], v[82:85]
	v_mfma_f32_16x16x32_bf16 v[70:73], v[182:185], v[222:225], v[70:73]
	v_mfma_f32_16x16x32_bf16 v[66:69], v[190:193], v[222:225], v[66:69]
	s_barrier
	s_add_i32 s19, s75, s52
	v_lshl_add_u64 v[168:169], s[44:45], 0, v[140:141]
	s_mov_b32 m0, s19
	ds_read_b128 v[194:197], v172 offset:16384
	ds_read_b128 v[198:201], v172 offset:17408
	ds_read_b128 v[202:205], v172 offset:18432
	ds_read_b128 v[206:209], v172 offset:19456
	ds_read_b128 v[210:213], v172 offset:20480
	ds_read_b128 v[214:217], v172 offset:21504
	ds_read_b128 v[218:221], v172 offset:22528
	ds_read_b128 v[222:225], v172 offset:23552
	global_load_lds_dwordx4 v[168:169], off
	s_add_i32 m0, s19, 0x2000
	s_add_u32 s20, s44, 0x80000
	v_lshl_add_u64 v[226:227], s[44:45], 0, v[144:145]
	s_addc_u32 s21, s45, 0
	s_add_i32 s19, s76, s52
	global_load_lds_dwordx4 v[226:227], off
	v_lshl_add_u64 v[228:229], s[20:21], 0, v[140:141]
	s_mov_b32 m0, s19
	v_lshl_add_u64 v[230:231], s[46:47], 0, v[142:143]
	global_load_lds_dwordx4 v[228:229], off
	v_lshl_add_u64 v[228:229], s[20:21], 0, v[144:145]
	s_add_i32 m0, s19, 0x2000
	s_nop 0
	global_load_lds_dwordx4 v[228:229], off
	v_lshl_add_u64 v[228:229], s[46:47], 0, v[138:139]
	s_mov_b32 m0, s41
	s_nop 0
	global_load_lds_dwordx4 v[228:229], off
	s_mov_b32 m0, s53
	s_nop 0
	global_load_lds_dwordx4 v[230:231], off
	s_waitcnt vmcnt(8)
	s_waitcnt lgkmcnt(0)
	v_mfma_f32_16x16x32_bf16 v[62:65], v[130:133], v[194:197], v[62:65]
	v_mfma_f32_16x16x32_bf16 v[58:61], v[164:167], v[194:197], v[58:61]
	v_mfma_f32_16x16x32_bf16 v[46:49], v[130:133], v[202:205], v[46:49]
	v_mfma_f32_16x16x32_bf16 v[42:45], v[164:167], v[202:205], v[42:45]
	s_barrier
	v_mfma_f32_16x16x32_bf16 v[30:33], v[130:133], v[210:213], v[30:33]
	v_mfma_f32_16x16x32_bf16 v[26:29], v[164:167], v[210:213], v[26:29]
	v_mfma_f32_16x16x32_bf16 v[14:17], v[130:133], v[218:221], v[14:17]
	v_mfma_f32_16x16x32_bf16 v[10:13], v[164:167], v[218:221], v[10:13]
	v_mfma_f32_16x16x32_bf16 v[62:65], v[134:137], v[198:201], v[62:65]
	v_mfma_f32_16x16x32_bf16 v[58:61], v[174:177], v[198:201], v[58:61]
	v_mfma_f32_16x16x32_bf16 v[46:49], v[134:137], v[206:209], v[46:49]
	v_mfma_f32_16x16x32_bf16 v[42:45], v[174:177], v[206:209], v[42:45]
	v_mfma_f32_16x16x32_bf16 v[30:33], v[134:137], v[214:217], v[30:33]
	v_mfma_f32_16x16x32_bf16 v[26:29], v[174:177], v[214:217], v[26:29]
	v_mfma_f32_16x16x32_bf16 v[14:17], v[134:137], v[222:225], v[14:17]
	v_mfma_f32_16x16x32_bf16 v[10:13], v[174:177], v[222:225], v[10:13]
	v_mfma_f32_16x16x32_bf16 v[54:57], v[178:181], v[194:197], v[54:57]
	v_mfma_f32_16x16x32_bf16 v[50:53], v[186:189], v[194:197], v[50:53]
	v_mfma_f32_16x16x32_bf16 v[38:41], v[178:181], v[202:205], v[38:41]
	v_mfma_f32_16x16x32_bf16 v[34:37], v[186:189], v[202:205], v[34:37]
	v_mfma_f32_16x16x32_bf16 v[22:25], v[178:181], v[210:213], v[22:25]
	v_mfma_f32_16x16x32_bf16 v[18:21], v[186:189], v[210:213], v[18:21]
	v_mfma_f32_16x16x32_bf16 v[6:9], v[178:181], v[218:221], v[6:9]
	v_mfma_f32_16x16x32_bf16 v[2:5], v[186:189], v[218:221], v[2:5]
	v_mfma_f32_16x16x32_bf16 v[54:57], v[182:185], v[198:201], v[54:57]
	v_mfma_f32_16x16x32_bf16 v[50:53], v[190:193], v[198:201], v[50:53]
	v_mfma_f32_16x16x32_bf16 v[38:41], v[182:185], v[206:209], v[38:41]
	v_mfma_f32_16x16x32_bf16 v[34:37], v[190:193], v[206:209], v[34:37]
	v_mfma_f32_16x16x32_bf16 v[22:25], v[182:185], v[214:217], v[22:25]
	v_mfma_f32_16x16x32_bf16 v[18:21], v[190:193], v[214:217], v[18:21]
	v_mfma_f32_16x16x32_bf16 v[6:9], v[182:185], v[222:225], v[6:9]
	v_mfma_f32_16x16x32_bf16 v[2:5], v[190:193], v[222:225], v[2:5]
	s_barrier
	s_add_i32 s19, 0, 0x18000
	v_add_u32_e32 v146, s19, v163
	s_add_i32 s31, 0, 0x1c000
	ds_read_b128 v[130:133], v146
	ds_read_b128 v[134:137], v146 offset:1024
	ds_read_b128 v[164:167], v146 offset:2048
	ds_read_b128 v[174:177], v146 offset:3072
	v_add_u32_e32 v146, s31, v163
	ds_read_b128 v[178:181], v146
	ds_read_b128 v[182:185], v146 offset:1024
	ds_read_b128 v[186:189], v146 offset:2048
	ds_read_b128 v[190:193], v146 offset:3072
	s_add_u32 s20, s46, 0x80000
	s_addc_u32 s21, s47, 0
	s_mov_b32 m0, s54
	v_lshl_add_u64 v[232:233], s[20:21], 0, v[138:139]
	ds_read_b128 v[194:197], v172 offset:32768
	ds_read_b128 v[198:201], v172 offset:33792
	ds_read_b128 v[202:205], v172 offset:34816
	ds_read_b128 v[206:209], v172 offset:35840
	ds_read_b128 v[210:213], v172 offset:36864
	ds_read_b128 v[214:217], v172 offset:37888
	ds_read_b128 v[218:221], v172 offset:38912
	ds_read_b128 v[222:225], v172 offset:39936
	global_load_lds_dwordx4 v[232:233], off
	v_lshl_add_u64 v[232:233], s[20:21], 0, v[142:143]
	s_mov_b32 m0, s55
	s_nop 0
	global_load_lds_dwordx4 v[232:233], off
	s_waitcnt vmcnt(8)
	s_waitcnt lgkmcnt(0)
	v_mfma_f32_16x16x32_bf16 v[126:129], v[130:133], v[194:197], v[126:129]
	v_mfma_f32_16x16x32_bf16 v[122:125], v[164:167], v[194:197], v[122:125]
	v_mfma_f32_16x16x32_bf16 v[110:113], v[130:133], v[202:205], v[110:113]
	v_mfma_f32_16x16x32_bf16 v[106:109], v[164:167], v[202:205], v[106:109]
	s_barrier
	v_mfma_f32_16x16x32_bf16 v[94:97], v[130:133], v[210:213], v[94:97]
	v_mfma_f32_16x16x32_bf16 v[90:93], v[164:167], v[210:213], v[90:93]
	v_mfma_f32_16x16x32_bf16 v[78:81], v[130:133], v[218:221], v[78:81]
	v_mfma_f32_16x16x32_bf16 v[74:77], v[164:167], v[218:221], v[74:77]
	v_mfma_f32_16x16x32_bf16 v[126:129], v[134:137], v[198:201], v[126:129]
	v_mfma_f32_16x16x32_bf16 v[122:125], v[174:177], v[198:201], v[122:125]
	v_mfma_f32_16x16x32_bf16 v[110:113], v[134:137], v[206:209], v[110:113]
	v_mfma_f32_16x16x32_bf16 v[106:109], v[174:177], v[206:209], v[106:109]
	v_mfma_f32_16x16x32_bf16 v[94:97], v[134:137], v[214:217], v[94:97]
	v_mfma_f32_16x16x32_bf16 v[90:93], v[174:177], v[214:217], v[90:93]
	v_mfma_f32_16x16x32_bf16 v[78:81], v[134:137], v[222:225], v[78:81]
	v_mfma_f32_16x16x32_bf16 v[74:77], v[174:177], v[222:225], v[74:77]
	v_mfma_f32_16x16x32_bf16 v[118:121], v[178:181], v[194:197], v[118:121]
	v_mfma_f32_16x16x32_bf16 v[114:117], v[186:189], v[194:197], v[114:117]
	v_mfma_f32_16x16x32_bf16 v[102:105], v[178:181], v[202:205], v[102:105]
	v_mfma_f32_16x16x32_bf16 v[98:101], v[186:189], v[202:205], v[98:101]
	v_mfma_f32_16x16x32_bf16 v[86:89], v[178:181], v[210:213], v[86:89]
	v_mfma_f32_16x16x32_bf16 v[82:85], v[186:189], v[210:213], v[82:85]
	v_mfma_f32_16x16x32_bf16 v[70:73], v[178:181], v[218:221], v[70:73]
	v_mfma_f32_16x16x32_bf16 v[66:69], v[186:189], v[218:221], v[66:69]
	v_mfma_f32_16x16x32_bf16 v[118:121], v[182:185], v[198:201], v[118:121]
	v_mfma_f32_16x16x32_bf16 v[114:117], v[190:193], v[198:201], v[114:117]
	v_mfma_f32_16x16x32_bf16 v[102:105], v[182:185], v[206:209], v[102:105]
	v_mfma_f32_16x16x32_bf16 v[98:101], v[190:193], v[206:209], v[98:101]
	v_mfma_f32_16x16x32_bf16 v[86:89], v[182:185], v[214:217], v[86:89]
	v_mfma_f32_16x16x32_bf16 v[82:85], v[190:193], v[214:217], v[82:85]
	v_mfma_f32_16x16x32_bf16 v[70:73], v[182:185], v[222:225], v[70:73]
	v_mfma_f32_16x16x32_bf16 v[66:69], v[190:193], v[222:225], v[66:69]
	s_barrier
	s_add_i32 s19, s19, s52
	v_lshl_add_u64 v[168:169], v[168:169], 0, s[10:11]
	s_mov_b32 m0, s19
	ds_read_b128 v[194:197], v172 offset:49152
	ds_read_b128 v[198:201], v172 offset:50176
	ds_read_b128 v[202:205], v172 offset:51200
	ds_read_b128 v[206:209], v172 offset:52224
	ds_read_b128 v[210:213], v172 offset:53248
	ds_read_b128 v[214:217], v172 offset:54272
	ds_read_b128 v[218:221], v172 offset:55296
	ds_read_b128 v[222:225], v172 offset:56320
	global_load_lds_dwordx4 v[168:169], off
	s_add_i32 m0, s19, 0x2000
	s_add_u32 s20, s44, 0x80080
	v_lshl_add_u64 v[168:169], v[226:227], 0, s[10:11]
	s_addc_u32 s21, s45, 0
	s_add_i32 s19, s31, s52
	global_load_lds_dwordx4 v[168:169], off
	v_lshl_add_u64 v[168:169], s[20:21], 0, v[140:141]
	s_mov_b32 m0, s19
	s_nop 0
	global_load_lds_dwordx4 v[168:169], off
	v_lshl_add_u64 v[168:169], s[20:21], 0, v[144:145]
	s_add_i32 m0, s19, 0x2000
	s_nop 0
	global_load_lds_dwordx4 v[168:169], off
	v_lshl_add_u64 v[168:169], v[228:229], 0, s[10:11]
	s_mov_b32 m0, s67
	s_nop 0
	global_load_lds_dwordx4 v[168:169], off
	v_lshl_add_u64 v[168:169], v[230:231], 0, s[10:11]
	s_mov_b32 m0, s68
	s_nop 0
	global_load_lds_dwordx4 v[168:169], off
	s_waitcnt vmcnt(8)
	s_waitcnt lgkmcnt(0)
	v_mfma_f32_16x16x32_bf16 v[62:65], v[130:133], v[194:197], v[62:65]
	v_mfma_f32_16x16x32_bf16 v[58:61], v[164:167], v[194:197], v[58:61]
	v_mfma_f32_16x16x32_bf16 v[46:49], v[130:133], v[202:205], v[46:49]
	v_mfma_f32_16x16x32_bf16 v[42:45], v[164:167], v[202:205], v[42:45]
	s_barrier
	v_mfma_f32_16x16x32_bf16 v[30:33], v[130:133], v[210:213], v[30:33]
	v_mfma_f32_16x16x32_bf16 v[26:29], v[164:167], v[210:213], v[26:29]
	v_mfma_f32_16x16x32_bf16 v[14:17], v[130:133], v[218:221], v[14:17]
	v_mfma_f32_16x16x32_bf16 v[10:13], v[164:167], v[218:221], v[10:13]
	v_mfma_f32_16x16x32_bf16 v[62:65], v[134:137], v[198:201], v[62:65]
	v_mfma_f32_16x16x32_bf16 v[58:61], v[174:177], v[198:201], v[58:61]
	v_mfma_f32_16x16x32_bf16 v[46:49], v[134:137], v[206:209], v[46:49]
	v_mfma_f32_16x16x32_bf16 v[42:45], v[174:177], v[206:209], v[42:45]
	v_mfma_f32_16x16x32_bf16 v[30:33], v[134:137], v[214:217], v[30:33]
	v_mfma_f32_16x16x32_bf16 v[26:29], v[174:177], v[214:217], v[26:29]
	v_mfma_f32_16x16x32_bf16 v[14:17], v[134:137], v[222:225], v[14:17]
	v_mfma_f32_16x16x32_bf16 v[10:13], v[174:177], v[222:225], v[10:13]
	v_mfma_f32_16x16x32_bf16 v[54:57], v[178:181], v[194:197], v[54:57]
	v_mfma_f32_16x16x32_bf16 v[50:53], v[186:189], v[194:197], v[50:53]
	v_mfma_f32_16x16x32_bf16 v[38:41], v[178:181], v[202:205], v[38:41]
	v_mfma_f32_16x16x32_bf16 v[34:37], v[186:189], v[202:205], v[34:37]
	v_mfma_f32_16x16x32_bf16 v[22:25], v[178:181], v[210:213], v[22:25]
	v_mfma_f32_16x16x32_bf16 v[18:21], v[186:189], v[210:213], v[18:21]
	v_mfma_f32_16x16x32_bf16 v[6:9], v[178:181], v[218:221], v[6:9]
	v_mfma_f32_16x16x32_bf16 v[2:5], v[186:189], v[218:221], v[2:5]
	v_mfma_f32_16x16x32_bf16 v[54:57], v[182:185], v[198:201], v[54:57]
	v_mfma_f32_16x16x32_bf16 v[50:53], v[190:193], v[198:201], v[50:53]
	v_mfma_f32_16x16x32_bf16 v[38:41], v[182:185], v[206:209], v[38:41]
	v_mfma_f32_16x16x32_bf16 v[34:37], v[190:193], v[206:209], v[34:37]
	v_mfma_f32_16x16x32_bf16 v[22:25], v[182:185], v[214:217], v[22:25]
	v_mfma_f32_16x16x32_bf16 v[18:21], v[190:193], v[214:217], v[18:21]
	v_mfma_f32_16x16x32_bf16 v[6:9], v[182:185], v[222:225], v[6:9]
	v_mfma_f32_16x16x32_bf16 v[2:5], v[190:193], v[222:225], v[2:5]
	s_barrier
	s_add_i32 s18, s18, 2
	s_add_u32 s42, s42, 0x100
	s_addc_u32 s43, s43, 0
	s_add_u32 s16, s16, 0x100
	s_addc_u32 s17, s17, 0
	s_cmp_gt_u32 s18, 29
	s_cbranch_scc0 .LBB0_466
	s_and_b64 vcc, exec, s[12:13]
	s_cbranch_vccz .LBB0_469
	s_barrier

.LBB0_699:
	ds_read_b128 v[134:137], v214
	ds_read_b128 v[138:141], v214 offset:1024
	ds_read_b128 v[142:145], v214 offset:2048
	ds_read_b128 v[178:181], v214 offset:3072
	ds_read_b128 v[182:185], v215
	ds_read_b128 v[186:189], v215 offset:1024
	ds_read_b128 v[190:193], v215 offset:2048
	ds_read_b128 v[194:197], v215 offset:3072
	s_add_u32 s40, s38, 0x100
	s_addc_u32 s41, s39, 0
	s_add_u32 s18, s15, s38
	s_addc_u32 s19, s16, s39
	s_cmp_eq_u32 s17, 60
	s_cselect_b32 s45, s3, s19
	s_cselect_b32 s19, 0, s40
	s_cselect_b32 s44, s14, s18
	s_cselect_b32 s18, 0, s41
	s_add_u32 s42, s10, s19
	s_addc_u32 s43, s11, s18
	s_mov_b32 m0, s66
	v_lshl_add_u64 v[244:245], v[130:131], 0, s[38:39]
	ds_read_b128 v[198:201], v216
	ds_read_b128 v[202:205], v216 offset:1024
	ds_read_b128 v[206:209], v216 offset:2048
	ds_read_b128 v[224:227], v216 offset:3072
	ds_read_b128 v[228:231], v216 offset:4096
	ds_read_b128 v[232:235], v216 offset:5120
	ds_read_b128 v[236:239], v216 offset:6144
	ds_read_b128 v[240:243], v216 offset:7168
	global_load_lds_dwordx4 v[244:245], off
	v_lshl_add_u64 v[244:245], v[132:133], 0, s[38:39]
	s_mov_b32 m0, s67
	s_nop 0
	global_load_lds_dwordx4 v[244:245], off
	s_waitcnt vmcnt(8)
	s_waitcnt lgkmcnt(0)
	v_mfma_f32_16x16x32_bf16 v[82:85], v[134:137], v[198:201], v[82:85]
	v_mfma_f32_16x16x32_bf16 v[78:81], v[142:145], v[198:201], v[78:81]
	v_mfma_f32_16x16x32_bf16 v[110:113], v[134:137], v[206:209], v[110:113]
	v_mfma_f32_16x16x32_bf16 v[106:109], v[142:145], v[206:209], v[106:109]
	s_barrier
	v_mfma_f32_16x16x32_bf16 v[118:121], v[134:137], v[228:231], v[118:121]
	v_mfma_f32_16x16x32_bf16 v[114:117], v[142:145], v[228:231], v[114:117]
	v_mfma_f32_16x16x32_bf16 v[126:129], v[134:137], v[236:239], v[126:129]
	v_mfma_f32_16x16x32_bf16 v[122:125], v[142:145], v[236:239], v[122:125]
	v_mfma_f32_16x16x32_bf16 v[82:85], v[138:141], v[202:205], v[82:85]
	v_mfma_f32_16x16x32_bf16 v[78:81], v[178:181], v[202:205], v[78:81]
	v_mfma_f32_16x16x32_bf16 v[110:113], v[138:141], v[224:227], v[110:113]
	v_mfma_f32_16x16x32_bf16 v[106:109], v[178:181], v[224:227], v[106:109]
	v_mfma_f32_16x16x32_bf16 v[118:121], v[138:141], v[232:235], v[118:121]
	v_mfma_f32_16x16x32_bf16 v[114:117], v[178:181], v[232:235], v[114:117]
	v_mfma_f32_16x16x32_bf16 v[126:129], v[138:141], v[240:243], v[126:129]
	v_mfma_f32_16x16x32_bf16 v[122:125], v[178:181], v[240:243], v[122:125]
	v_mfma_f32_16x16x32_bf16 v[22:25], v[182:185], v[198:201], v[22:25]
	v_mfma_f32_16x16x32_bf16 v[26:29], v[190:193], v[198:201], v[26:29]
	v_mfma_f32_16x16x32_bf16 v[42:45], v[182:185], v[206:209], v[42:45]
	v_mfma_f32_16x16x32_bf16 v[46:49], v[190:193], v[206:209], v[46:49]
	v_mfma_f32_16x16x32_bf16 v[62:65], v[182:185], v[228:231], v[62:65]
	v_mfma_f32_16x16x32_bf16 v[70:73], v[190:193], v[228:231], v[70:73]
	v_mfma_f32_16x16x32_bf16 v[90:93], v[182:185], v[236:239], v[90:93]
	v_mfma_f32_16x16x32_bf16 v[94:97], v[190:193], v[236:239], v[94:97]
	v_mfma_f32_16x16x32_bf16 v[22:25], v[186:189], v[202:205], v[22:25]
	v_mfma_f32_16x16x32_bf16 v[26:29], v[194:197], v[202:205], v[26:29]
	v_mfma_f32_16x16x32_bf16 v[42:45], v[186:189], v[224:227], v[42:45]
	v_mfma_f32_16x16x32_bf16 v[46:49], v[194:197], v[224:227], v[46:49]
	v_mfma_f32_16x16x32_bf16 v[62:65], v[186:189], v[232:235], v[62:65]
	v_mfma_f32_16x16x32_bf16 v[70:73], v[194:197], v[232:235], v[70:73]
	v_mfma_f32_16x16x32_bf16 v[90:93], v[186:189], v[240:243], v[90:93]
	v_mfma_f32_16x16x32_bf16 v[94:97], v[194:197], v[240:243], v[94:97]
	s_barrier
	s_mov_b32 m0, s68
	v_lshl_add_u64 v[244:245], s[42:43], 0, v[150:151]
	s_add_u32 s18, s42, 0x100000
	ds_read_b128 v[198:201], v216 offset:16384
	ds_read_b128 v[202:205], v216 offset:17408
	ds_read_b128 v[206:209], v216 offset:18432
	ds_read_b128 v[224:227], v216 offset:19456
	ds_read_b128 v[228:231], v216 offset:20480
	ds_read_b128 v[232:235], v216 offset:21504
	ds_read_b128 v[236:239], v216 offset:22528
	ds_read_b128 v[240:243], v216 offset:23552
	global_load_lds_dwordx4 v[244:245], off
	v_lshl_add_u64 v[246:247], s[42:43], 0, v[146:147]
	s_mov_b32 m0, s69
	s_addc_u32 s19, s43, 0
	global_load_lds_dwordx4 v[246:247], off
	v_lshl_add_u64 v[248:249], s[18:19], 0, v[150:151]
	s_mov_b32 m0, s73
	v_lshl_add_u64 v[250:251], s[44:45], 0, v[148:149]
	global_load_lds_dwordx4 v[248:249], off
	v_lshl_add_u64 v[248:249], s[18:19], 0, v[146:147]
	s_mov_b32 m0, s74
	s_nop 0
	global_load_lds_dwordx4 v[248:249], off
	v_lshl_add_u64 v[248:249], s[44:45], 0, v[152:153]
	s_mov_b32 m0, s9
	s_nop 0
	global_load_lds_dwordx4 v[248:249], off
	s_mov_b32 m0, s55
	s_nop 0
	global_load_lds_dwordx4 v[250:251], off
	s_waitcnt vmcnt(8)
	s_waitcnt lgkmcnt(0)
	v_mfma_f32_16x16x32_bf16 v[102:105], v[134:137], v[198:201], v[102:105]
	v_mfma_f32_16x16x32_bf16 v[98:101], v[142:145], v[198:201], v[98:101]
	v_mfma_f32_16x16x32_bf16 v[66:69], v[134:137], v[206:209], v[66:69]
	v_mfma_f32_16x16x32_bf16 v[58:61], v[142:145], v[206:209], v[58:61]
	s_barrier
	v_mfma_f32_16x16x32_bf16 v[38:41], v[134:137], v[228:231], v[38:41]
	v_mfma_f32_16x16x32_bf16 v[34:37], v[142:145], v[228:231], v[34:37]
	v_mfma_f32_16x16x32_bf16 v[14:17], v[134:137], v[236:239], v[14:17]
	v_mfma_f32_16x16x32_bf16 v[10:13], v[142:145], v[236:239], v[10:13]
	v_mfma_f32_16x16x32_bf16 v[102:105], v[138:141], v[202:205], v[102:105]
	v_mfma_f32_16x16x32_bf16 v[98:101], v[178:181], v[202:205], v[98:101]
	v_mfma_f32_16x16x32_bf16 v[66:69], v[138:141], v[224:227], v[66:69]
	v_mfma_f32_16x16x32_bf16 v[58:61], v[178:181], v[224:227], v[58:61]
	v_mfma_f32_16x16x32_bf16 v[38:41], v[138:141], v[232:235], v[38:41]
	v_mfma_f32_16x16x32_bf16 v[34:37], v[178:181], v[232:235], v[34:37]
	v_mfma_f32_16x16x32_bf16 v[14:17], v[138:141], v[240:243], v[14:17]
	v_mfma_f32_16x16x32_bf16 v[10:13], v[178:181], v[240:243], v[10:13]
	v_mfma_f32_16x16x32_bf16 v[86:89], v[182:185], v[198:201], v[86:89]
	v_mfma_f32_16x16x32_bf16 v[74:77], v[190:193], v[198:201], v[74:77]
	v_mfma_f32_16x16x32_bf16 v[54:57], v[182:185], v[206:209], v[54:57]
	v_mfma_f32_16x16x32_bf16 v[50:53], v[190:193], v[206:209], v[50:53]
	v_mfma_f32_16x16x32_bf16 v[30:33], v[182:185], v[228:231], v[30:33]
	v_mfma_f32_16x16x32_bf16 v[18:21], v[190:193], v[228:231], v[18:21]
	v_mfma_f32_16x16x32_bf16 v[6:9], v[182:185], v[236:239], v[6:9]
	v_mfma_f32_16x16x32_bf16 v[2:5], v[190:193], v[236:239], v[2:5]
	v_mfma_f32_16x16x32_bf16 v[86:89], v[186:189], v[202:205], v[86:89]
	v_mfma_f32_16x16x32_bf16 v[74:77], v[194:197], v[202:205], v[74:77]
	v_mfma_f32_16x16x32_bf16 v[54:57], v[186:189], v[224:227], v[54:57]
	v_mfma_f32_16x16x32_bf16 v[50:53], v[194:197], v[224:227], v[50:53]
	v_mfma_f32_16x16x32_bf16 v[30:33], v[186:189], v[232:235], v[30:33]
	v_mfma_f32_16x16x32_bf16 v[18:21], v[194:197], v[232:235], v[18:21]
	v_mfma_f32_16x16x32_bf16 v[6:9], v[186:189], v[240:243], v[6:9]
	v_mfma_f32_16x16x32_bf16 v[2:5], v[194:197], v[240:243], v[2:5]
	s_barrier
	s_add_i32 s20, 0, 0x1c000
	v_add_u32_e32 v194, s20, v212
	ds_read_b128 v[134:137], v220
	ds_read_b128 v[138:141], v220 offset:1024
	ds_read_b128 v[142:145], v220 offset:2048
	ds_read_b128 v[178:181], v220 offset:3072
	ds_read_b128 v[182:185], v194
	ds_read_b128 v[186:189], v194 offset:1024
	ds_read_b128 v[190:193], v194 offset:2048
	ds_read_b128 v[194:197], v194 offset:3072
	s_add_u32 s18, s44, 0x100000
	s_addc_u32 s19, s45, 0
	s_mov_b32 m0, s56
	v_lshl_add_u64 v[252:253], s[18:19], 0, v[152:153]
	ds_read_b128 v[198:201], v216 offset:32768
	ds_read_b128 v[202:205], v216 offset:33792
	ds_read_b128 v[206:209], v216 offset:34816
	ds_read_b128 v[224:227], v216 offset:35840
	ds_read_b128 v[228:231], v216 offset:36864
	ds_read_b128 v[232:235], v216 offset:37888
	ds_read_b128 v[236:239], v216 offset:38912
	ds_read_b128 v[240:243], v216 offset:39936
	global_load_lds_dwordx4 v[252:253], off
	v_lshl_add_u64 v[252:253], s[18:19], 0, v[148:149]
	s_mov_b32 m0, s57
	s_nop 0
	global_load_lds_dwordx4 v[252:253], off
	s_waitcnt vmcnt(8)
	s_waitcnt lgkmcnt(0)
	v_mfma_f32_16x16x32_bf16 v[82:85], v[134:137], v[198:201], v[82:85]
	v_mfma_f32_16x16x32_bf16 v[78:81], v[142:145], v[198:201], v[78:81]
	v_mfma_f32_16x16x32_bf16 v[110:113], v[134:137], v[206:209], v[110:113]
	v_mfma_f32_16x16x32_bf16 v[106:109], v[142:145], v[206:209], v[106:109]
	s_barrier
	v_mfma_f32_16x16x32_bf16 v[118:121], v[134:137], v[228:231], v[118:121]
	v_mfma_f32_16x16x32_bf16 v[114:117], v[142:145], v[228:231], v[114:117]
	v_mfma_f32_16x16x32_bf16 v[126:129], v[134:137], v[236:239], v[126:129]
	v_mfma_f32_16x16x32_bf16 v[122:125], v[142:145], v[236:239], v[122:125]
	v_mfma_f32_16x16x32_bf16 v[82:85], v[138:141], v[202:205], v[82:85]
	v_mfma_f32_16x16x32_bf16 v[78:81], v[178:181], v[202:205], v[78:81]
	v_mfma_f32_16x16x32_bf16 v[110:113], v[138:141], v[224:227], v[110:113]
	v_mfma_f32_16x16x32_bf16 v[106:109], v[178:181], v[224:227], v[106:109]
	v_mfma_f32_16x16x32_bf16 v[118:121], v[138:141], v[232:235], v[118:121]
	v_mfma_f32_16x16x32_bf16 v[114:117], v[178:181], v[232:235], v[114:117]
	v_mfma_f32_16x16x32_bf16 v[126:129], v[138:141], v[240:243], v[126:129]
	v_mfma_f32_16x16x32_bf16 v[122:125], v[178:181], v[240:243], v[122:125]
	v_mfma_f32_16x16x32_bf16 v[22:25], v[182:185], v[198:201], v[22:25]
	v_mfma_f32_16x16x32_bf16 v[26:29], v[190:193], v[198:201], v[26:29]
	v_mfma_f32_16x16x32_bf16 v[42:45], v[182:185], v[206:209], v[42:45]
	v_mfma_f32_16x16x32_bf16 v[46:49], v[190:193], v[206:209], v[46:49]
	v_mfma_f32_16x16x32_bf16 v[62:65], v[182:185], v[228:231], v[62:65]
	v_mfma_f32_16x16x32_bf16 v[70:73], v[190:193], v[228:231], v[70:73]
	v_mfma_f32_16x16x32_bf16 v[90:93], v[182:185], v[236:239], v[90:93]
	v_mfma_f32_16x16x32_bf16 v[94:97], v[190:193], v[236:239], v[94:97]
	v_mfma_f32_16x16x32_bf16 v[22:25], v[186:189], v[202:205], v[22:25]
	v_mfma_f32_16x16x32_bf16 v[26:29], v[194:197], v[202:205], v[26:29]
	v_mfma_f32_16x16x32_bf16 v[42:45], v[186:189], v[224:227], v[42:45]
	v_mfma_f32_16x16x32_bf16 v[46:49], v[194:197], v[224:227], v[46:49]
	v_mfma_f32_16x16x32_bf16 v[62:65], v[186:189], v[232:235], v[62:65]
	v_mfma_f32_16x16x32_bf16 v[70:73], v[194:197], v[232:235], v[70:73]
	v_mfma_f32_16x16x32_bf16 v[90:93], v[186:189], v[240:243], v[90:93]
	v_mfma_f32_16x16x32_bf16 v[94:97], v[194:197], v[240:243], v[94:97]
	s_barrier
	s_add_i32 s18, s75, s54
	v_lshl_add_u64 v[244:245], v[244:245], 0, s[26:27]
	s_mov_b32 m0, s18
	ds_read_b128 v[198:201], v216 offset:49152
	ds_read_b128 v[202:205], v216 offset:50176
	ds_read_b128 v[206:209], v216 offset:51200
	ds_read_b128 v[224:227], v216 offset:52224
	ds_read_b128 v[228:231], v216 offset:53248
	ds_read_b128 v[232:235], v216 offset:54272
	ds_read_b128 v[236:239], v216 offset:55296
	ds_read_b128 v[240:243], v216 offset:56320
	global_load_lds_dwordx4 v[244:245], off
	s_add_i32 m0, s18, 0x2000
	s_add_u32 s18, s42, 0x100080
	v_lshl_add_u64 v[244:245], v[246:247], 0, s[26:27]
	s_addc_u32 s19, s43, 0
	s_add_i32 s20, s20, s54
	global_load_lds_dwordx4 v[244:245], off
	v_lshl_add_u64 v[244:245], s[18:19], 0, v[150:151]
	s_mov_b32 m0, s20
	s_nop 0
	global_load_lds_dwordx4 v[244:245], off
	v_lshl_add_u64 v[244:245], s[18:19], 0, v[146:147]
	s_add_i32 m0, s20, 0x2000
	s_nop 0
	global_load_lds_dwordx4 v[244:245], off
	v_lshl_add_u64 v[244:245], v[248:249], 0, s[26:27]
	s_mov_b32 m0, s63
	s_nop 0
	global_load_lds_dwordx4 v[244:245], off
	v_lshl_add_u64 v[244:245], v[250:251], 0, s[26:27]
	s_mov_b32 m0, s64
	s_nop 0
	global_load_lds_dwordx4 v[244:245], off
	s_waitcnt vmcnt(8)
	s_waitcnt lgkmcnt(0)
	v_mfma_f32_16x16x32_bf16 v[102:105], v[134:137], v[198:201], v[102:105]
	v_mfma_f32_16x16x32_bf16 v[98:101], v[142:145], v[198:201], v[98:101]
	v_mfma_f32_16x16x32_bf16 v[66:69], v[134:137], v[206:209], v[66:69]
	v_mfma_f32_16x16x32_bf16 v[58:61], v[142:145], v[206:209], v[58:61]
	s_barrier
	v_mfma_f32_16x16x32_bf16 v[38:41], v[134:137], v[228:231], v[38:41]
	v_mfma_f32_16x16x32_bf16 v[34:37], v[142:145], v[228:231], v[34:37]
	v_mfma_f32_16x16x32_bf16 v[14:17], v[134:137], v[236:239], v[14:17]
	v_mfma_f32_16x16x32_bf16 v[10:13], v[142:145], v[236:239], v[10:13]
	v_mfma_f32_16x16x32_bf16 v[102:105], v[138:141], v[202:205], v[102:105]
	v_mfma_f32_16x16x32_bf16 v[98:101], v[178:181], v[202:205], v[98:101]
	v_mfma_f32_16x16x32_bf16 v[66:69], v[138:141], v[224:227], v[66:69]
	v_mfma_f32_16x16x32_bf16 v[58:61], v[178:181], v[224:227], v[58:61]
	v_mfma_f32_16x16x32_bf16 v[38:41], v[138:141], v[232:235], v[38:41]
	v_mfma_f32_16x16x32_bf16 v[34:37], v[178:181], v[232:235], v[34:37]
	v_mfma_f32_16x16x32_bf16 v[14:17], v[138:141], v[240:243], v[14:17]
	v_mfma_f32_16x16x32_bf16 v[10:13], v[178:181], v[240:243], v[10:13]
	v_mfma_f32_16x16x32_bf16 v[86:89], v[182:185], v[198:201], v[86:89]
	v_mfma_f32_16x16x32_bf16 v[74:77], v[190:193], v[198:201], v[74:77]
	v_mfma_f32_16x16x32_bf16 v[54:57], v[182:185], v[206:209], v[54:57]
	v_mfma_f32_16x16x32_bf16 v[50:53], v[190:193], v[206:209], v[50:53]
	v_mfma_f32_16x16x32_bf16 v[30:33], v[182:185], v[228:231], v[30:33]
	v_mfma_f32_16x16x32_bf16 v[18:21], v[190:193], v[228:231], v[18:21]
	v_mfma_f32_16x16x32_bf16 v[6:9], v[182:185], v[236:239], v[6:9]
	v_mfma_f32_16x16x32_bf16 v[2:5], v[190:193], v[236:239], v[2:5]
	v_mfma_f32_16x16x32_bf16 v[86:89], v[186:189], v[202:205], v[86:89]
	v_mfma_f32_16x16x32_bf16 v[74:77], v[194:197], v[202:205], v[74:77]
	v_mfma_f32_16x16x32_bf16 v[54:57], v[186:189], v[224:227], v[54:57]
	v_mfma_f32_16x16x32_bf16 v[50:53], v[194:197], v[224:227], v[50:53]
	v_mfma_f32_16x16x32_bf16 v[30:33], v[186:189], v[232:235], v[30:33]
	v_mfma_f32_16x16x32_bf16 v[18:21], v[194:197], v[232:235], v[18:21]
	v_mfma_f32_16x16x32_bf16 v[6:9], v[186:189], v[240:243], v[6:9]
	v_mfma_f32_16x16x32_bf16 v[2:5], v[194:197], v[240:243], v[2:5]
	s_barrier
	s_add_i32 s17, s17, 2
	s_cmp_gt_u32 s17, 61
	s_mov_b64 s[38:39], s[40:41]
	s_cbranch_scc0 .LBB0_699
	s_and_b64 vcc, exec, s[28:29]
	s_cbranch_vccz .LBB0_702
	s_barrier

.LBB0_877:
	ds_read_b128 v[130:133], v220
	ds_read_b128 v[134:137], v220 offset:1024
	ds_read_b128 v[138:141], v220 offset:2048
	ds_read_b128 v[142:145], v220 offset:3072
	ds_read_b128 v[184:187], v224
	ds_read_b128 v[188:191], v224 offset:1024
	ds_read_b128 v[192:195], v224 offset:2048
	ds_read_b128 v[196:199], v224 offset:3072
	s_add_u32 s14, s36, 0xffea0080
	s_addc_u32 s15, s37, -1
	s_cmpk_eq_i32 s3, 0x54
	s_cselect_b32 s43, s29, s15
	s_cselect_b32 s42, s28, s14
	s_cselect_b32 s41, s9, s39
	s_cselect_b32 s40, s8, s38
	s_mov_b32 m0, s50
	v_lshl_add_u64 v[244:245], s[36:37], 0, v[178:179]
	ds_read_b128 v[200:203], v221
	ds_read_b128 v[204:207], v221 offset:1024
	ds_read_b128 v[208:211], v221 offset:2048
	ds_read_b128 v[212:215], v221 offset:3072
	ds_read_b128 v[228:231], v221 offset:4096
	ds_read_b128 v[232:235], v221 offset:5120
	ds_read_b128 v[236:239], v221 offset:6144
	ds_read_b128 v[240:243], v221 offset:7168
	global_load_lds_dwordx4 v[244:245], off
	v_lshl_add_u64 v[244:245], s[36:37], 0, v[180:181]
	s_mov_b32 m0, s51
	s_nop 0
	global_load_lds_dwordx4 v[244:245], off
	s_waitcnt vmcnt(8)
	s_waitcnt lgkmcnt(0)
	v_mfma_f32_16x16x32_bf16 v[30:33], v[130:133], v[200:203], v[30:33]
	v_mfma_f32_16x16x32_bf16 v[26:29], v[138:141], v[200:203], v[26:29]
	v_mfma_f32_16x16x32_bf16 v[46:49], v[130:133], v[208:211], v[46:49]
	v_mfma_f32_16x16x32_bf16 v[42:45], v[138:141], v[208:211], v[42:45]
	s_barrier
	v_mfma_f32_16x16x32_bf16 v[62:65], v[130:133], v[228:231], v[62:65]
	v_mfma_f32_16x16x32_bf16 v[58:61], v[138:141], v[228:231], v[58:61]
	v_mfma_f32_16x16x32_bf16 v[94:97], v[130:133], v[236:239], v[94:97]
	v_mfma_f32_16x16x32_bf16 v[90:93], v[138:141], v[236:239], v[90:93]
	v_mfma_f32_16x16x32_bf16 v[30:33], v[134:137], v[204:207], v[30:33]
	v_mfma_f32_16x16x32_bf16 v[26:29], v[142:145], v[204:207], v[26:29]
	v_mfma_f32_16x16x32_bf16 v[46:49], v[134:137], v[212:215], v[46:49]
	v_mfma_f32_16x16x32_bf16 v[42:45], v[142:145], v[212:215], v[42:45]
	v_mfma_f32_16x16x32_bf16 v[62:65], v[134:137], v[232:235], v[62:65]
	v_mfma_f32_16x16x32_bf16 v[58:61], v[142:145], v[232:235], v[58:61]
	v_mfma_f32_16x16x32_bf16 v[94:97], v[134:137], v[240:243], v[94:97]
	v_mfma_f32_16x16x32_bf16 v[90:93], v[142:145], v[240:243], v[90:93]
	v_mfma_f32_16x16x32_bf16 v[2:5], v[184:187], v[200:203], v[2:5]
	v_mfma_f32_16x16x32_bf16 v[6:9], v[192:195], v[200:203], v[6:9]
	v_mfma_f32_16x16x32_bf16 v[10:13], v[184:187], v[208:211], v[10:13]
	v_mfma_f32_16x16x32_bf16 v[14:17], v[192:195], v[208:211], v[14:17]
	v_mfma_f32_16x16x32_bf16 v[18:21], v[184:187], v[228:231], v[18:21]
	v_mfma_f32_16x16x32_bf16 v[22:25], v[192:195], v[228:231], v[22:25]
	v_mfma_f32_16x16x32_bf16 v[34:37], v[184:187], v[236:239], v[34:37]
	v_mfma_f32_16x16x32_bf16 v[38:41], v[192:195], v[236:239], v[38:41]
	v_mfma_f32_16x16x32_bf16 v[2:5], v[188:191], v[204:207], v[2:5]
	v_mfma_f32_16x16x32_bf16 v[6:9], v[196:199], v[204:207], v[6:9]
	v_mfma_f32_16x16x32_bf16 v[10:13], v[188:191], v[212:215], v[10:13]
	v_mfma_f32_16x16x32_bf16 v[14:17], v[196:199], v[212:215], v[14:17]
	v_mfma_f32_16x16x32_bf16 v[18:21], v[188:191], v[232:235], v[18:21]
	v_mfma_f32_16x16x32_bf16 v[22:25], v[196:199], v[232:235], v[22:25]
	v_mfma_f32_16x16x32_bf16 v[34:37], v[188:191], v[240:243], v[34:37]
	v_mfma_f32_16x16x32_bf16 v[38:41], v[196:199], v[240:243], v[38:41]
	s_barrier
	s_mov_b32 m0, s52
	v_lshl_add_u64 v[244:245], s[40:41], 0, v[150:151]
	s_add_u32 s14, s40, 0x160000
	ds_read_b128 v[200:203], v221 offset:16384
	ds_read_b128 v[204:207], v221 offset:17408
	ds_read_b128 v[208:211], v221 offset:18432
	ds_read_b128 v[212:215], v221 offset:19456
	ds_read_b128 v[228:231], v221 offset:20480
	ds_read_b128 v[232:235], v221 offset:21504
	ds_read_b128 v[236:239], v221 offset:22528
	ds_read_b128 v[240:243], v221 offset:23552
	global_load_lds_dwordx4 v[244:245], off
	v_lshl_add_u64 v[246:247], s[40:41], 0, v[146:147]
	s_mov_b32 m0, s53
	s_addc_u32 s15, s41, 0
	global_load_lds_dwordx4 v[246:247], off
	v_lshl_add_u64 v[248:249], s[14:15], 0, v[150:151]
	s_mov_b32 m0, s54
	v_lshl_add_u64 v[250:251], s[42:43], 0, v[148:149]
	global_load_lds_dwordx4 v[248:249], off
	v_lshl_add_u64 v[248:249], s[14:15], 0, v[146:147]
	s_mov_b32 m0, s55
	s_nop 0
	global_load_lds_dwordx4 v[248:249], off
	v_lshl_add_u64 v[248:249], s[42:43], 0, v[152:153]
	s_mov_b32 m0, s61
	s_nop 0
	global_load_lds_dwordx4 v[248:249], off
	s_mov_b32 m0, s62
	s_nop 0
	global_load_lds_dwordx4 v[250:251], off
	s_waitcnt vmcnt(8)
	s_waitcnt lgkmcnt(0)
	v_mfma_f32_16x16x32_bf16 v[114:117], v[130:133], v[200:203], v[114:117]
	v_mfma_f32_16x16x32_bf16 v[110:113], v[138:141], v[200:203], v[110:113]
	v_mfma_f32_16x16x32_bf16 v[126:129], v[130:133], v[208:211], v[126:129]
	v_mfma_f32_16x16x32_bf16 v[122:125], v[138:141], v[208:211], v[122:125]
	s_barrier
	v_mfma_f32_16x16x32_bf16 v[118:121], v[130:133], v[228:231], v[118:121]
	v_mfma_f32_16x16x32_bf16 v[106:109], v[138:141], v[228:231], v[106:109]
	v_mfma_f32_16x16x32_bf16 v[78:81], v[130:133], v[236:239], v[78:81]
	v_mfma_f32_16x16x32_bf16 v[74:77], v[138:141], v[236:239], v[74:77]
	v_mfma_f32_16x16x32_bf16 v[114:117], v[134:137], v[204:207], v[114:117]
	v_mfma_f32_16x16x32_bf16 v[110:113], v[142:145], v[204:207], v[110:113]
	v_mfma_f32_16x16x32_bf16 v[126:129], v[134:137], v[212:215], v[126:129]
	v_mfma_f32_16x16x32_bf16 v[122:125], v[142:145], v[212:215], v[122:125]
	v_mfma_f32_16x16x32_bf16 v[118:121], v[134:137], v[232:235], v[118:121]
	v_mfma_f32_16x16x32_bf16 v[106:109], v[142:145], v[232:235], v[106:109]
	v_mfma_f32_16x16x32_bf16 v[78:81], v[134:137], v[240:243], v[78:81]
	v_mfma_f32_16x16x32_bf16 v[74:77], v[142:145], v[240:243], v[74:77]
	v_mfma_f32_16x16x32_bf16 v[50:53], v[184:187], v[200:203], v[50:53]
	v_mfma_f32_16x16x32_bf16 v[54:57], v[192:195], v[200:203], v[54:57]
	v_mfma_f32_16x16x32_bf16 v[82:85], v[184:187], v[208:211], v[82:85]
	v_mfma_f32_16x16x32_bf16 v[86:89], v[192:195], v[208:211], v[86:89]
	v_mfma_f32_16x16x32_bf16 v[102:105], v[184:187], v[228:231], v[102:105]
	v_mfma_f32_16x16x32_bf16 v[98:101], v[192:195], v[228:231], v[98:101]
	v_mfma_f32_16x16x32_bf16 v[70:73], v[184:187], v[236:239], v[70:73]
	v_mfma_f32_16x16x32_bf16 v[66:69], v[192:195], v[236:239], v[66:69]
	v_mfma_f32_16x16x32_bf16 v[50:53], v[188:191], v[204:207], v[50:53]
	v_mfma_f32_16x16x32_bf16 v[54:57], v[196:199], v[204:207], v[54:57]
	v_mfma_f32_16x16x32_bf16 v[82:85], v[188:191], v[212:215], v[82:85]
	v_mfma_f32_16x16x32_bf16 v[86:89], v[196:199], v[212:215], v[86:89]
	v_mfma_f32_16x16x32_bf16 v[102:105], v[188:191], v[232:235], v[102:105]
	v_mfma_f32_16x16x32_bf16 v[98:101], v[196:199], v[232:235], v[98:101]
	v_mfma_f32_16x16x32_bf16 v[70:73], v[188:191], v[240:243], v[70:73]
	v_mfma_f32_16x16x32_bf16 v[66:69], v[196:199], v[240:243], v[66:69]
	s_barrier
	v_add_u32_e32 v196, s74, v218
	ds_read_b128 v[130:133], v225
	ds_read_b128 v[134:137], v225 offset:1024
	ds_read_b128 v[138:141], v225 offset:2048
	ds_read_b128 v[142:145], v225 offset:3072
	ds_read_b128 v[184:187], v196
	ds_read_b128 v[188:191], v196 offset:1024
	ds_read_b128 v[192:195], v196 offset:2048
	ds_read_b128 v[196:199], v196 offset:3072
	s_add_u32 s14, s42, 0x160000
	s_addc_u32 s15, s43, 0
	s_mov_b32 m0, s63
	v_lshl_add_u64 v[252:253], s[14:15], 0, v[152:153]
	ds_read_b128 v[200:203], v221 offset:32768
	ds_read_b128 v[204:207], v221 offset:33792
	ds_read_b128 v[208:211], v221 offset:34816
	ds_read_b128 v[212:215], v221 offset:35840
	ds_read_b128 v[228:231], v221 offset:36864
	ds_read_b128 v[232:235], v221 offset:37888
	ds_read_b128 v[236:239], v221 offset:38912
	ds_read_b128 v[240:243], v221 offset:39936
	global_load_lds_dwordx4 v[252:253], off
	v_lshl_add_u64 v[252:253], s[14:15], 0, v[148:149]
	s_mov_b32 m0, s64
	s_nop 0
	global_load_lds_dwordx4 v[252:253], off
	s_waitcnt vmcnt(8)
	s_waitcnt lgkmcnt(0)
	v_mfma_f32_16x16x32_bf16 v[30:33], v[130:133], v[200:203], v[30:33]
	v_mfma_f32_16x16x32_bf16 v[26:29], v[138:141], v[200:203], v[26:29]
	v_mfma_f32_16x16x32_bf16 v[46:49], v[130:133], v[208:211], v[46:49]
	v_mfma_f32_16x16x32_bf16 v[42:45], v[138:141], v[208:211], v[42:45]
	s_barrier
	v_mfma_f32_16x16x32_bf16 v[62:65], v[130:133], v[228:231], v[62:65]
	v_mfma_f32_16x16x32_bf16 v[58:61], v[138:141], v[228:231], v[58:61]
	v_mfma_f32_16x16x32_bf16 v[94:97], v[130:133], v[236:239], v[94:97]
	v_mfma_f32_16x16x32_bf16 v[90:93], v[138:141], v[236:239], v[90:93]
	v_mfma_f32_16x16x32_bf16 v[30:33], v[134:137], v[204:207], v[30:33]
	v_mfma_f32_16x16x32_bf16 v[26:29], v[142:145], v[204:207], v[26:29]
	v_mfma_f32_16x16x32_bf16 v[46:49], v[134:137], v[212:215], v[46:49]
	v_mfma_f32_16x16x32_bf16 v[42:45], v[142:145], v[212:215], v[42:45]
	v_mfma_f32_16x16x32_bf16 v[62:65], v[134:137], v[232:235], v[62:65]
	v_mfma_f32_16x16x32_bf16 v[58:61], v[142:145], v[232:235], v[58:61]
	v_mfma_f32_16x16x32_bf16 v[94:97], v[134:137], v[240:243], v[94:97]
	v_mfma_f32_16x16x32_bf16 v[90:93], v[142:145], v[240:243], v[90:93]
	v_mfma_f32_16x16x32_bf16 v[2:5], v[184:187], v[200:203], v[2:5]
	v_mfma_f32_16x16x32_bf16 v[6:9], v[192:195], v[200:203], v[6:9]
	v_mfma_f32_16x16x32_bf16 v[10:13], v[184:187], v[208:211], v[10:13]
	v_mfma_f32_16x16x32_bf16 v[14:17], v[192:195], v[208:211], v[14:17]
	v_mfma_f32_16x16x32_bf16 v[18:21], v[184:187], v[228:231], v[18:21]
	v_mfma_f32_16x16x32_bf16 v[22:25], v[192:195], v[228:231], v[22:25]
	v_mfma_f32_16x16x32_bf16 v[34:37], v[184:187], v[236:239], v[34:37]
	v_mfma_f32_16x16x32_bf16 v[38:41], v[192:195], v[236:239], v[38:41]
	v_mfma_f32_16x16x32_bf16 v[2:5], v[188:191], v[204:207], v[2:5]
	v_mfma_f32_16x16x32_bf16 v[6:9], v[196:199], v[204:207], v[6:9]
	v_mfma_f32_16x16x32_bf16 v[10:13], v[188:191], v[212:215], v[10:13]
	v_mfma_f32_16x16x32_bf16 v[14:17], v[196:199], v[212:215], v[14:17]
	v_mfma_f32_16x16x32_bf16 v[18:21], v[188:191], v[232:235], v[18:21]
	v_mfma_f32_16x16x32_bf16 v[22:25], v[196:199], v[232:235], v[22:25]
	v_mfma_f32_16x16x32_bf16 v[34:37], v[188:191], v[240:243], v[34:37]
	v_mfma_f32_16x16x32_bf16 v[38:41], v[196:199], v[240:243], v[38:41]
	s_barrier
	s_mov_b32 m0, s75
	v_lshl_add_u64 v[244:245], v[244:245], 0, s[22:23]
	s_add_u32 s14, s40, 0x160080
	ds_read_b128 v[200:203], v221 offset:49152
	ds_read_b128 v[204:207], v221 offset:50176
	ds_read_b128 v[208:211], v221 offset:51200
	ds_read_b128 v[212:215], v221 offset:52224
	ds_read_b128 v[228:231], v221 offset:53248
	ds_read_b128 v[232:235], v221 offset:54272
	ds_read_b128 v[236:239], v221 offset:55296
	ds_read_b128 v[240:243], v221 offset:56320
	global_load_lds_dwordx4 v[244:245], off
	v_lshl_add_u64 v[244:245], v[246:247], 0, s[22:23]
	s_mov_b32 m0, s76
	s_addc_u32 s15, s41, 0
	global_load_lds_dwordx4 v[244:245], off
	v_lshl_add_u64 v[244:245], s[14:15], 0, v[150:151]
	s_mov_b32 m0, s77
	s_nop 0
	global_load_lds_dwordx4 v[244:245], off
	v_lshl_add_u64 v[244:245], s[14:15], 0, v[146:147]
	s_mov_b32 m0, s78
	s_nop 0
	global_load_lds_dwordx4 v[244:245], off
	v_lshl_add_u64 v[244:245], v[248:249], 0, s[22:23]
	s_mov_b32 m0, s68
	s_nop 0
	global_load_lds_dwordx4 v[244:245], off
	v_lshl_add_u64 v[244:245], v[250:251], 0, s[22:23]
	s_mov_b32 m0, s69
	s_nop 0
	global_load_lds_dwordx4 v[244:245], off
	s_waitcnt vmcnt(8)
	s_waitcnt lgkmcnt(0)
	v_mfma_f32_16x16x32_bf16 v[114:117], v[130:133], v[200:203], v[114:117]
	v_mfma_f32_16x16x32_bf16 v[110:113], v[138:141], v[200:203], v[110:113]
	v_mfma_f32_16x16x32_bf16 v[126:129], v[130:133], v[208:211], v[126:129]
	v_mfma_f32_16x16x32_bf16 v[122:125], v[138:141], v[208:211], v[122:125]
	s_barrier
	v_mfma_f32_16x16x32_bf16 v[118:121], v[130:133], v[228:231], v[118:121]
	v_mfma_f32_16x16x32_bf16 v[106:109], v[138:141], v[228:231], v[106:109]
	v_mfma_f32_16x16x32_bf16 v[78:81], v[130:133], v[236:239], v[78:81]
	v_mfma_f32_16x16x32_bf16 v[74:77], v[138:141], v[236:239], v[74:77]
	v_mfma_f32_16x16x32_bf16 v[114:117], v[134:137], v[204:207], v[114:117]
	v_mfma_f32_16x16x32_bf16 v[110:113], v[142:145], v[204:207], v[110:113]
	v_mfma_f32_16x16x32_bf16 v[126:129], v[134:137], v[212:215], v[126:129]
	v_mfma_f32_16x16x32_bf16 v[122:125], v[142:145], v[212:215], v[122:125]
	v_mfma_f32_16x16x32_bf16 v[118:121], v[134:137], v[232:235], v[118:121]
	v_mfma_f32_16x16x32_bf16 v[106:109], v[142:145], v[232:235], v[106:109]
	v_mfma_f32_16x16x32_bf16 v[78:81], v[134:137], v[240:243], v[78:81]
	v_mfma_f32_16x16x32_bf16 v[74:77], v[142:145], v[240:243], v[74:77]
	v_mfma_f32_16x16x32_bf16 v[50:53], v[184:187], v[200:203], v[50:53]
	v_mfma_f32_16x16x32_bf16 v[54:57], v[192:195], v[200:203], v[54:57]
	v_mfma_f32_16x16x32_bf16 v[82:85], v[184:187], v[208:211], v[82:85]
	v_mfma_f32_16x16x32_bf16 v[86:89], v[192:195], v[208:211], v[86:89]
	v_mfma_f32_16x16x32_bf16 v[102:105], v[184:187], v[228:231], v[102:105]
	v_mfma_f32_16x16x32_bf16 v[98:101], v[192:195], v[228:231], v[98:101]
	v_mfma_f32_16x16x32_bf16 v[70:73], v[184:187], v[236:239], v[70:73]
	v_mfma_f32_16x16x32_bf16 v[66:69], v[192:195], v[236:239], v[66:69]
	v_mfma_f32_16x16x32_bf16 v[50:53], v[188:191], v[204:207], v[50:53]
	v_mfma_f32_16x16x32_bf16 v[54:57], v[196:199], v[204:207], v[54:57]
	v_mfma_f32_16x16x32_bf16 v[82:85], v[188:191], v[212:215], v[82:85]
	v_mfma_f32_16x16x32_bf16 v[86:89], v[196:199], v[212:215], v[86:89]
	v_mfma_f32_16x16x32_bf16 v[102:105], v[188:191], v[232:235], v[102:105]
	v_mfma_f32_16x16x32_bf16 v[98:101], v[196:199], v[232:235], v[98:101]
	v_mfma_f32_16x16x32_bf16 v[70:73], v[188:191], v[240:243], v[70:73]
	v_mfma_f32_16x16x32_bf16 v[66:69], v[196:199], v[240:243], v[66:69]
	s_barrier
	s_add_i32 s3, s3, 2
	s_add_u32 s36, s36, 0x100
	s_addc_u32 s37, s37, 0
	s_add_u32 s38, s38, 0x100
	s_addc_u32 s39, s39, 0
	s_cmpk_gt_u32 s3, 0x55
	s_cbranch_scc0 .LBB0_877
	s_and_b64 vcc, exec, s[24:25]
	s_cbranch_vccz .LBB0_880
	s_barrier

.LBB0_986:
	ds_read_b128 v[130:133], v172
	ds_read_b128 v[134:137], v172 offset:1024
	ds_read_b128 v[138:141], v172 offset:2048
	ds_read_b128 v[142:145], v172 offset:3072
	ds_read_b128 v[166:169], v173
	ds_read_b128 v[176:179], v173 offset:1024
	ds_read_b128 v[180:183], v173 offset:2048
	ds_read_b128 v[184:187], v173 offset:3072
	s_add_u32 s20, s52, 0xfff80080
	s_addc_u32 s21, s53, -1
	s_cmp_eq_u32 s19, 28
	s_cselect_b32 s57, s3, s21
	s_cselect_b32 s56, s14, s20
	s_cselect_b32 s55, s15, s18
	s_cselect_b32 s54, s16, s17
	v_lshl_add_u64 v[220:221], s[52:53], 0, v[156:157]
	s_add_i32 m0, s65, 0xc000
	ds_read_b128 v[188:191], v174
	ds_read_b128 v[192:195], v174 offset:1024
	ds_read_b128 v[196:199], v174 offset:2048
	ds_read_b128 v[200:203], v174 offset:3072
	ds_read_b128 v[204:207], v174 offset:4096
	ds_read_b128 v[208:211], v174 offset:5120
	ds_read_b128 v[212:215], v174 offset:6144
	ds_read_b128 v[216:219], v174 offset:7168
	global_load_lds_dwordx4 v[220:221], off
	v_lshl_add_u64 v[220:221], s[52:53], 0, v[158:159]
	s_add_i32 m0, s65, 0xe000
	s_nop 0
	global_load_lds_dwordx4 v[220:221], off
	s_waitcnt vmcnt(8)
	s_waitcnt lgkmcnt(0)
	v_mfma_f32_16x16x32_bf16 v[126:129], v[130:133], v[188:191], v[126:129]
	v_mfma_f32_16x16x32_bf16 v[122:125], v[138:141], v[188:191], v[122:125]
	v_mfma_f32_16x16x32_bf16 v[110:113], v[130:133], v[196:199], v[110:113]
	v_mfma_f32_16x16x32_bf16 v[106:109], v[138:141], v[196:199], v[106:109]
	s_barrier
	v_mfma_f32_16x16x32_bf16 v[94:97], v[130:133], v[204:207], v[94:97]
	v_mfma_f32_16x16x32_bf16 v[90:93], v[138:141], v[204:207], v[90:93]
	v_mfma_f32_16x16x32_bf16 v[78:81], v[130:133], v[212:215], v[78:81]
	v_mfma_f32_16x16x32_bf16 v[74:77], v[138:141], v[212:215], v[74:77]
	v_mfma_f32_16x16x32_bf16 v[126:129], v[134:137], v[192:195], v[126:129]
	v_mfma_f32_16x16x32_bf16 v[122:125], v[142:145], v[192:195], v[122:125]
	v_mfma_f32_16x16x32_bf16 v[110:113], v[134:137], v[200:203], v[110:113]
	v_mfma_f32_16x16x32_bf16 v[106:109], v[142:145], v[200:203], v[106:109]
	v_mfma_f32_16x16x32_bf16 v[94:97], v[134:137], v[208:211], v[94:97]
	v_mfma_f32_16x16x32_bf16 v[90:93], v[142:145], v[208:211], v[90:93]
	v_mfma_f32_16x16x32_bf16 v[78:81], v[134:137], v[216:219], v[78:81]
	v_mfma_f32_16x16x32_bf16 v[74:77], v[142:145], v[216:219], v[74:77]
	v_mfma_f32_16x16x32_bf16 v[118:121], v[166:169], v[188:191], v[118:121]
	v_mfma_f32_16x16x32_bf16 v[114:117], v[180:183], v[188:191], v[114:117]
	v_mfma_f32_16x16x32_bf16 v[102:105], v[166:169], v[196:199], v[102:105]
	v_mfma_f32_16x16x32_bf16 v[98:101], v[180:183], v[196:199], v[98:101]
	v_mfma_f32_16x16x32_bf16 v[86:89], v[166:169], v[204:207], v[86:89]
	v_mfma_f32_16x16x32_bf16 v[82:85], v[180:183], v[204:207], v[82:85]
	v_mfma_f32_16x16x32_bf16 v[70:73], v[166:169], v[212:215], v[70:73]
	v_mfma_f32_16x16x32_bf16 v[66:69], v[180:183], v[212:215], v[66:69]
	v_mfma_f32_16x16x32_bf16 v[118:121], v[176:179], v[192:195], v[118:121]
	v_mfma_f32_16x16x32_bf16 v[114:117], v[184:187], v[192:195], v[114:117]
	v_mfma_f32_16x16x32_bf16 v[102:105], v[176:179], v[200:203], v[102:105]
	v_mfma_f32_16x16x32_bf16 v[98:101], v[184:187], v[200:203], v[98:101]
	v_mfma_f32_16x16x32_bf16 v[86:89], v[176:179], v[208:211], v[86:89]
	v_mfma_f32_16x16x32_bf16 v[82:85], v[184:187], v[208:211], v[82:85]
	v_mfma_f32_16x16x32_bf16 v[70:73], v[176:179], v[216:219], v[70:73]
	v_mfma_f32_16x16x32_bf16 v[66:69], v[184:187], v[216:219], v[66:69]
	s_barrier
	s_add_i32 s20, s77, s64
	v_lshl_add_u64 v[220:221], s[54:55], 0, v[146:147]
	s_mov_b32 m0, s20
	ds_read_b128 v[188:191], v174 offset:16384
	ds_read_b128 v[192:195], v174 offset:17408
	ds_read_b128 v[196:199], v174 offset:18432
	ds_read_b128 v[200:203], v174 offset:19456
	ds_read_b128 v[204:207], v174 offset:20480
	ds_read_b128 v[208:211], v174 offset:21504
	ds_read_b128 v[212:215], v174 offset:22528
	ds_read_b128 v[216:219], v174 offset:23552
	global_load_lds_dwordx4 v[220:221], off
	s_add_i32 m0, s20, 0x2000
	s_add_u32 s20, s54, 0x80000
	v_lshl_add_u64 v[222:223], s[54:55], 0, v[148:149]
	s_addc_u32 s21, s55, 0
	s_add_i32 s43, s78, s64
	global_load_lds_dwordx4 v[222:223], off
	v_lshl_add_u64 v[224:225], s[20:21], 0, v[146:147]
	s_mov_b32 m0, s43
	v_lshl_add_u64 v[226:227], s[56:57], 0, v[148:149]
	global_load_lds_dwordx4 v[224:225], off
	v_lshl_add_u64 v[224:225], s[20:21], 0, v[148:149]
	s_add_i32 m0, s43, 0x2000
	s_nop 0
	global_load_lds_dwordx4 v[224:225], off
	v_lshl_add_u64 v[224:225], s[56:57], 0, v[146:147]
	s_mov_b32 m0, s65
	s_nop 0
	global_load_lds_dwordx4 v[224:225], off
	s_mov_b32 m0, s66
	s_nop 0
	global_load_lds_dwordx4 v[226:227], off
	s_waitcnt vmcnt(8)
	s_waitcnt lgkmcnt(0)
	v_mfma_f32_16x16x32_bf16 v[62:65], v[130:133], v[188:191], v[62:65]
	v_mfma_f32_16x16x32_bf16 v[58:61], v[138:141], v[188:191], v[58:61]
	v_mfma_f32_16x16x32_bf16 v[46:49], v[130:133], v[196:199], v[46:49]
	v_mfma_f32_16x16x32_bf16 v[42:45], v[138:141], v[196:199], v[42:45]
	s_barrier
	v_mfma_f32_16x16x32_bf16 v[30:33], v[130:133], v[204:207], v[30:33]
	v_mfma_f32_16x16x32_bf16 v[26:29], v[138:141], v[204:207], v[26:29]
	v_mfma_f32_16x16x32_bf16 v[14:17], v[130:133], v[212:215], v[14:17]
	v_mfma_f32_16x16x32_bf16 v[10:13], v[138:141], v[212:215], v[10:13]
	v_mfma_f32_16x16x32_bf16 v[62:65], v[134:137], v[192:195], v[62:65]
	v_mfma_f32_16x16x32_bf16 v[58:61], v[142:145], v[192:195], v[58:61]
	v_mfma_f32_16x16x32_bf16 v[46:49], v[134:137], v[200:203], v[46:49]
	v_mfma_f32_16x16x32_bf16 v[42:45], v[142:145], v[200:203], v[42:45]
	v_mfma_f32_16x16x32_bf16 v[30:33], v[134:137], v[208:211], v[30:33]
	v_mfma_f32_16x16x32_bf16 v[26:29], v[142:145], v[208:211], v[26:29]
	v_mfma_f32_16x16x32_bf16 v[14:17], v[134:137], v[216:219], v[14:17]
	v_mfma_f32_16x16x32_bf16 v[10:13], v[142:145], v[216:219], v[10:13]
	v_mfma_f32_16x16x32_bf16 v[54:57], v[166:169], v[188:191], v[54:57]
	v_mfma_f32_16x16x32_bf16 v[50:53], v[180:183], v[188:191], v[50:53]
	v_mfma_f32_16x16x32_bf16 v[38:41], v[166:169], v[196:199], v[38:41]
	v_mfma_f32_16x16x32_bf16 v[34:37], v[180:183], v[196:199], v[34:37]
	v_mfma_f32_16x16x32_bf16 v[22:25], v[166:169], v[204:207], v[22:25]
	v_mfma_f32_16x16x32_bf16 v[18:21], v[180:183], v[204:207], v[18:21]
	v_mfma_f32_16x16x32_bf16 v[6:9], v[166:169], v[212:215], v[6:9]
	v_mfma_f32_16x16x32_bf16 v[2:5], v[180:183], v[212:215], v[2:5]
	v_mfma_f32_16x16x32_bf16 v[54:57], v[176:179], v[192:195], v[54:57]
	v_mfma_f32_16x16x32_bf16 v[50:53], v[184:187], v[192:195], v[50:53]
	v_mfma_f32_16x16x32_bf16 v[38:41], v[176:179], v[200:203], v[38:41]
	v_mfma_f32_16x16x32_bf16 v[34:37], v[184:187], v[200:203], v[34:37]
	v_mfma_f32_16x16x32_bf16 v[22:25], v[176:179], v[208:211], v[22:25]
	v_mfma_f32_16x16x32_bf16 v[18:21], v[184:187], v[208:211], v[18:21]
	v_mfma_f32_16x16x32_bf16 v[6:9], v[176:179], v[216:219], v[6:9]
	v_mfma_f32_16x16x32_bf16 v[2:5], v[184:187], v[216:219], v[2:5]
	s_barrier
	s_add_i32 s43, 0, 0x18000
	s_add_i32 s45, 0, 0x1c000
	v_add_u32_e32 v142, s43, v170
	v_add_u32_e32 v184, s45, v170
	ds_read_b128 v[130:133], v142
	ds_read_b128 v[134:137], v142 offset:1024
	ds_read_b128 v[138:141], v142 offset:2048
	ds_read_b128 v[142:145], v142 offset:3072
	ds_read_b128 v[166:169], v184
	ds_read_b128 v[176:179], v184 offset:1024
	ds_read_b128 v[180:183], v184 offset:2048
	ds_read_b128 v[184:187], v184 offset:3072
	s_add_u32 s20, s56, 0x80000
	s_addc_u32 s21, s57, 0
	s_mov_b32 m0, s67
	v_lshl_add_u64 v[228:229], s[20:21], 0, v[146:147]
	ds_read_b128 v[188:191], v174 offset:32768
	ds_read_b128 v[192:195], v174 offset:33792
	ds_read_b128 v[196:199], v174 offset:34816
	ds_read_b128 v[200:203], v174 offset:35840
	ds_read_b128 v[204:207], v174 offset:36864
	ds_read_b128 v[208:211], v174 offset:37888
	ds_read_b128 v[212:215], v174 offset:38912
	ds_read_b128 v[216:219], v174 offset:39936
	global_load_lds_dwordx4 v[228:229], off
	v_lshl_add_u64 v[228:229], s[20:21], 0, v[148:149]
	s_mov_b32 m0, s68
	s_nop 0
	global_load_lds_dwordx4 v[228:229], off
	s_waitcnt vmcnt(8)
	s_waitcnt lgkmcnt(0)
	v_mfma_f32_16x16x32_bf16 v[126:129], v[130:133], v[188:191], v[126:129]
	v_mfma_f32_16x16x32_bf16 v[122:125], v[138:141], v[188:191], v[122:125]
	v_mfma_f32_16x16x32_bf16 v[110:113], v[130:133], v[196:199], v[110:113]
	v_mfma_f32_16x16x32_bf16 v[106:109], v[138:141], v[196:199], v[106:109]
	s_barrier
	v_mfma_f32_16x16x32_bf16 v[94:97], v[130:133], v[204:207], v[94:97]
	v_mfma_f32_16x16x32_bf16 v[90:93], v[138:141], v[204:207], v[90:93]
	v_mfma_f32_16x16x32_bf16 v[78:81], v[130:133], v[212:215], v[78:81]
	v_mfma_f32_16x16x32_bf16 v[74:77], v[138:141], v[212:215], v[74:77]
	v_mfma_f32_16x16x32_bf16 v[126:129], v[134:137], v[192:195], v[126:129]
	v_mfma_f32_16x16x32_bf16 v[122:125], v[142:145], v[192:195], v[122:125]
	v_mfma_f32_16x16x32_bf16 v[110:113], v[134:137], v[200:203], v[110:113]
	v_mfma_f32_16x16x32_bf16 v[106:109], v[142:145], v[200:203], v[106:109]
	v_mfma_f32_16x16x32_bf16 v[94:97], v[134:137], v[208:211], v[94:97]
	v_mfma_f32_16x16x32_bf16 v[90:93], v[142:145], v[208:211], v[90:93]
	v_mfma_f32_16x16x32_bf16 v[78:81], v[134:137], v[216:219], v[78:81]
	v_mfma_f32_16x16x32_bf16 v[74:77], v[142:145], v[216:219], v[74:77]
	v_mfma_f32_16x16x32_bf16 v[118:121], v[166:169], v[188:191], v[118:121]
	v_mfma_f32_16x16x32_bf16 v[114:117], v[180:183], v[188:191], v[114:117]
	v_mfma_f32_16x16x32_bf16 v[102:105], v[166:169], v[196:199], v[102:105]
	v_mfma_f32_16x16x32_bf16 v[98:101], v[180:183], v[196:199], v[98:101]
	v_mfma_f32_16x16x32_bf16 v[86:89], v[166:169], v[204:207], v[86:89]
	v_mfma_f32_16x16x32_bf16 v[82:85], v[180:183], v[204:207], v[82:85]
	v_mfma_f32_16x16x32_bf16 v[70:73], v[166:169], v[212:215], v[70:73]
	v_mfma_f32_16x16x32_bf16 v[66:69], v[180:183], v[212:215], v[66:69]
	v_mfma_f32_16x16x32_bf16 v[118:121], v[176:179], v[192:195], v[118:121]
	v_mfma_f32_16x16x32_bf16 v[114:117], v[184:187], v[192:195], v[114:117]
	v_mfma_f32_16x16x32_bf16 v[102:105], v[176:179], v[200:203], v[102:105]
	v_mfma_f32_16x16x32_bf16 v[98:101], v[184:187], v[200:203], v[98:101]
	v_mfma_f32_16x16x32_bf16 v[86:89], v[176:179], v[208:211], v[86:89]
	v_mfma_f32_16x16x32_bf16 v[82:85], v[184:187], v[208:211], v[82:85]
	v_mfma_f32_16x16x32_bf16 v[70:73], v[176:179], v[216:219], v[70:73]
	v_mfma_f32_16x16x32_bf16 v[66:69], v[184:187], v[216:219], v[66:69]
	s_barrier
	s_add_i32 s20, s43, s64
	v_lshl_add_u64 v[220:221], v[220:221], 0, s[26:27]
	s_mov_b32 m0, s20
	ds_read_b128 v[188:191], v174 offset:49152
	ds_read_b128 v[192:195], v174 offset:50176
	ds_read_b128 v[196:199], v174 offset:51200
	ds_read_b128 v[200:203], v174 offset:52224
	ds_read_b128 v[204:207], v174 offset:53248
	ds_read_b128 v[208:211], v174 offset:54272
	ds_read_b128 v[212:215], v174 offset:55296
	ds_read_b128 v[216:219], v174 offset:56320
	global_load_lds_dwordx4 v[220:221], off
	s_add_i32 m0, s20, 0x2000
	s_add_u32 s20, s54, 0x80080
	v_lshl_add_u64 v[220:221], v[222:223], 0, s[26:27]
	s_addc_u32 s21, s55, 0
	s_add_i32 s43, s45, s64
	global_load_lds_dwordx4 v[220:221], off
	v_lshl_add_u64 v[220:221], s[20:21], 0, v[146:147]
	s_mov_b32 m0, s43
	s_nop 0
	global_load_lds_dwordx4 v[220:221], off
	v_lshl_add_u64 v[220:221], s[20:21], 0, v[148:149]
	s_add_i32 m0, s43, 0x2000
	s_nop 0
	global_load_lds_dwordx4 v[220:221], off
	v_lshl_add_u64 v[220:221], v[224:225], 0, s[26:27]
	s_mov_b32 m0, s73
	s_nop 0
	global_load_lds_dwordx4 v[220:221], off
	v_lshl_add_u64 v[220:221], v[226:227], 0, s[26:27]
	s_mov_b32 m0, s74
	s_nop 0
	global_load_lds_dwordx4 v[220:221], off
	s_waitcnt vmcnt(8)
	s_waitcnt lgkmcnt(0)
	v_mfma_f32_16x16x32_bf16 v[62:65], v[130:133], v[188:191], v[62:65]
	v_mfma_f32_16x16x32_bf16 v[58:61], v[138:141], v[188:191], v[58:61]
	v_mfma_f32_16x16x32_bf16 v[46:49], v[130:133], v[196:199], v[46:49]
	v_mfma_f32_16x16x32_bf16 v[42:45], v[138:141], v[196:199], v[42:45]
	s_barrier
	v_mfma_f32_16x16x32_bf16 v[30:33], v[130:133], v[204:207], v[30:33]
	v_mfma_f32_16x16x32_bf16 v[26:29], v[138:141], v[204:207], v[26:29]
	v_mfma_f32_16x16x32_bf16 v[14:17], v[130:133], v[212:215], v[14:17]
	v_mfma_f32_16x16x32_bf16 v[10:13], v[138:141], v[212:215], v[10:13]
	v_mfma_f32_16x16x32_bf16 v[62:65], v[134:137], v[192:195], v[62:65]
	v_mfma_f32_16x16x32_bf16 v[58:61], v[142:145], v[192:195], v[58:61]
	v_mfma_f32_16x16x32_bf16 v[46:49], v[134:137], v[200:203], v[46:49]
	v_mfma_f32_16x16x32_bf16 v[42:45], v[142:145], v[200:203], v[42:45]
	v_mfma_f32_16x16x32_bf16 v[30:33], v[134:137], v[208:211], v[30:33]
	v_mfma_f32_16x16x32_bf16 v[26:29], v[142:145], v[208:211], v[26:29]
	v_mfma_f32_16x16x32_bf16 v[14:17], v[134:137], v[216:219], v[14:17]
	v_mfma_f32_16x16x32_bf16 v[10:13], v[142:145], v[216:219], v[10:13]
	v_mfma_f32_16x16x32_bf16 v[54:57], v[166:169], v[188:191], v[54:57]
	v_mfma_f32_16x16x32_bf16 v[50:53], v[180:183], v[188:191], v[50:53]
	v_mfma_f32_16x16x32_bf16 v[38:41], v[166:169], v[196:199], v[38:41]
	v_mfma_f32_16x16x32_bf16 v[34:37], v[180:183], v[196:199], v[34:37]
	v_mfma_f32_16x16x32_bf16 v[22:25], v[166:169], v[204:207], v[22:25]
	v_mfma_f32_16x16x32_bf16 v[18:21], v[180:183], v[204:207], v[18:21]
	v_mfma_f32_16x16x32_bf16 v[6:9], v[166:169], v[212:215], v[6:9]
	v_mfma_f32_16x16x32_bf16 v[2:5], v[180:183], v[212:215], v[2:5]
	v_mfma_f32_16x16x32_bf16 v[54:57], v[176:179], v[192:195], v[54:57]
	v_mfma_f32_16x16x32_bf16 v[50:53], v[184:187], v[192:195], v[50:53]
	v_mfma_f32_16x16x32_bf16 v[38:41], v[176:179], v[200:203], v[38:41]
	v_mfma_f32_16x16x32_bf16 v[34:37], v[184:187], v[200:203], v[34:37]
	v_mfma_f32_16x16x32_bf16 v[22:25], v[176:179], v[208:211], v[22:25]
	v_mfma_f32_16x16x32_bf16 v[18:21], v[184:187], v[208:211], v[18:21]
	v_mfma_f32_16x16x32_bf16 v[6:9], v[176:179], v[216:219], v[6:9]
	v_mfma_f32_16x16x32_bf16 v[2:5], v[184:187], v[216:219], v[2:5]
	s_barrier
	s_add_i32 s19, s19, 2
	s_add_u32 s52, s52, 0x100
	s_addc_u32 s53, s53, 0
	s_add_u32 s17, s17, 0x100
	s_addc_u32 s18, s18, 0
	s_cmp_gt_u32 s19, 29
	s_cbranch_scc0 .LBB0_986
	s_and_b64 vcc, exec, s[28:29]
	s_cbranch_vccnz .LBB0_991
	v_lshl_add_u32 v166, s50, 8, v163
	s_cmp_gt_i32 s10, 1
	s_mov_b64 s[50:51], -1
	s_cbranch_scc1 .LBB0_992

.LBB0_1213:
	ds_read_b128 v[130:133], v189
	ds_read_b128 v[134:137], v189 offset:1024
	ds_read_b128 v[138:141], v189 offset:2048
	ds_read_b128 v[142:145], v189 offset:3072
	ds_read_b128 v[164:167], v190
	ds_read_b128 v[168:171], v190 offset:1024
	ds_read_b128 v[172:175], v190 offset:2048
	ds_read_b128 v[194:197], v190 offset:3072
	s_add_u32 s20, s52, 0xfff80080
	s_addc_u32 s21, s53, -1
	s_cmp_eq_u32 s19, 28
	s_cselect_b32 s57, s3, s21
	s_cselect_b32 s56, s14, s20
	s_cselect_b32 s55, s15, s18
	s_cselect_b32 s54, s16, s17
	v_lshl_add_u64 v[230:231], s[52:53], 0, v[154:155]
	s_add_i32 m0, s65, 0xc000
	ds_read_b128 v[198:201], v191
	ds_read_b128 v[202:205], v191 offset:1024
	ds_read_b128 v[206:209], v191 offset:2048
	ds_read_b128 v[210:213], v191 offset:3072
	ds_read_b128 v[214:217], v191 offset:4096
	ds_read_b128 v[218:221], v191 offset:5120
	ds_read_b128 v[222:225], v191 offset:6144
	ds_read_b128 v[226:229], v191 offset:7168
	global_load_lds_dwordx4 v[230:231], off
	v_lshl_add_u64 v[230:231], s[52:53], 0, v[156:157]
	s_add_i32 m0, s65, 0xe000
	s_nop 0
	global_load_lds_dwordx4 v[230:231], off
	s_waitcnt vmcnt(8)
	s_waitcnt lgkmcnt(0)
	v_mfma_f32_16x16x32_bf16 v[126:129], v[130:133], v[198:201], v[126:129]
	v_mfma_f32_16x16x32_bf16 v[122:125], v[138:141], v[198:201], v[122:125]
	v_mfma_f32_16x16x32_bf16 v[110:113], v[130:133], v[206:209], v[110:113]
	v_mfma_f32_16x16x32_bf16 v[106:109], v[138:141], v[206:209], v[106:109]
	s_barrier
	v_mfma_f32_16x16x32_bf16 v[94:97], v[130:133], v[214:217], v[94:97]
	v_mfma_f32_16x16x32_bf16 v[90:93], v[138:141], v[214:217], v[90:93]
	v_mfma_f32_16x16x32_bf16 v[78:81], v[130:133], v[222:225], v[78:81]
	v_mfma_f32_16x16x32_bf16 v[74:77], v[138:141], v[222:225], v[74:77]
	v_mfma_f32_16x16x32_bf16 v[126:129], v[134:137], v[202:205], v[126:129]
	v_mfma_f32_16x16x32_bf16 v[122:125], v[142:145], v[202:205], v[122:125]
	v_mfma_f32_16x16x32_bf16 v[110:113], v[134:137], v[210:213], v[110:113]
	v_mfma_f32_16x16x32_bf16 v[106:109], v[142:145], v[210:213], v[106:109]
	v_mfma_f32_16x16x32_bf16 v[94:97], v[134:137], v[218:221], v[94:97]
	v_mfma_f32_16x16x32_bf16 v[90:93], v[142:145], v[218:221], v[90:93]
	v_mfma_f32_16x16x32_bf16 v[78:81], v[134:137], v[226:229], v[78:81]
	v_mfma_f32_16x16x32_bf16 v[74:77], v[142:145], v[226:229], v[74:77]
	v_mfma_f32_16x16x32_bf16 v[118:121], v[164:167], v[198:201], v[118:121]
	v_mfma_f32_16x16x32_bf16 v[114:117], v[172:175], v[198:201], v[114:117]
	v_mfma_f32_16x16x32_bf16 v[102:105], v[164:167], v[206:209], v[102:105]
	v_mfma_f32_16x16x32_bf16 v[98:101], v[172:175], v[206:209], v[98:101]
	v_mfma_f32_16x16x32_bf16 v[86:89], v[164:167], v[214:217], v[86:89]
	v_mfma_f32_16x16x32_bf16 v[82:85], v[172:175], v[214:217], v[82:85]
	v_mfma_f32_16x16x32_bf16 v[70:73], v[164:167], v[222:225], v[70:73]
	v_mfma_f32_16x16x32_bf16 v[66:69], v[172:175], v[222:225], v[66:69]
	v_mfma_f32_16x16x32_bf16 v[118:121], v[168:171], v[202:205], v[118:121]
	v_mfma_f32_16x16x32_bf16 v[114:117], v[194:197], v[202:205], v[114:117]
	v_mfma_f32_16x16x32_bf16 v[102:105], v[168:171], v[210:213], v[102:105]
	v_mfma_f32_16x16x32_bf16 v[98:101], v[194:197], v[210:213], v[98:101]
	v_mfma_f32_16x16x32_bf16 v[86:89], v[168:171], v[218:221], v[86:89]
	v_mfma_f32_16x16x32_bf16 v[82:85], v[194:197], v[218:221], v[82:85]
	v_mfma_f32_16x16x32_bf16 v[70:73], v[168:171], v[226:229], v[70:73]
	v_mfma_f32_16x16x32_bf16 v[66:69], v[194:197], v[226:229], v[66:69]
	s_barrier
	s_add_i32 s20, s77, s64
	v_lshl_add_u64 v[230:231], s[54:55], 0, v[146:147]
	s_mov_b32 m0, s20
	ds_read_b128 v[198:201], v191 offset:16384
	ds_read_b128 v[202:205], v191 offset:17408
	ds_read_b128 v[206:209], v191 offset:18432
	ds_read_b128 v[210:213], v191 offset:19456
	ds_read_b128 v[214:217], v191 offset:20480
	ds_read_b128 v[218:221], v191 offset:21504
	ds_read_b128 v[222:225], v191 offset:22528
	ds_read_b128 v[226:229], v191 offset:23552
	global_load_lds_dwordx4 v[230:231], off
	s_add_i32 m0, s20, 0x2000
	s_add_u32 s20, s54, 0x80000
	v_lshl_add_u64 v[232:233], s[54:55], 0, v[148:149]
	s_addc_u32 s21, s55, 0
	s_add_i32 s43, s78, s64
	global_load_lds_dwordx4 v[232:233], off
	v_lshl_add_u64 v[234:235], s[20:21], 0, v[146:147]
	s_mov_b32 m0, s43
	v_lshl_add_u64 v[236:237], s[56:57], 0, v[148:149]
	global_load_lds_dwordx4 v[234:235], off
	v_lshl_add_u64 v[234:235], s[20:21], 0, v[148:149]
	s_add_i32 m0, s43, 0x2000
	s_nop 0
	global_load_lds_dwordx4 v[234:235], off
	v_lshl_add_u64 v[234:235], s[56:57], 0, v[146:147]
	s_mov_b32 m0, s65
	s_nop 0
	global_load_lds_dwordx4 v[234:235], off
	s_mov_b32 m0, s66
	s_nop 0
	global_load_lds_dwordx4 v[236:237], off
	s_waitcnt vmcnt(8)
	s_waitcnt lgkmcnt(0)
	v_mfma_f32_16x16x32_bf16 v[62:65], v[130:133], v[198:201], v[62:65]
	v_mfma_f32_16x16x32_bf16 v[58:61], v[138:141], v[198:201], v[58:61]
	v_mfma_f32_16x16x32_bf16 v[46:49], v[130:133], v[206:209], v[46:49]
	v_mfma_f32_16x16x32_bf16 v[42:45], v[138:141], v[206:209], v[42:45]
	s_barrier
	v_mfma_f32_16x16x32_bf16 v[30:33], v[130:133], v[214:217], v[30:33]
	v_mfma_f32_16x16x32_bf16 v[26:29], v[138:141], v[214:217], v[26:29]
	v_mfma_f32_16x16x32_bf16 v[14:17], v[130:133], v[222:225], v[14:17]
	v_mfma_f32_16x16x32_bf16 v[10:13], v[138:141], v[222:225], v[10:13]
	v_mfma_f32_16x16x32_bf16 v[62:65], v[134:137], v[202:205], v[62:65]
	v_mfma_f32_16x16x32_bf16 v[58:61], v[142:145], v[202:205], v[58:61]
	v_mfma_f32_16x16x32_bf16 v[46:49], v[134:137], v[210:213], v[46:49]
	v_mfma_f32_16x16x32_bf16 v[42:45], v[142:145], v[210:213], v[42:45]
	v_mfma_f32_16x16x32_bf16 v[30:33], v[134:137], v[218:221], v[30:33]
	v_mfma_f32_16x16x32_bf16 v[26:29], v[142:145], v[218:221], v[26:29]
	v_mfma_f32_16x16x32_bf16 v[14:17], v[134:137], v[226:229], v[14:17]
	v_mfma_f32_16x16x32_bf16 v[10:13], v[142:145], v[226:229], v[10:13]
	v_mfma_f32_16x16x32_bf16 v[54:57], v[164:167], v[198:201], v[54:57]
	v_mfma_f32_16x16x32_bf16 v[50:53], v[172:175], v[198:201], v[50:53]
	v_mfma_f32_16x16x32_bf16 v[38:41], v[164:167], v[206:209], v[38:41]
	v_mfma_f32_16x16x32_bf16 v[34:37], v[172:175], v[206:209], v[34:37]
	v_mfma_f32_16x16x32_bf16 v[22:25], v[164:167], v[214:217], v[22:25]
	v_mfma_f32_16x16x32_bf16 v[18:21], v[172:175], v[214:217], v[18:21]
	v_mfma_f32_16x16x32_bf16 v[6:9], v[164:167], v[222:225], v[6:9]
	v_mfma_f32_16x16x32_bf16 v[2:5], v[172:175], v[222:225], v[2:5]
	v_mfma_f32_16x16x32_bf16 v[54:57], v[168:171], v[202:205], v[54:57]
	v_mfma_f32_16x16x32_bf16 v[50:53], v[194:197], v[202:205], v[50:53]
	v_mfma_f32_16x16x32_bf16 v[38:41], v[168:171], v[210:213], v[38:41]
	v_mfma_f32_16x16x32_bf16 v[34:37], v[194:197], v[210:213], v[34:37]
	v_mfma_f32_16x16x32_bf16 v[22:25], v[168:171], v[218:221], v[22:25]
	v_mfma_f32_16x16x32_bf16 v[18:21], v[194:197], v[218:221], v[18:21]
	v_mfma_f32_16x16x32_bf16 v[6:9], v[168:171], v[226:229], v[6:9]
	v_mfma_f32_16x16x32_bf16 v[2:5], v[194:197], v[226:229], v[2:5]
	s_barrier
	s_add_i32 s43, 0, 0x18000
	s_add_i32 s45, 0, 0x1c000
	v_add_u32_e32 v142, s43, v187
	v_add_u32_e32 v193, s45, v187
	ds_read_b128 v[130:133], v142
	ds_read_b128 v[134:137], v142 offset:1024
	ds_read_b128 v[138:141], v142 offset:2048
	ds_read_b128 v[142:145], v142 offset:3072
	ds_read_b128 v[164:167], v193
	ds_read_b128 v[168:171], v193 offset:1024
	ds_read_b128 v[172:175], v193 offset:2048
	ds_read_b128 v[194:197], v193 offset:3072
	s_add_u32 s20, s56, 0x80000
	s_addc_u32 s21, s57, 0
	s_mov_b32 m0, s67
	v_lshl_add_u64 v[238:239], s[20:21], 0, v[146:147]
	ds_read_b128 v[198:201], v191 offset:32768
	ds_read_b128 v[202:205], v191 offset:33792
	ds_read_b128 v[206:209], v191 offset:34816
	ds_read_b128 v[210:213], v191 offset:35840
	ds_read_b128 v[214:217], v191 offset:36864
	ds_read_b128 v[218:221], v191 offset:37888
	ds_read_b128 v[222:225], v191 offset:38912
	ds_read_b128 v[226:229], v191 offset:39936
	global_load_lds_dwordx4 v[238:239], off
	v_lshl_add_u64 v[238:239], s[20:21], 0, v[148:149]
	s_mov_b32 m0, s68
	s_nop 0
	global_load_lds_dwordx4 v[238:239], off
	s_waitcnt vmcnt(8)
	s_waitcnt lgkmcnt(0)
	v_mfma_f32_16x16x32_bf16 v[126:129], v[130:133], v[198:201], v[126:129]
	v_mfma_f32_16x16x32_bf16 v[122:125], v[138:141], v[198:201], v[122:125]
	v_mfma_f32_16x16x32_bf16 v[110:113], v[130:133], v[206:209], v[110:113]
	v_mfma_f32_16x16x32_bf16 v[106:109], v[138:141], v[206:209], v[106:109]
	s_barrier
	v_mfma_f32_16x16x32_bf16 v[94:97], v[130:133], v[214:217], v[94:97]
	v_mfma_f32_16x16x32_bf16 v[90:93], v[138:141], v[214:217], v[90:93]
	v_mfma_f32_16x16x32_bf16 v[78:81], v[130:133], v[222:225], v[78:81]
	v_mfma_f32_16x16x32_bf16 v[74:77], v[138:141], v[222:225], v[74:77]
	v_mfma_f32_16x16x32_bf16 v[126:129], v[134:137], v[202:205], v[126:129]
	v_mfma_f32_16x16x32_bf16 v[122:125], v[142:145], v[202:205], v[122:125]
	v_mfma_f32_16x16x32_bf16 v[110:113], v[134:137], v[210:213], v[110:113]
	v_mfma_f32_16x16x32_bf16 v[106:109], v[142:145], v[210:213], v[106:109]
	v_mfma_f32_16x16x32_bf16 v[94:97], v[134:137], v[218:221], v[94:97]
	v_mfma_f32_16x16x32_bf16 v[90:93], v[142:145], v[218:221], v[90:93]
	v_mfma_f32_16x16x32_bf16 v[78:81], v[134:137], v[226:229], v[78:81]
	v_mfma_f32_16x16x32_bf16 v[74:77], v[142:145], v[226:229], v[74:77]
	v_mfma_f32_16x16x32_bf16 v[118:121], v[164:167], v[198:201], v[118:121]
	v_mfma_f32_16x16x32_bf16 v[114:117], v[172:175], v[198:201], v[114:117]
	v_mfma_f32_16x16x32_bf16 v[102:105], v[164:167], v[206:209], v[102:105]
	v_mfma_f32_16x16x32_bf16 v[98:101], v[172:175], v[206:209], v[98:101]
	v_mfma_f32_16x16x32_bf16 v[86:89], v[164:167], v[214:217], v[86:89]
	v_mfma_f32_16x16x32_bf16 v[82:85], v[172:175], v[214:217], v[82:85]
	v_mfma_f32_16x16x32_bf16 v[70:73], v[164:167], v[222:225], v[70:73]
	v_mfma_f32_16x16x32_bf16 v[66:69], v[172:175], v[222:225], v[66:69]
	v_mfma_f32_16x16x32_bf16 v[118:121], v[168:171], v[202:205], v[118:121]
	v_mfma_f32_16x16x32_bf16 v[114:117], v[194:197], v[202:205], v[114:117]
	v_mfma_f32_16x16x32_bf16 v[102:105], v[168:171], v[210:213], v[102:105]
	v_mfma_f32_16x16x32_bf16 v[98:101], v[194:197], v[210:213], v[98:101]
	v_mfma_f32_16x16x32_bf16 v[86:89], v[168:171], v[218:221], v[86:89]
	v_mfma_f32_16x16x32_bf16 v[82:85], v[194:197], v[218:221], v[82:85]
	v_mfma_f32_16x16x32_bf16 v[70:73], v[168:171], v[226:229], v[70:73]
	v_mfma_f32_16x16x32_bf16 v[66:69], v[194:197], v[226:229], v[66:69]
	s_barrier
	s_add_i32 s20, s43, s64
	v_lshl_add_u64 v[230:231], v[230:231], 0, s[26:27]
	s_mov_b32 m0, s20
	ds_read_b128 v[198:201], v191 offset:49152
	ds_read_b128 v[202:205], v191 offset:50176
	ds_read_b128 v[206:209], v191 offset:51200
	ds_read_b128 v[210:213], v191 offset:52224
	ds_read_b128 v[214:217], v191 offset:53248
	ds_read_b128 v[218:221], v191 offset:54272
	ds_read_b128 v[222:225], v191 offset:55296
	ds_read_b128 v[226:229], v191 offset:56320
	global_load_lds_dwordx4 v[230:231], off
	s_add_i32 m0, s20, 0x2000
	s_add_u32 s20, s54, 0x80080
	v_lshl_add_u64 v[230:231], v[232:233], 0, s[26:27]
	s_addc_u32 s21, s55, 0
	s_add_i32 s43, s45, s64
	global_load_lds_dwordx4 v[230:231], off
	v_lshl_add_u64 v[230:231], s[20:21], 0, v[146:147]
	s_mov_b32 m0, s43
	s_nop 0
	global_load_lds_dwordx4 v[230:231], off
	v_lshl_add_u64 v[230:231], s[20:21], 0, v[148:149]
	s_add_i32 m0, s43, 0x2000
	s_nop 0
	global_load_lds_dwordx4 v[230:231], off
	v_lshl_add_u64 v[230:231], v[234:235], 0, s[26:27]
	s_mov_b32 m0, s73
	s_nop 0
	global_load_lds_dwordx4 v[230:231], off
	v_lshl_add_u64 v[230:231], v[236:237], 0, s[26:27]
	s_mov_b32 m0, s74
	s_nop 0
	global_load_lds_dwordx4 v[230:231], off
	s_waitcnt vmcnt(8)
	s_waitcnt lgkmcnt(0)
	v_mfma_f32_16x16x32_bf16 v[62:65], v[130:133], v[198:201], v[62:65]
	v_mfma_f32_16x16x32_bf16 v[58:61], v[138:141], v[198:201], v[58:61]
	v_mfma_f32_16x16x32_bf16 v[46:49], v[130:133], v[206:209], v[46:49]
	v_mfma_f32_16x16x32_bf16 v[42:45], v[138:141], v[206:209], v[42:45]
	s_barrier
	v_mfma_f32_16x16x32_bf16 v[30:33], v[130:133], v[214:217], v[30:33]
	v_mfma_f32_16x16x32_bf16 v[26:29], v[138:141], v[214:217], v[26:29]
	v_mfma_f32_16x16x32_bf16 v[14:17], v[130:133], v[222:225], v[14:17]
	v_mfma_f32_16x16x32_bf16 v[10:13], v[138:141], v[222:225], v[10:13]
	v_mfma_f32_16x16x32_bf16 v[62:65], v[134:137], v[202:205], v[62:65]
	v_mfma_f32_16x16x32_bf16 v[58:61], v[142:145], v[202:205], v[58:61]
	v_mfma_f32_16x16x32_bf16 v[46:49], v[134:137], v[210:213], v[46:49]
	v_mfma_f32_16x16x32_bf16 v[42:45], v[142:145], v[210:213], v[42:45]
	v_mfma_f32_16x16x32_bf16 v[30:33], v[134:137], v[218:221], v[30:33]
	v_mfma_f32_16x16x32_bf16 v[26:29], v[142:145], v[218:221], v[26:29]
	v_mfma_f32_16x16x32_bf16 v[14:17], v[134:137], v[226:229], v[14:17]
	v_mfma_f32_16x16x32_bf16 v[10:13], v[142:145], v[226:229], v[10:13]
	v_mfma_f32_16x16x32_bf16 v[54:57], v[164:167], v[198:201], v[54:57]
	v_mfma_f32_16x16x32_bf16 v[50:53], v[172:175], v[198:201], v[50:53]
	v_mfma_f32_16x16x32_bf16 v[38:41], v[164:167], v[206:209], v[38:41]
	v_mfma_f32_16x16x32_bf16 v[34:37], v[172:175], v[206:209], v[34:37]
	v_mfma_f32_16x16x32_bf16 v[22:25], v[164:167], v[214:217], v[22:25]
	v_mfma_f32_16x16x32_bf16 v[18:21], v[172:175], v[214:217], v[18:21]
	v_mfma_f32_16x16x32_bf16 v[6:9], v[164:167], v[222:225], v[6:9]
	v_mfma_f32_16x16x32_bf16 v[2:5], v[172:175], v[222:225], v[2:5]
	v_mfma_f32_16x16x32_bf16 v[54:57], v[168:171], v[202:205], v[54:57]
	v_mfma_f32_16x16x32_bf16 v[50:53], v[194:197], v[202:205], v[50:53]
	v_mfma_f32_16x16x32_bf16 v[38:41], v[168:171], v[210:213], v[38:41]
	v_mfma_f32_16x16x32_bf16 v[34:37], v[194:197], v[210:213], v[34:37]
	v_mfma_f32_16x16x32_bf16 v[22:25], v[168:171], v[218:221], v[22:25]
	v_mfma_f32_16x16x32_bf16 v[18:21], v[194:197], v[218:221], v[18:21]
	v_mfma_f32_16x16x32_bf16 v[6:9], v[168:171], v[226:229], v[6:9]
	v_mfma_f32_16x16x32_bf16 v[2:5], v[194:197], v[226:229], v[2:5]
	s_barrier
	s_add_i32 s19, s19, 2
	s_add_u32 s52, s52, 0x100
	s_addc_u32 s53, s53, 0
	s_add_u32 s17, s17, 0x100
	s_addc_u32 s18, s18, 0
	s_cmp_gt_u32 s19, 29
	s_cbranch_scc0 .LBB0_1213
	s_and_b64 vcc, exec, s[28:29]
	s_cbranch_vccnz .LBB0_1218
	v_lshl_add_u32 v164, s50, 8, v186
	s_cmp_gt_i32 s10, 1
	s_mov_b64 s[50:51], -1
	s_cbranch_scc1 .LBB0_1219

.LBB0_1264:
	ds_read_b128 v[142:145], v163
	ds_read_b128 v[146:149], v163 offset:1024
	ds_read_b128 v[150:153], v163 offset:2048
	ds_read_b128 v[154:157], v163 offset:3072
	ds_read_b128 v[170:173], v166
	ds_read_b128 v[174:177], v166 offset:1024
	ds_read_b128 v[178:181], v166 offset:2048
	ds_read_b128 v[182:185], v166 offset:3072
	s_add_u32 s44, s42, 0xfffe0080
	s_addc_u32 s45, s43, -1
	s_cmp_eq_u32 s29, 4
	s_cselect_b32 s47, s3, s45
	s_cselect_b32 s46, s16, s44
	s_cselect_b32 s45, s17, s27
	s_cselect_b32 s44, s18, s19
	v_lshl_add_u64 v[218:219], s[42:43], 0, v[138:139]
	s_add_i32 m0, s39, 0xc000
	ds_read_b128 v[186:189], v167
	ds_read_b128 v[190:193], v167 offset:1024
	ds_read_b128 v[194:197], v167 offset:2048
	ds_read_b128 v[198:201], v167 offset:3072
	ds_read_b128 v[202:205], v167 offset:4096
	ds_read_b128 v[206:209], v167 offset:5120
	ds_read_b128 v[210:213], v167 offset:6144
	ds_read_b128 v[214:217], v167 offset:7168
	global_load_lds_dwordx4 v[218:219], off
	v_lshl_add_u64 v[218:219], s[42:43], 0, v[140:141]
	s_add_i32 m0, s39, 0xe000
	s_nop 0
	global_load_lds_dwordx4 v[218:219], off
	s_waitcnt vmcnt(8)
	s_waitcnt lgkmcnt(0)
	v_mfma_f32_16x16x32_bf16 v[126:129], v[142:145], v[186:189], v[126:129]
	v_mfma_f32_16x16x32_bf16 v[122:125], v[150:153], v[186:189], v[122:125]
	v_mfma_f32_16x16x32_bf16 v[118:121], v[142:145], v[194:197], v[118:121]
	v_mfma_f32_16x16x32_bf16 v[110:113], v[150:153], v[194:197], v[110:113]
	s_barrier
	v_mfma_f32_16x16x32_bf16 v[102:105], v[142:145], v[202:205], v[102:105]
	v_mfma_f32_16x16x32_bf16 v[94:97], v[150:153], v[202:205], v[94:97]
	v_mfma_f32_16x16x32_bf16 v[86:89], v[142:145], v[210:213], v[86:89]
	v_mfma_f32_16x16x32_bf16 v[78:81], v[150:153], v[210:213], v[78:81]
	v_mfma_f32_16x16x32_bf16 v[126:129], v[146:149], v[190:193], v[126:129]
	v_mfma_f32_16x16x32_bf16 v[122:125], v[154:157], v[190:193], v[122:125]
	v_mfma_f32_16x16x32_bf16 v[118:121], v[146:149], v[198:201], v[118:121]
	v_mfma_f32_16x16x32_bf16 v[110:113], v[154:157], v[198:201], v[110:113]
	v_mfma_f32_16x16x32_bf16 v[102:105], v[146:149], v[206:209], v[102:105]
	v_mfma_f32_16x16x32_bf16 v[94:97], v[154:157], v[206:209], v[94:97]
	v_mfma_f32_16x16x32_bf16 v[86:89], v[146:149], v[214:217], v[86:89]
	v_mfma_f32_16x16x32_bf16 v[78:81], v[154:157], v[214:217], v[78:81]
	v_mfma_f32_16x16x32_bf16 v[114:117], v[170:173], v[186:189], v[114:117]
	v_mfma_f32_16x16x32_bf16 v[106:109], v[178:181], v[186:189], v[106:109]
	v_mfma_f32_16x16x32_bf16 v[98:101], v[170:173], v[194:197], v[98:101]
	v_mfma_f32_16x16x32_bf16 v[90:93], v[178:181], v[194:197], v[90:93]
	v_mfma_f32_16x16x32_bf16 v[82:85], v[170:173], v[202:205], v[82:85]
	v_mfma_f32_16x16x32_bf16 v[74:77], v[178:181], v[202:205], v[74:77]
	v_mfma_f32_16x16x32_bf16 v[70:73], v[170:173], v[210:213], v[70:73]
	v_mfma_f32_16x16x32_bf16 v[66:69], v[178:181], v[210:213], v[66:69]
	v_mfma_f32_16x16x32_bf16 v[114:117], v[174:177], v[190:193], v[114:117]
	v_mfma_f32_16x16x32_bf16 v[106:109], v[182:185], v[190:193], v[106:109]
	v_mfma_f32_16x16x32_bf16 v[98:101], v[174:177], v[198:201], v[98:101]
	v_mfma_f32_16x16x32_bf16 v[90:93], v[182:185], v[198:201], v[90:93]
	v_mfma_f32_16x16x32_bf16 v[82:85], v[174:177], v[206:209], v[82:85]
	v_mfma_f32_16x16x32_bf16 v[74:77], v[182:185], v[206:209], v[74:77]
	v_mfma_f32_16x16x32_bf16 v[70:73], v[174:177], v[214:217], v[70:73]
	v_mfma_f32_16x16x32_bf16 v[66:69], v[182:185], v[214:217], v[66:69]
	s_barrier
	s_add_i32 s62, s60, s54
	v_lshl_add_u64 v[218:219], s[44:45], 0, v[132:133]
	s_mov_b32 m0, s62
	ds_read_b128 v[186:189], v167 offset:16384
	ds_read_b128 v[190:193], v167 offset:17408
	ds_read_b128 v[194:197], v167 offset:18432
	ds_read_b128 v[198:201], v167 offset:19456
	ds_read_b128 v[202:205], v167 offset:20480
	ds_read_b128 v[206:209], v167 offset:21504
	ds_read_b128 v[210:213], v167 offset:22528
	ds_read_b128 v[214:217], v167 offset:23552
	global_load_lds_dwordx4 v[218:219], off
	s_add_i32 m0, s62, 0x2000
	s_add_u32 s62, s44, 0x20000
	v_lshl_add_u64 v[220:221], s[44:45], 0, v[136:137]
	s_addc_u32 s63, s45, 0
	s_add_i32 s64, s61, s54
	global_load_lds_dwordx4 v[220:221], off
	v_lshl_add_u64 v[222:223], s[62:63], 0, v[132:133]
	s_mov_b32 m0, s64
	v_lshl_add_u64 v[224:225], s[46:47], 0, v[134:135]
	global_load_lds_dwordx4 v[222:223], off
	v_lshl_add_u64 v[222:223], s[62:63], 0, v[136:137]
	s_add_i32 m0, s64, 0x2000
	s_nop 0
	global_load_lds_dwordx4 v[222:223], off
	v_lshl_add_u64 v[222:223], s[46:47], 0, v[130:131]
	s_mov_b32 m0, s39
	s_nop 0
	global_load_lds_dwordx4 v[222:223], off
	s_mov_b32 m0, s41
	s_nop 0
	global_load_lds_dwordx4 v[224:225], off
	s_waitcnt vmcnt(8)
	s_waitcnt lgkmcnt(0)
	v_mfma_f32_16x16x32_bf16 v[62:65], v[142:145], v[186:189], v[62:65]
	v_mfma_f32_16x16x32_bf16 v[58:61], v[150:153], v[186:189], v[58:61]
	v_mfma_f32_16x16x32_bf16 v[54:57], v[142:145], v[194:197], v[54:57]
	v_mfma_f32_16x16x32_bf16 v[46:49], v[150:153], v[194:197], v[46:49]
	s_barrier
	v_mfma_f32_16x16x32_bf16 v[38:41], v[142:145], v[202:205], v[38:41]
	v_mfma_f32_16x16x32_bf16 v[30:33], v[150:153], v[202:205], v[30:33]
	v_mfma_f32_16x16x32_bf16 v[22:25], v[142:145], v[210:213], v[22:25]
	v_mfma_f32_16x16x32_bf16 v[14:17], v[150:153], v[210:213], v[14:17]
	v_mfma_f32_16x16x32_bf16 v[62:65], v[146:149], v[190:193], v[62:65]
	v_mfma_f32_16x16x32_bf16 v[58:61], v[154:157], v[190:193], v[58:61]
	v_mfma_f32_16x16x32_bf16 v[54:57], v[146:149], v[198:201], v[54:57]
	v_mfma_f32_16x16x32_bf16 v[46:49], v[154:157], v[198:201], v[46:49]
	v_mfma_f32_16x16x32_bf16 v[38:41], v[146:149], v[206:209], v[38:41]
	v_mfma_f32_16x16x32_bf16 v[30:33], v[154:157], v[206:209], v[30:33]
	v_mfma_f32_16x16x32_bf16 v[22:25], v[146:149], v[214:217], v[22:25]
	v_mfma_f32_16x16x32_bf16 v[14:17], v[154:157], v[214:217], v[14:17]
	v_mfma_f32_16x16x32_bf16 v[50:53], v[170:173], v[186:189], v[50:53]
	v_mfma_f32_16x16x32_bf16 v[42:45], v[178:181], v[186:189], v[42:45]
	v_mfma_f32_16x16x32_bf16 v[34:37], v[170:173], v[194:197], v[34:37]
	v_mfma_f32_16x16x32_bf16 v[26:29], v[178:181], v[194:197], v[26:29]
	v_mfma_f32_16x16x32_bf16 v[18:21], v[170:173], v[202:205], v[18:21]
	v_mfma_f32_16x16x32_bf16 v[10:13], v[178:181], v[202:205], v[10:13]
	v_mfma_f32_16x16x32_bf16 v[6:9], v[170:173], v[210:213], v[6:9]
	v_mfma_f32_16x16x32_bf16 v[2:5], v[178:181], v[210:213], v[2:5]
	v_mfma_f32_16x16x32_bf16 v[50:53], v[174:177], v[190:193], v[50:53]
	v_mfma_f32_16x16x32_bf16 v[42:45], v[182:185], v[190:193], v[42:45]
	v_mfma_f32_16x16x32_bf16 v[34:37], v[174:177], v[198:201], v[34:37]
	v_mfma_f32_16x16x32_bf16 v[26:29], v[182:185], v[198:201], v[26:29]
	v_mfma_f32_16x16x32_bf16 v[18:21], v[174:177], v[206:209], v[18:21]
	v_mfma_f32_16x16x32_bf16 v[10:13], v[182:185], v[206:209], v[10:13]
	v_mfma_f32_16x16x32_bf16 v[6:9], v[174:177], v[214:217], v[6:9]
	v_mfma_f32_16x16x32_bf16 v[2:5], v[182:185], v[214:217], v[2:5]
	s_barrier
	s_add_i32 s62, 0, 0x18000
	s_add_i32 s63, 0, 0x1c000
	v_add_u32_e32 v154, s62, v161
	v_add_u32_e32 v158, s63, v161
	ds_read_b128 v[142:145], v154
	ds_read_b128 v[146:149], v154 offset:1024
	ds_read_b128 v[150:153], v154 offset:2048
	ds_read_b128 v[154:157], v154 offset:3072
	ds_read_b128 v[170:173], v158
	ds_read_b128 v[174:177], v158 offset:1024
	ds_read_b128 v[178:181], v158 offset:2048
	ds_read_b128 v[182:185], v158 offset:3072
	s_add_u32 s46, s46, 0x20000
	s_addc_u32 s47, s47, 0
	s_mov_b32 m0, s55
	v_lshl_add_u64 v[226:227], s[46:47], 0, v[130:131]
	ds_read_b128 v[186:189], v167 offset:32768
	ds_read_b128 v[190:193], v167 offset:33792
	ds_read_b128 v[194:197], v167 offset:34816
	ds_read_b128 v[198:201], v167 offset:35840
	ds_read_b128 v[202:205], v167 offset:36864
	ds_read_b128 v[206:209], v167 offset:37888
	ds_read_b128 v[210:213], v167 offset:38912
	ds_read_b128 v[214:217], v167 offset:39936
	global_load_lds_dwordx4 v[226:227], off
	v_lshl_add_u64 v[226:227], s[46:47], 0, v[134:135]
	s_mov_b32 m0, s56
	s_nop 0
	global_load_lds_dwordx4 v[226:227], off
	s_waitcnt vmcnt(8)
	s_waitcnt lgkmcnt(0)
	v_mfma_f32_16x16x32_bf16 v[126:129], v[142:145], v[186:189], v[126:129]
	v_mfma_f32_16x16x32_bf16 v[122:125], v[150:153], v[186:189], v[122:125]
	v_mfma_f32_16x16x32_bf16 v[118:121], v[142:145], v[194:197], v[118:121]
	v_mfma_f32_16x16x32_bf16 v[110:113], v[150:153], v[194:197], v[110:113]
	s_barrier
	v_mfma_f32_16x16x32_bf16 v[102:105], v[142:145], v[202:205], v[102:105]
	v_mfma_f32_16x16x32_bf16 v[94:97], v[150:153], v[202:205], v[94:97]
	v_mfma_f32_16x16x32_bf16 v[86:89], v[142:145], v[210:213], v[86:89]
	v_mfma_f32_16x16x32_bf16 v[78:81], v[150:153], v[210:213], v[78:81]
	v_mfma_f32_16x16x32_bf16 v[126:129], v[146:149], v[190:193], v[126:129]
	v_mfma_f32_16x16x32_bf16 v[122:125], v[154:157], v[190:193], v[122:125]
	v_mfma_f32_16x16x32_bf16 v[118:121], v[146:149], v[198:201], v[118:121]
	v_mfma_f32_16x16x32_bf16 v[110:113], v[154:157], v[198:201], v[110:113]
	v_mfma_f32_16x16x32_bf16 v[102:105], v[146:149], v[206:209], v[102:105]
	v_mfma_f32_16x16x32_bf16 v[94:97], v[154:157], v[206:209], v[94:97]
	v_mfma_f32_16x16x32_bf16 v[86:89], v[146:149], v[214:217], v[86:89]
	v_mfma_f32_16x16x32_bf16 v[78:81], v[154:157], v[214:217], v[78:81]
	v_mfma_f32_16x16x32_bf16 v[114:117], v[170:173], v[186:189], v[114:117]
	v_mfma_f32_16x16x32_bf16 v[106:109], v[178:181], v[186:189], v[106:109]
	v_mfma_f32_16x16x32_bf16 v[98:101], v[170:173], v[194:197], v[98:101]
	v_mfma_f32_16x16x32_bf16 v[90:93], v[178:181], v[194:197], v[90:93]
	v_mfma_f32_16x16x32_bf16 v[82:85], v[170:173], v[202:205], v[82:85]
	v_mfma_f32_16x16x32_bf16 v[74:77], v[178:181], v[202:205], v[74:77]
	v_mfma_f32_16x16x32_bf16 v[70:73], v[170:173], v[210:213], v[70:73]
	v_mfma_f32_16x16x32_bf16 v[66:69], v[178:181], v[210:213], v[66:69]
	v_mfma_f32_16x16x32_bf16 v[114:117], v[174:177], v[190:193], v[114:117]
	v_mfma_f32_16x16x32_bf16 v[106:109], v[182:185], v[190:193], v[106:109]
	v_mfma_f32_16x16x32_bf16 v[98:101], v[174:177], v[198:201], v[98:101]
	v_mfma_f32_16x16x32_bf16 v[90:93], v[182:185], v[198:201], v[90:93]
	v_mfma_f32_16x16x32_bf16 v[82:85], v[174:177], v[206:209], v[82:85]
	v_mfma_f32_16x16x32_bf16 v[74:77], v[182:185], v[206:209], v[74:77]
	v_mfma_f32_16x16x32_bf16 v[70:73], v[174:177], v[214:217], v[70:73]
	v_mfma_f32_16x16x32_bf16 v[66:69], v[182:185], v[214:217], v[66:69]
	s_barrier
	s_add_i32 s46, s62, s54
	v_lshl_add_u64 v[218:219], v[218:219], 0, s[22:23]
	s_mov_b32 m0, s46
	ds_read_b128 v[186:189], v167 offset:49152
	ds_read_b128 v[190:193], v167 offset:50176
	ds_read_b128 v[194:197], v167 offset:51200
	ds_read_b128 v[198:201], v167 offset:52224
	ds_read_b128 v[202:205], v167 offset:53248
	ds_read_b128 v[206:209], v167 offset:54272
	ds_read_b128 v[210:213], v167 offset:55296
	ds_read_b128 v[214:217], v167 offset:56320
	global_load_lds_dwordx4 v[218:219], off
	s_add_i32 m0, s46, 0x2000
	s_add_u32 s44, s44, 0x20080
	v_lshl_add_u64 v[218:219], v[220:221], 0, s[22:23]
	s_addc_u32 s45, s45, 0
	s_add_i32 s46, s63, s54
	global_load_lds_dwordx4 v[218:219], off
	v_lshl_add_u64 v[218:219], s[44:45], 0, v[132:133]
	s_mov_b32 m0, s46
	s_nop 0
	global_load_lds_dwordx4 v[218:219], off
	v_lshl_add_u64 v[218:219], s[44:45], 0, v[136:137]
	s_add_i32 m0, s46, 0x2000
	s_nop 0
	global_load_lds_dwordx4 v[218:219], off
	v_lshl_add_u64 v[218:219], v[222:223], 0, s[22:23]
	s_mov_b32 m0, s14
	s_nop 0
	global_load_lds_dwordx4 v[218:219], off
	v_lshl_add_u64 v[218:219], v[224:225], 0, s[22:23]
	s_mov_b32 m0, s15
	s_nop 0
	global_load_lds_dwordx4 v[218:219], off
	s_waitcnt vmcnt(8)
	s_waitcnt lgkmcnt(0)
	v_mfma_f32_16x16x32_bf16 v[62:65], v[142:145], v[186:189], v[62:65]
	v_mfma_f32_16x16x32_bf16 v[58:61], v[150:153], v[186:189], v[58:61]
	v_mfma_f32_16x16x32_bf16 v[54:57], v[142:145], v[194:197], v[54:57]
	v_mfma_f32_16x16x32_bf16 v[46:49], v[150:153], v[194:197], v[46:49]
	s_barrier
	v_mfma_f32_16x16x32_bf16 v[38:41], v[142:145], v[202:205], v[38:41]
	v_mfma_f32_16x16x32_bf16 v[30:33], v[150:153], v[202:205], v[30:33]
	v_mfma_f32_16x16x32_bf16 v[22:25], v[142:145], v[210:213], v[22:25]
	v_mfma_f32_16x16x32_bf16 v[14:17], v[150:153], v[210:213], v[14:17]
	v_mfma_f32_16x16x32_bf16 v[62:65], v[146:149], v[190:193], v[62:65]
	v_mfma_f32_16x16x32_bf16 v[58:61], v[154:157], v[190:193], v[58:61]
	v_mfma_f32_16x16x32_bf16 v[54:57], v[146:149], v[198:201], v[54:57]
	v_mfma_f32_16x16x32_bf16 v[46:49], v[154:157], v[198:201], v[46:49]
	v_mfma_f32_16x16x32_bf16 v[38:41], v[146:149], v[206:209], v[38:41]
	v_mfma_f32_16x16x32_bf16 v[30:33], v[154:157], v[206:209], v[30:33]
	v_mfma_f32_16x16x32_bf16 v[22:25], v[146:149], v[214:217], v[22:25]
	v_mfma_f32_16x16x32_bf16 v[14:17], v[154:157], v[214:217], v[14:17]
	v_mfma_f32_16x16x32_bf16 v[50:53], v[170:173], v[186:189], v[50:53]
	v_mfma_f32_16x16x32_bf16 v[42:45], v[178:181], v[186:189], v[42:45]
	v_mfma_f32_16x16x32_bf16 v[34:37], v[170:173], v[194:197], v[34:37]
	v_mfma_f32_16x16x32_bf16 v[26:29], v[178:181], v[194:197], v[26:29]
	v_mfma_f32_16x16x32_bf16 v[18:21], v[170:173], v[202:205], v[18:21]
	v_mfma_f32_16x16x32_bf16 v[10:13], v[178:181], v[202:205], v[10:13]
	v_mfma_f32_16x16x32_bf16 v[6:9], v[170:173], v[210:213], v[6:9]
	v_mfma_f32_16x16x32_bf16 v[2:5], v[178:181], v[210:213], v[2:5]
	v_mfma_f32_16x16x32_bf16 v[50:53], v[174:177], v[190:193], v[50:53]
	v_mfma_f32_16x16x32_bf16 v[42:45], v[182:185], v[190:193], v[42:45]
	v_mfma_f32_16x16x32_bf16 v[34:37], v[174:177], v[198:201], v[34:37]
	v_mfma_f32_16x16x32_bf16 v[26:29], v[182:185], v[198:201], v[26:29]
	v_mfma_f32_16x16x32_bf16 v[18:21], v[174:177], v[206:209], v[18:21]
	v_mfma_f32_16x16x32_bf16 v[10:13], v[182:185], v[206:209], v[10:13]
	v_mfma_f32_16x16x32_bf16 v[6:9], v[174:177], v[214:217], v[6:9]
	v_mfma_f32_16x16x32_bf16 v[2:5], v[182:185], v[214:217], v[2:5]
	s_barrier
	s_add_i32 s29, s29, 2
	s_add_u32 s42, s42, 0x100
	s_addc_u32 s43, s43, 0
	s_add_u32 s19, s19, 0x100
	s_addc_u32 s27, s27, 0
	s_cmp_gt_u32 s29, 5
	s_cbranch_scc0 .LBB0_1264
	s_and_b64 vcc, exec, s[24:25]
	s_cbranch_vccz .LBB0_1267
	s_barrier

.LBB0_1336:
	ds_read_b128 v[154:157], v175
	ds_read_b128 v[158:161], v175 offset:1024
	ds_read_b128 v[164:167], v175 offset:2048
	ds_read_b128 v[168:171], v175 offset:3072
	ds_read_b128 v[180:183], v176
	ds_read_b128 v[184:187], v176 offset:1024
	ds_read_b128 v[188:191], v176 offset:2048
	ds_read_b128 v[192:195], v176 offset:3072
	s_add_u32 s20, s36, 0xfffe0080
	s_addc_u32 s21, s37, -1
	s_cmp_eq_u32 s19, 4
	s_cselect_b32 s41, s3, s21
	s_cselect_b32 s40, s14, s20
	s_cselect_b32 s39, s15, s18
	s_cselect_b32 s38, s16, s17
	v_lshl_add_u64 v[228:229], s[36:37], 0, v[144:145]
	s_add_i32 m0, s49, 0xc000
	ds_read_b128 v[196:199], v177
	ds_read_b128 v[200:203], v177 offset:1024
	ds_read_b128 v[204:207], v177 offset:2048
	ds_read_b128 v[208:211], v177 offset:3072
	ds_read_b128 v[212:215], v177 offset:4096
	ds_read_b128 v[216:219], v177 offset:5120
	ds_read_b128 v[220:223], v177 offset:6144
	ds_read_b128 v[224:227], v177 offset:7168
	global_load_lds_dwordx4 v[228:229], off
	v_lshl_add_u64 v[228:229], s[36:37], 0, v[146:147]
	s_add_i32 m0, s49, 0xe000
	s_nop 0
	global_load_lds_dwordx4 v[228:229], off
	s_waitcnt vmcnt(8)
	s_waitcnt lgkmcnt(0)
	v_mfma_f32_16x16x32_bf16 v[126:129], v[154:157], v[196:199], v[126:129]
	v_mfma_f32_16x16x32_bf16 v[122:125], v[164:167], v[196:199], v[122:125]
	v_mfma_f32_16x16x32_bf16 v[118:121], v[154:157], v[204:207], v[118:121]
	v_mfma_f32_16x16x32_bf16 v[110:113], v[164:167], v[204:207], v[110:113]
	s_barrier
	v_mfma_f32_16x16x32_bf16 v[102:105], v[154:157], v[212:215], v[102:105]
	v_mfma_f32_16x16x32_bf16 v[94:97], v[164:167], v[212:215], v[94:97]
	v_mfma_f32_16x16x32_bf16 v[86:89], v[154:157], v[220:223], v[86:89]
	v_mfma_f32_16x16x32_bf16 v[78:81], v[164:167], v[220:223], v[78:81]
	v_mfma_f32_16x16x32_bf16 v[126:129], v[158:161], v[200:203], v[126:129]
	v_mfma_f32_16x16x32_bf16 v[122:125], v[168:171], v[200:203], v[122:125]
	v_mfma_f32_16x16x32_bf16 v[118:121], v[158:161], v[208:211], v[118:121]
	v_mfma_f32_16x16x32_bf16 v[110:113], v[168:171], v[208:211], v[110:113]
	v_mfma_f32_16x16x32_bf16 v[102:105], v[158:161], v[216:219], v[102:105]
	v_mfma_f32_16x16x32_bf16 v[94:97], v[168:171], v[216:219], v[94:97]
	v_mfma_f32_16x16x32_bf16 v[86:89], v[158:161], v[224:227], v[86:89]
	v_mfma_f32_16x16x32_bf16 v[78:81], v[168:171], v[224:227], v[78:81]
	v_mfma_f32_16x16x32_bf16 v[114:117], v[180:183], v[196:199], v[114:117]
	v_mfma_f32_16x16x32_bf16 v[106:109], v[188:191], v[196:199], v[106:109]
	v_mfma_f32_16x16x32_bf16 v[98:101], v[180:183], v[204:207], v[98:101]
	v_mfma_f32_16x16x32_bf16 v[90:93], v[188:191], v[204:207], v[90:93]
	v_mfma_f32_16x16x32_bf16 v[82:85], v[180:183], v[212:215], v[82:85]
	v_mfma_f32_16x16x32_bf16 v[74:77], v[188:191], v[212:215], v[74:77]
	v_mfma_f32_16x16x32_bf16 v[70:73], v[180:183], v[220:223], v[70:73]
	v_mfma_f32_16x16x32_bf16 v[66:69], v[188:191], v[220:223], v[66:69]
	v_mfma_f32_16x16x32_bf16 v[114:117], v[184:187], v[200:203], v[114:117]
	v_mfma_f32_16x16x32_bf16 v[106:109], v[192:195], v[200:203], v[106:109]
	v_mfma_f32_16x16x32_bf16 v[98:101], v[184:187], v[208:211], v[98:101]
	v_mfma_f32_16x16x32_bf16 v[90:93], v[192:195], v[208:211], v[90:93]
	v_mfma_f32_16x16x32_bf16 v[82:85], v[184:187], v[216:219], v[82:85]
	v_mfma_f32_16x16x32_bf16 v[74:77], v[192:195], v[216:219], v[74:77]
	v_mfma_f32_16x16x32_bf16 v[70:73], v[184:187], v[224:227], v[70:73]
	v_mfma_f32_16x16x32_bf16 v[66:69], v[192:195], v[224:227], v[66:69]
	s_barrier
	s_add_i32 s20, s57, s46
	v_lshl_add_u64 v[228:229], s[38:39], 0, v[134:135]
	s_mov_b32 m0, s20
	ds_read_b128 v[196:199], v177 offset:16384
	ds_read_b128 v[200:203], v177 offset:17408
	ds_read_b128 v[204:207], v177 offset:18432
	ds_read_b128 v[208:211], v177 offset:19456
	ds_read_b128 v[212:215], v177 offset:20480
	ds_read_b128 v[216:219], v177 offset:21504
	ds_read_b128 v[220:223], v177 offset:22528
	ds_read_b128 v[224:227], v177 offset:23552
	global_load_lds_dwordx4 v[228:229], off
	s_add_i32 m0, s20, 0x2000
	s_add_u32 s20, s38, 0x20000
	v_lshl_add_u64 v[230:231], s[38:39], 0, v[130:131]
	s_addc_u32 s21, s39, 0
	s_add_i32 s27, s60, s46
	global_load_lds_dwordx4 v[230:231], off
	v_lshl_add_u64 v[232:233], s[20:21], 0, v[134:135]
	s_mov_b32 m0, s27
	v_lshl_add_u64 v[234:235], s[40:41], 0, v[132:133]
	global_load_lds_dwordx4 v[232:233], off
	v_lshl_add_u64 v[232:233], s[20:21], 0, v[130:131]
	s_add_i32 m0, s27, 0x2000
	s_nop 0
	global_load_lds_dwordx4 v[232:233], off
	v_lshl_add_u64 v[232:233], s[40:41], 0, v[136:137]
	s_mov_b32 m0, s49
	s_nop 0
	global_load_lds_dwordx4 v[232:233], off
	s_mov_b32 m0, s50
	s_nop 0
	global_load_lds_dwordx4 v[234:235], off
	s_waitcnt vmcnt(8)
	s_waitcnt lgkmcnt(0)
	v_mfma_f32_16x16x32_bf16 v[62:65], v[154:157], v[196:199], v[62:65]
	v_mfma_f32_16x16x32_bf16 v[58:61], v[164:167], v[196:199], v[58:61]
	v_mfma_f32_16x16x32_bf16 v[54:57], v[154:157], v[204:207], v[54:57]
	v_mfma_f32_16x16x32_bf16 v[46:49], v[164:167], v[204:207], v[46:49]
	s_barrier
	v_mfma_f32_16x16x32_bf16 v[38:41], v[154:157], v[212:215], v[38:41]
	v_mfma_f32_16x16x32_bf16 v[30:33], v[164:167], v[212:215], v[30:33]
	v_mfma_f32_16x16x32_bf16 v[22:25], v[154:157], v[220:223], v[22:25]
	v_mfma_f32_16x16x32_bf16 v[14:17], v[164:167], v[220:223], v[14:17]
	v_mfma_f32_16x16x32_bf16 v[62:65], v[158:161], v[200:203], v[62:65]
	v_mfma_f32_16x16x32_bf16 v[58:61], v[168:171], v[200:203], v[58:61]
	v_mfma_f32_16x16x32_bf16 v[54:57], v[158:161], v[208:211], v[54:57]
	v_mfma_f32_16x16x32_bf16 v[46:49], v[168:171], v[208:211], v[46:49]
	v_mfma_f32_16x16x32_bf16 v[38:41], v[158:161], v[216:219], v[38:41]
	v_mfma_f32_16x16x32_bf16 v[30:33], v[168:171], v[216:219], v[30:33]
	v_mfma_f32_16x16x32_bf16 v[22:25], v[158:161], v[224:227], v[22:25]
	v_mfma_f32_16x16x32_bf16 v[14:17], v[168:171], v[224:227], v[14:17]
	v_mfma_f32_16x16x32_bf16 v[50:53], v[180:183], v[196:199], v[50:53]
	v_mfma_f32_16x16x32_bf16 v[42:45], v[188:191], v[196:199], v[42:45]
	v_mfma_f32_16x16x32_bf16 v[34:37], v[180:183], v[204:207], v[34:37]
	v_mfma_f32_16x16x32_bf16 v[26:29], v[188:191], v[204:207], v[26:29]
	v_mfma_f32_16x16x32_bf16 v[18:21], v[180:183], v[212:215], v[18:21]
	v_mfma_f32_16x16x32_bf16 v[10:13], v[188:191], v[212:215], v[10:13]
	v_mfma_f32_16x16x32_bf16 v[6:9], v[180:183], v[220:223], v[6:9]
	v_mfma_f32_16x16x32_bf16 v[2:5], v[188:191], v[220:223], v[2:5]
	v_mfma_f32_16x16x32_bf16 v[50:53], v[184:187], v[200:203], v[50:53]
	v_mfma_f32_16x16x32_bf16 v[42:45], v[192:195], v[200:203], v[42:45]
	v_mfma_f32_16x16x32_bf16 v[34:37], v[184:187], v[208:211], v[34:37]
	v_mfma_f32_16x16x32_bf16 v[26:29], v[192:195], v[208:211], v[26:29]
	v_mfma_f32_16x16x32_bf16 v[18:21], v[184:187], v[216:219], v[18:21]
	v_mfma_f32_16x16x32_bf16 v[10:13], v[192:195], v[216:219], v[10:13]
	v_mfma_f32_16x16x32_bf16 v[6:9], v[184:187], v[224:227], v[6:9]
	v_mfma_f32_16x16x32_bf16 v[2:5], v[192:195], v[224:227], v[2:5]
	s_barrier
	s_add_i32 s27, 0, 0x18000
	v_add_u32_e32 v153, s27, v173
	s_add_i32 s29, 0, 0x1c000
	ds_read_b128 v[154:157], v153
	ds_read_b128 v[158:161], v153 offset:1024
	ds_read_b128 v[164:167], v153 offset:2048
	ds_read_b128 v[168:171], v153 offset:3072
	v_add_u32_e32 v153, s29, v173
	ds_read_b128 v[180:183], v153
	ds_read_b128 v[184:187], v153 offset:1024
	ds_read_b128 v[188:191], v153 offset:2048
	ds_read_b128 v[192:195], v153 offset:3072
	s_add_u32 s20, s40, 0x20000
	s_addc_u32 s21, s41, 0
	s_mov_b32 m0, s51
	v_lshl_add_u64 v[236:237], s[20:21], 0, v[136:137]
	ds_read_b128 v[196:199], v177 offset:32768
	ds_read_b128 v[200:203], v177 offset:33792
	ds_read_b128 v[204:207], v177 offset:34816
	ds_read_b128 v[208:211], v177 offset:35840
	ds_read_b128 v[212:215], v177 offset:36864
	ds_read_b128 v[216:219], v177 offset:37888
	ds_read_b128 v[220:223], v177 offset:38912
	ds_read_b128 v[224:227], v177 offset:39936
	global_load_lds_dwordx4 v[236:237], off
	v_lshl_add_u64 v[236:237], s[20:21], 0, v[132:133]
	s_mov_b32 m0, s52
	s_nop 0
	global_load_lds_dwordx4 v[236:237], off
	s_waitcnt vmcnt(8)
	s_waitcnt lgkmcnt(0)
	v_mfma_f32_16x16x32_bf16 v[126:129], v[154:157], v[196:199], v[126:129]
	v_mfma_f32_16x16x32_bf16 v[122:125], v[164:167], v[196:199], v[122:125]
	v_mfma_f32_16x16x32_bf16 v[118:121], v[154:157], v[204:207], v[118:121]
	v_mfma_f32_16x16x32_bf16 v[110:113], v[164:167], v[204:207], v[110:113]
	s_barrier
	v_mfma_f32_16x16x32_bf16 v[102:105], v[154:157], v[212:215], v[102:105]
	v_mfma_f32_16x16x32_bf16 v[94:97], v[164:167], v[212:215], v[94:97]
	v_mfma_f32_16x16x32_bf16 v[86:89], v[154:157], v[220:223], v[86:89]
	v_mfma_f32_16x16x32_bf16 v[78:81], v[164:167], v[220:223], v[78:81]
	v_mfma_f32_16x16x32_bf16 v[126:129], v[158:161], v[200:203], v[126:129]
	v_mfma_f32_16x16x32_bf16 v[122:125], v[168:171], v[200:203], v[122:125]
	v_mfma_f32_16x16x32_bf16 v[118:121], v[158:161], v[208:211], v[118:121]
	v_mfma_f32_16x16x32_bf16 v[110:113], v[168:171], v[208:211], v[110:113]
	v_mfma_f32_16x16x32_bf16 v[102:105], v[158:161], v[216:219], v[102:105]
	v_mfma_f32_16x16x32_bf16 v[94:97], v[168:171], v[216:219], v[94:97]
	v_mfma_f32_16x16x32_bf16 v[86:89], v[158:161], v[224:227], v[86:89]
	v_mfma_f32_16x16x32_bf16 v[78:81], v[168:171], v[224:227], v[78:81]
	v_mfma_f32_16x16x32_bf16 v[114:117], v[180:183], v[196:199], v[114:117]
	v_mfma_f32_16x16x32_bf16 v[106:109], v[188:191], v[196:199], v[106:109]
	v_mfma_f32_16x16x32_bf16 v[98:101], v[180:183], v[204:207], v[98:101]
	v_mfma_f32_16x16x32_bf16 v[90:93], v[188:191], v[204:207], v[90:93]
	v_mfma_f32_16x16x32_bf16 v[82:85], v[180:183], v[212:215], v[82:85]
	v_mfma_f32_16x16x32_bf16 v[74:77], v[188:191], v[212:215], v[74:77]
	v_mfma_f32_16x16x32_bf16 v[70:73], v[180:183], v[220:223], v[70:73]
	v_mfma_f32_16x16x32_bf16 v[66:69], v[188:191], v[220:223], v[66:69]
	v_mfma_f32_16x16x32_bf16 v[114:117], v[184:187], v[200:203], v[114:117]
	v_mfma_f32_16x16x32_bf16 v[106:109], v[192:195], v[200:203], v[106:109]
	v_mfma_f32_16x16x32_bf16 v[98:101], v[184:187], v[208:211], v[98:101]
	v_mfma_f32_16x16x32_bf16 v[90:93], v[192:195], v[208:211], v[90:93]
	v_mfma_f32_16x16x32_bf16 v[82:85], v[184:187], v[216:219], v[82:85]
	v_mfma_f32_16x16x32_bf16 v[74:77], v[192:195], v[216:219], v[74:77]
	v_mfma_f32_16x16x32_bf16 v[70:73], v[184:187], v[224:227], v[70:73]
	v_mfma_f32_16x16x32_bf16 v[66:69], v[192:195], v[224:227], v[66:69]
	s_barrier
	s_add_i32 s20, s27, s46
	v_lshl_add_u64 v[228:229], v[228:229], 0, s[22:23]
	s_mov_b32 m0, s20
	ds_read_b128 v[196:199], v177 offset:49152
	ds_read_b128 v[200:203], v177 offset:50176
	ds_read_b128 v[204:207], v177 offset:51200
	ds_read_b128 v[208:211], v177 offset:52224
	ds_read_b128 v[212:215], v177 offset:53248
	ds_read_b128 v[216:219], v177 offset:54272
	ds_read_b128 v[220:223], v177 offset:55296
	ds_read_b128 v[224:227], v177 offset:56320
	global_load_lds_dwordx4 v[228:229], off
	s_add_i32 m0, s20, 0x2000
	s_add_u32 s20, s38, 0x20080
	v_lshl_add_u64 v[228:229], v[230:231], 0, s[22:23]
	s_addc_u32 s21, s39, 0
	s_add_i32 s27, s29, s46
	global_load_lds_dwordx4 v[228:229], off
	v_lshl_add_u64 v[228:229], s[20:21], 0, v[134:135]
	s_mov_b32 m0, s27
	s_nop 0
	global_load_lds_dwordx4 v[228:229], off
	v_lshl_add_u64 v[228:229], s[20:21], 0, v[130:131]
	s_add_i32 m0, s27, 0x2000
	s_nop 0
	global_load_lds_dwordx4 v[228:229], off
	v_lshl_add_u64 v[228:229], v[232:233], 0, s[22:23]
	s_mov_b32 m0, s53
	s_nop 0
	global_load_lds_dwordx4 v[228:229], off
	v_lshl_add_u64 v[228:229], v[234:235], 0, s[22:23]
	s_mov_b32 m0, s54
	s_nop 0
	global_load_lds_dwordx4 v[228:229], off
	s_waitcnt vmcnt(8)
	s_waitcnt lgkmcnt(0)
	v_mfma_f32_16x16x32_bf16 v[62:65], v[154:157], v[196:199], v[62:65]
	v_mfma_f32_16x16x32_bf16 v[58:61], v[164:167], v[196:199], v[58:61]
	v_mfma_f32_16x16x32_bf16 v[54:57], v[154:157], v[204:207], v[54:57]
	v_mfma_f32_16x16x32_bf16 v[46:49], v[164:167], v[204:207], v[46:49]
	s_barrier
	v_mfma_f32_16x16x32_bf16 v[38:41], v[154:157], v[212:215], v[38:41]
	v_mfma_f32_16x16x32_bf16 v[30:33], v[164:167], v[212:215], v[30:33]
	v_mfma_f32_16x16x32_bf16 v[22:25], v[154:157], v[220:223], v[22:25]
	v_mfma_f32_16x16x32_bf16 v[14:17], v[164:167], v[220:223], v[14:17]
	v_mfma_f32_16x16x32_bf16 v[62:65], v[158:161], v[200:203], v[62:65]
	v_mfma_f32_16x16x32_bf16 v[58:61], v[168:171], v[200:203], v[58:61]
	v_mfma_f32_16x16x32_bf16 v[54:57], v[158:161], v[208:211], v[54:57]
	v_mfma_f32_16x16x32_bf16 v[46:49], v[168:171], v[208:211], v[46:49]
	v_mfma_f32_16x16x32_bf16 v[38:41], v[158:161], v[216:219], v[38:41]
	v_mfma_f32_16x16x32_bf16 v[30:33], v[168:171], v[216:219], v[30:33]
	v_mfma_f32_16x16x32_bf16 v[22:25], v[158:161], v[224:227], v[22:25]
	v_mfma_f32_16x16x32_bf16 v[14:17], v[168:171], v[224:227], v[14:17]
	v_mfma_f32_16x16x32_bf16 v[50:53], v[180:183], v[196:199], v[50:53]
	v_mfma_f32_16x16x32_bf16 v[42:45], v[188:191], v[196:199], v[42:45]
	v_mfma_f32_16x16x32_bf16 v[34:37], v[180:183], v[204:207], v[34:37]
	v_mfma_f32_16x16x32_bf16 v[26:29], v[188:191], v[204:207], v[26:29]
	v_mfma_f32_16x16x32_bf16 v[18:21], v[180:183], v[212:215], v[18:21]
	v_mfma_f32_16x16x32_bf16 v[10:13], v[188:191], v[212:215], v[10:13]
	v_mfma_f32_16x16x32_bf16 v[6:9], v[180:183], v[220:223], v[6:9]
	v_mfma_f32_16x16x32_bf16 v[2:5], v[188:191], v[220:223], v[2:5]
	v_mfma_f32_16x16x32_bf16 v[50:53], v[184:187], v[200:203], v[50:53]
	v_mfma_f32_16x16x32_bf16 v[42:45], v[192:195], v[200:203], v[42:45]
	v_mfma_f32_16x16x32_bf16 v[34:37], v[184:187], v[208:211], v[34:37]
	v_mfma_f32_16x16x32_bf16 v[26:29], v[192:195], v[208:211], v[26:29]
	v_mfma_f32_16x16x32_bf16 v[18:21], v[184:187], v[216:219], v[18:21]
	v_mfma_f32_16x16x32_bf16 v[10:13], v[192:195], v[216:219], v[10:13]
	v_mfma_f32_16x16x32_bf16 v[6:9], v[184:187], v[224:227], v[6:9]
	v_mfma_f32_16x16x32_bf16 v[2:5], v[192:195], v[224:227], v[2:5]
	s_barrier
	s_add_i32 s19, s19, 2
	s_add_u32 s36, s36, 0x100
	s_addc_u32 s37, s37, 0
	s_add_u32 s17, s17, 0x100
	s_addc_u32 s18, s18, 0
	s_cmp_gt_u32 s19, 5
	s_cbranch_scc0 .LBB0_1336
	s_and_b64 vcc, exec, s[24:25]
	s_cbranch_vccz .LBB0_1339
	s_barrier

.LBB0_1497:
	ds_read_b128 v[134:137], v214
	ds_read_b128 v[138:141], v214 offset:1024
	ds_read_b128 v[142:145], v214 offset:2048
	ds_read_b128 v[178:181], v214 offset:3072
	ds_read_b128 v[182:185], v215
	ds_read_b128 v[186:189], v215 offset:1024
	ds_read_b128 v[190:193], v215 offset:2048
	ds_read_b128 v[194:197], v215 offset:3072
	s_add_u32 s40, s38, 0x100
	s_addc_u32 s41, s39, 0
	s_add_u32 s0, s15, s38
	s_addc_u32 s1, s16, s39
	s_cmp_eq_u32 s17, 28
	s_cselect_b32 s45, s3, s1
	s_cselect_b32 s1, 0, s40
	s_cselect_b32 s44, s14, s0
	s_cselect_b32 s0, 0, s41
	s_add_u32 s42, s10, s1
	s_addc_u32 s43, s11, s0
	s_mov_b32 m0, s64
	v_lshl_add_u64 v[244:245], v[130:131], 0, s[38:39]
	ds_read_b128 v[198:201], v216
	ds_read_b128 v[202:205], v216 offset:1024
	ds_read_b128 v[206:209], v216 offset:2048
	ds_read_b128 v[224:227], v216 offset:3072
	ds_read_b128 v[228:231], v216 offset:4096
	ds_read_b128 v[232:235], v216 offset:5120
	ds_read_b128 v[236:239], v216 offset:6144
	ds_read_b128 v[240:243], v216 offset:7168
	global_load_lds_dwordx4 v[244:245], off
	v_lshl_add_u64 v[244:245], v[132:133], 0, s[38:39]
	s_mov_b32 m0, s65
	s_nop 0
	global_load_lds_dwordx4 v[244:245], off
	s_waitcnt vmcnt(8)
	s_waitcnt lgkmcnt(0)
	v_mfma_f32_16x16x32_bf16 v[82:85], v[134:137], v[198:201], v[82:85]
	v_mfma_f32_16x16x32_bf16 v[78:81], v[142:145], v[198:201], v[78:81]
	v_mfma_f32_16x16x32_bf16 v[110:113], v[134:137], v[206:209], v[110:113]
	v_mfma_f32_16x16x32_bf16 v[106:109], v[142:145], v[206:209], v[106:109]
	s_barrier
	v_mfma_f32_16x16x32_bf16 v[118:121], v[134:137], v[228:231], v[118:121]
	v_mfma_f32_16x16x32_bf16 v[114:117], v[142:145], v[228:231], v[114:117]
	v_mfma_f32_16x16x32_bf16 v[126:129], v[134:137], v[236:239], v[126:129]
	v_mfma_f32_16x16x32_bf16 v[122:125], v[142:145], v[236:239], v[122:125]
	v_mfma_f32_16x16x32_bf16 v[82:85], v[138:141], v[202:205], v[82:85]
	v_mfma_f32_16x16x32_bf16 v[78:81], v[178:181], v[202:205], v[78:81]
	v_mfma_f32_16x16x32_bf16 v[110:113], v[138:141], v[224:227], v[110:113]
	v_mfma_f32_16x16x32_bf16 v[106:109], v[178:181], v[224:227], v[106:109]
	v_mfma_f32_16x16x32_bf16 v[118:121], v[138:141], v[232:235], v[118:121]
	v_mfma_f32_16x16x32_bf16 v[114:117], v[178:181], v[232:235], v[114:117]
	v_mfma_f32_16x16x32_bf16 v[126:129], v[138:141], v[240:243], v[126:129]
	v_mfma_f32_16x16x32_bf16 v[122:125], v[178:181], v[240:243], v[122:125]
	v_mfma_f32_16x16x32_bf16 v[22:25], v[182:185], v[198:201], v[22:25]
	v_mfma_f32_16x16x32_bf16 v[26:29], v[190:193], v[198:201], v[26:29]
	v_mfma_f32_16x16x32_bf16 v[42:45], v[182:185], v[206:209], v[42:45]
	v_mfma_f32_16x16x32_bf16 v[46:49], v[190:193], v[206:209], v[46:49]
	v_mfma_f32_16x16x32_bf16 v[62:65], v[182:185], v[228:231], v[62:65]
	v_mfma_f32_16x16x32_bf16 v[70:73], v[190:193], v[228:231], v[70:73]
	v_mfma_f32_16x16x32_bf16 v[90:93], v[182:185], v[236:239], v[90:93]
	v_mfma_f32_16x16x32_bf16 v[94:97], v[190:193], v[236:239], v[94:97]
	v_mfma_f32_16x16x32_bf16 v[22:25], v[186:189], v[202:205], v[22:25]
	v_mfma_f32_16x16x32_bf16 v[26:29], v[194:197], v[202:205], v[26:29]
	v_mfma_f32_16x16x32_bf16 v[42:45], v[186:189], v[224:227], v[42:45]
	v_mfma_f32_16x16x32_bf16 v[46:49], v[194:197], v[224:227], v[46:49]
	v_mfma_f32_16x16x32_bf16 v[62:65], v[186:189], v[232:235], v[62:65]
	v_mfma_f32_16x16x32_bf16 v[70:73], v[194:197], v[232:235], v[70:73]
	v_mfma_f32_16x16x32_bf16 v[90:93], v[186:189], v[240:243], v[90:93]
	v_mfma_f32_16x16x32_bf16 v[94:97], v[194:197], v[240:243], v[94:97]
	s_barrier
	s_mov_b32 m0, s66
	v_lshl_add_u64 v[244:245], s[42:43], 0, v[150:151]
	s_add_u32 s18, s42, 0x80000
	ds_read_b128 v[198:201], v216 offset:16384
	ds_read_b128 v[202:205], v216 offset:17408
	ds_read_b128 v[206:209], v216 offset:18432
	ds_read_b128 v[224:227], v216 offset:19456
	ds_read_b128 v[228:231], v216 offset:20480
	ds_read_b128 v[232:235], v216 offset:21504
	ds_read_b128 v[236:239], v216 offset:22528
	ds_read_b128 v[240:243], v216 offset:23552
	global_load_lds_dwordx4 v[244:245], off
	v_lshl_add_u64 v[246:247], s[42:43], 0, v[146:147]
	s_mov_b32 m0, s67
	s_addc_u32 s19, s43, 0
	global_load_lds_dwordx4 v[246:247], off
	v_lshl_add_u64 v[248:249], s[18:19], 0, v[150:151]
	s_mov_b32 m0, s68
	v_lshl_add_u64 v[250:251], s[44:45], 0, v[148:149]
	global_load_lds_dwordx4 v[248:249], off
	v_lshl_add_u64 v[248:249], s[18:19], 0, v[146:147]
	s_mov_b32 m0, s69
	s_nop 0
	global_load_lds_dwordx4 v[248:249], off
	v_lshl_add_u64 v[248:249], s[44:45], 0, v[152:153]
	s_mov_b32 m0, s9
	s_nop 0
	global_load_lds_dwordx4 v[248:249], off
	s_mov_b32 m0, s55
	s_nop 0
	global_load_lds_dwordx4 v[250:251], off
	s_waitcnt vmcnt(8)
	s_waitcnt lgkmcnt(0)
	v_mfma_f32_16x16x32_bf16 v[102:105], v[134:137], v[198:201], v[102:105]
	v_mfma_f32_16x16x32_bf16 v[98:101], v[142:145], v[198:201], v[98:101]
	v_mfma_f32_16x16x32_bf16 v[66:69], v[134:137], v[206:209], v[66:69]
	v_mfma_f32_16x16x32_bf16 v[58:61], v[142:145], v[206:209], v[58:61]
	s_barrier
	v_mfma_f32_16x16x32_bf16 v[38:41], v[134:137], v[228:231], v[38:41]
	v_mfma_f32_16x16x32_bf16 v[34:37], v[142:145], v[228:231], v[34:37]
	v_mfma_f32_16x16x32_bf16 v[14:17], v[134:137], v[236:239], v[14:17]
	v_mfma_f32_16x16x32_bf16 v[10:13], v[142:145], v[236:239], v[10:13]
	v_mfma_f32_16x16x32_bf16 v[102:105], v[138:141], v[202:205], v[102:105]
	v_mfma_f32_16x16x32_bf16 v[98:101], v[178:181], v[202:205], v[98:101]
	v_mfma_f32_16x16x32_bf16 v[66:69], v[138:141], v[224:227], v[66:69]
	v_mfma_f32_16x16x32_bf16 v[58:61], v[178:181], v[224:227], v[58:61]
	v_mfma_f32_16x16x32_bf16 v[38:41], v[138:141], v[232:235], v[38:41]
	v_mfma_f32_16x16x32_bf16 v[34:37], v[178:181], v[232:235], v[34:37]
	v_mfma_f32_16x16x32_bf16 v[14:17], v[138:141], v[240:243], v[14:17]
	v_mfma_f32_16x16x32_bf16 v[10:13], v[178:181], v[240:243], v[10:13]
	v_mfma_f32_16x16x32_bf16 v[86:89], v[182:185], v[198:201], v[86:89]
	v_mfma_f32_16x16x32_bf16 v[74:77], v[190:193], v[198:201], v[74:77]
	v_mfma_f32_16x16x32_bf16 v[54:57], v[182:185], v[206:209], v[54:57]
	v_mfma_f32_16x16x32_bf16 v[50:53], v[190:193], v[206:209], v[50:53]
	v_mfma_f32_16x16x32_bf16 v[30:33], v[182:185], v[228:231], v[30:33]
	v_mfma_f32_16x16x32_bf16 v[18:21], v[190:193], v[228:231], v[18:21]
	v_mfma_f32_16x16x32_bf16 v[6:9], v[182:185], v[236:239], v[6:9]
	v_mfma_f32_16x16x32_bf16 v[2:5], v[190:193], v[236:239], v[2:5]
	v_mfma_f32_16x16x32_bf16 v[86:89], v[186:189], v[202:205], v[86:89]
	v_mfma_f32_16x16x32_bf16 v[74:77], v[194:197], v[202:205], v[74:77]
	v_mfma_f32_16x16x32_bf16 v[54:57], v[186:189], v[224:227], v[54:57]
	v_mfma_f32_16x16x32_bf16 v[50:53], v[194:197], v[224:227], v[50:53]
	v_mfma_f32_16x16x32_bf16 v[30:33], v[186:189], v[232:235], v[30:33]
	v_mfma_f32_16x16x32_bf16 v[18:21], v[194:197], v[232:235], v[18:21]
	v_mfma_f32_16x16x32_bf16 v[6:9], v[186:189], v[240:243], v[6:9]
	v_mfma_f32_16x16x32_bf16 v[2:5], v[194:197], v[240:243], v[2:5]
	s_barrier
	s_add_i32 s0, 0, 0x1c000
	v_add_u32_e32 v194, s0, v212
	ds_read_b128 v[134:137], v220
	ds_read_b128 v[138:141], v220 offset:1024
	ds_read_b128 v[142:145], v220 offset:2048
	ds_read_b128 v[178:181], v220 offset:3072
	ds_read_b128 v[182:185], v194
	ds_read_b128 v[186:189], v194 offset:1024
	ds_read_b128 v[190:193], v194 offset:2048
	ds_read_b128 v[194:197], v194 offset:3072
	s_add_u32 s18, s44, 0x80000
	s_addc_u32 s19, s45, 0
	s_mov_b32 m0, s56
	v_lshl_add_u64 v[252:253], s[18:19], 0, v[152:153]
	ds_read_b128 v[198:201], v216 offset:32768
	ds_read_b128 v[202:205], v216 offset:33792
	ds_read_b128 v[206:209], v216 offset:34816
	ds_read_b128 v[224:227], v216 offset:35840
	ds_read_b128 v[228:231], v216 offset:36864
	ds_read_b128 v[232:235], v216 offset:37888
	ds_read_b128 v[236:239], v216 offset:38912
	ds_read_b128 v[240:243], v216 offset:39936
	global_load_lds_dwordx4 v[252:253], off
	v_lshl_add_u64 v[252:253], s[18:19], 0, v[148:149]
	s_mov_b32 m0, s57
	s_nop 0
	global_load_lds_dwordx4 v[252:253], off
	s_waitcnt vmcnt(8)
	s_waitcnt lgkmcnt(0)
	v_mfma_f32_16x16x32_bf16 v[82:85], v[134:137], v[198:201], v[82:85]
	v_mfma_f32_16x16x32_bf16 v[78:81], v[142:145], v[198:201], v[78:81]
	v_mfma_f32_16x16x32_bf16 v[110:113], v[134:137], v[206:209], v[110:113]
	v_mfma_f32_16x16x32_bf16 v[106:109], v[142:145], v[206:209], v[106:109]
	s_barrier
	v_mfma_f32_16x16x32_bf16 v[118:121], v[134:137], v[228:231], v[118:121]
	v_mfma_f32_16x16x32_bf16 v[114:117], v[142:145], v[228:231], v[114:117]
	v_mfma_f32_16x16x32_bf16 v[126:129], v[134:137], v[236:239], v[126:129]
	v_mfma_f32_16x16x32_bf16 v[122:125], v[142:145], v[236:239], v[122:125]
	v_mfma_f32_16x16x32_bf16 v[82:85], v[138:141], v[202:205], v[82:85]
	v_mfma_f32_16x16x32_bf16 v[78:81], v[178:181], v[202:205], v[78:81]
	v_mfma_f32_16x16x32_bf16 v[110:113], v[138:141], v[224:227], v[110:113]
	v_mfma_f32_16x16x32_bf16 v[106:109], v[178:181], v[224:227], v[106:109]
	v_mfma_f32_16x16x32_bf16 v[118:121], v[138:141], v[232:235], v[118:121]
	v_mfma_f32_16x16x32_bf16 v[114:117], v[178:181], v[232:235], v[114:117]
	v_mfma_f32_16x16x32_bf16 v[126:129], v[138:141], v[240:243], v[126:129]
	v_mfma_f32_16x16x32_bf16 v[122:125], v[178:181], v[240:243], v[122:125]
	v_mfma_f32_16x16x32_bf16 v[22:25], v[182:185], v[198:201], v[22:25]
	v_mfma_f32_16x16x32_bf16 v[26:29], v[190:193], v[198:201], v[26:29]
	v_mfma_f32_16x16x32_bf16 v[42:45], v[182:185], v[206:209], v[42:45]
	v_mfma_f32_16x16x32_bf16 v[46:49], v[190:193], v[206:209], v[46:49]
	v_mfma_f32_16x16x32_bf16 v[62:65], v[182:185], v[228:231], v[62:65]
	v_mfma_f32_16x16x32_bf16 v[70:73], v[190:193], v[228:231], v[70:73]
	v_mfma_f32_16x16x32_bf16 v[90:93], v[182:185], v[236:239], v[90:93]
	v_mfma_f32_16x16x32_bf16 v[94:97], v[190:193], v[236:239], v[94:97]
	v_mfma_f32_16x16x32_bf16 v[22:25], v[186:189], v[202:205], v[22:25]
	v_mfma_f32_16x16x32_bf16 v[26:29], v[194:197], v[202:205], v[26:29]
	v_mfma_f32_16x16x32_bf16 v[42:45], v[186:189], v[224:227], v[42:45]
	v_mfma_f32_16x16x32_bf16 v[46:49], v[194:197], v[224:227], v[46:49]
	v_mfma_f32_16x16x32_bf16 v[62:65], v[186:189], v[232:235], v[62:65]
	v_mfma_f32_16x16x32_bf16 v[70:73], v[194:197], v[232:235], v[70:73]
	v_mfma_f32_16x16x32_bf16 v[90:93], v[186:189], v[240:243], v[90:93]
	v_mfma_f32_16x16x32_bf16 v[94:97], v[194:197], v[240:243], v[94:97]
	s_barrier
	s_add_i32 s1, s72, s54
	v_lshl_add_u64 v[244:245], v[244:245], 0, s[26:27]
	s_mov_b32 m0, s1
	ds_read_b128 v[198:201], v216 offset:49152
	ds_read_b128 v[202:205], v216 offset:50176
	ds_read_b128 v[206:209], v216 offset:51200
	ds_read_b128 v[224:227], v216 offset:52224
	ds_read_b128 v[228:231], v216 offset:53248
	ds_read_b128 v[232:235], v216 offset:54272
	ds_read_b128 v[236:239], v216 offset:55296
	ds_read_b128 v[240:243], v216 offset:56320
	global_load_lds_dwordx4 v[244:245], off
	s_add_i32 m0, s1, 0x2000
	s_add_u32 s18, s42, 0x80080
	v_lshl_add_u64 v[244:245], v[246:247], 0, s[26:27]
	s_addc_u32 s19, s43, 0
	s_add_i32 s0, s0, s54
	global_load_lds_dwordx4 v[244:245], off
	v_lshl_add_u64 v[244:245], s[18:19], 0, v[150:151]
	s_mov_b32 m0, s0
	s_nop 0
	global_load_lds_dwordx4 v[244:245], off
	v_lshl_add_u64 v[244:245], s[18:19], 0, v[146:147]
	s_add_i32 m0, s0, 0x2000
	s_nop 0
	global_load_lds_dwordx4 v[244:245], off
	v_lshl_add_u64 v[244:245], v[248:249], 0, s[26:27]
	s_mov_b32 m0, s61
	s_nop 0
	global_load_lds_dwordx4 v[244:245], off
	v_lshl_add_u64 v[244:245], v[250:251], 0, s[26:27]
	s_mov_b32 m0, s62
	s_nop 0
	global_load_lds_dwordx4 v[244:245], off
	s_waitcnt vmcnt(8)
	s_waitcnt lgkmcnt(0)
	v_mfma_f32_16x16x32_bf16 v[102:105], v[134:137], v[198:201], v[102:105]
	v_mfma_f32_16x16x32_bf16 v[98:101], v[142:145], v[198:201], v[98:101]
	v_mfma_f32_16x16x32_bf16 v[66:69], v[134:137], v[206:209], v[66:69]
	v_mfma_f32_16x16x32_bf16 v[58:61], v[142:145], v[206:209], v[58:61]
	s_barrier
	v_mfma_f32_16x16x32_bf16 v[38:41], v[134:137], v[228:231], v[38:41]
	v_mfma_f32_16x16x32_bf16 v[34:37], v[142:145], v[228:231], v[34:37]
	v_mfma_f32_16x16x32_bf16 v[14:17], v[134:137], v[236:239], v[14:17]
	v_mfma_f32_16x16x32_bf16 v[10:13], v[142:145], v[236:239], v[10:13]
	v_mfma_f32_16x16x32_bf16 v[102:105], v[138:141], v[202:205], v[102:105]
	v_mfma_f32_16x16x32_bf16 v[98:101], v[178:181], v[202:205], v[98:101]
	v_mfma_f32_16x16x32_bf16 v[66:69], v[138:141], v[224:227], v[66:69]
	v_mfma_f32_16x16x32_bf16 v[58:61], v[178:181], v[224:227], v[58:61]
	v_mfma_f32_16x16x32_bf16 v[38:41], v[138:141], v[232:235], v[38:41]
	v_mfma_f32_16x16x32_bf16 v[34:37], v[178:181], v[232:235], v[34:37]
	v_mfma_f32_16x16x32_bf16 v[14:17], v[138:141], v[240:243], v[14:17]
	v_mfma_f32_16x16x32_bf16 v[10:13], v[178:181], v[240:243], v[10:13]
	v_mfma_f32_16x16x32_bf16 v[86:89], v[182:185], v[198:201], v[86:89]
	v_mfma_f32_16x16x32_bf16 v[74:77], v[190:193], v[198:201], v[74:77]
	v_mfma_f32_16x16x32_bf16 v[54:57], v[182:185], v[206:209], v[54:57]
	v_mfma_f32_16x16x32_bf16 v[50:53], v[190:193], v[206:209], v[50:53]
	v_mfma_f32_16x16x32_bf16 v[30:33], v[182:185], v[228:231], v[30:33]
	v_mfma_f32_16x16x32_bf16 v[18:21], v[190:193], v[228:231], v[18:21]
	v_mfma_f32_16x16x32_bf16 v[6:9], v[182:185], v[236:239], v[6:9]
	v_mfma_f32_16x16x32_bf16 v[2:5], v[190:193], v[236:239], v[2:5]
	v_mfma_f32_16x16x32_bf16 v[86:89], v[186:189], v[202:205], v[86:89]
	v_mfma_f32_16x16x32_bf16 v[74:77], v[194:197], v[202:205], v[74:77]
	v_mfma_f32_16x16x32_bf16 v[54:57], v[186:189], v[224:227], v[54:57]
	v_mfma_f32_16x16x32_bf16 v[50:53], v[194:197], v[224:227], v[50:53]
	v_mfma_f32_16x16x32_bf16 v[30:33], v[186:189], v[232:235], v[30:33]
	v_mfma_f32_16x16x32_bf16 v[18:21], v[194:197], v[232:235], v[18:21]
	v_mfma_f32_16x16x32_bf16 v[6:9], v[186:189], v[240:243], v[6:9]
	v_mfma_f32_16x16x32_bf16 v[2:5], v[194:197], v[240:243], v[2:5]
	s_barrier
	s_add_i32 s17, s17, 2
	s_cmp_gt_u32 s17, 29
	s_mov_b64 s[38:39], s[40:41]
	s_cbranch_scc0 .LBB0_1497
	s_and_b64 vcc, exec, s[28:29]
	s_cbranch_vccz .LBB0_1500
	s_barrier

.LBB0_1604:
	ds_read_b128 v[154:157], v151
	ds_read_b128 v[158:161], v151 offset:1024
	ds_read_b128 v[164:167], v151 offset:2048
	ds_read_b128 v[168:171], v151 offset:3072
	ds_read_b128 v[172:175], v152
	ds_read_b128 v[176:179], v152 offset:1024
	ds_read_b128 v[180:183], v152 offset:2048
	ds_read_b128 v[184:187], v152 offset:3072
	s_add_u32 s0, s34, 0xfff80080
	s_addc_u32 s1, s35, -1
	s_cmp_eq_u32 s53, 28
	s_cselect_b32 s39, s16, s1
	s_cselect_b32 s38, s17, s0
	s_cselect_b32 s37, s18, s25
	s_cselect_b32 s36, s19, s23
	v_lshl_add_u64 v[146:147], s[34:35], 0, v[138:139]
	s_add_i32 m0, s31, 0xc000
	ds_read_b128 v[188:191], v153
	ds_read_b128 v[192:195], v153 offset:1024
	ds_read_b128 v[196:199], v153 offset:2048
	ds_read_b128 v[200:203], v153 offset:3072
	ds_read_b128 v[204:207], v153 offset:4096
	ds_read_b128 v[208:211], v153 offset:5120
	ds_read_b128 v[212:215], v153 offset:6144
	ds_read_b128 v[216:219], v153 offset:7168
	global_load_lds_dwordx4 v[146:147], off
	v_lshl_add_u64 v[146:147], s[34:35], 0, v[140:141]
	s_add_i32 m0, s31, 0xe000
	s_nop 0
	global_load_lds_dwordx4 v[146:147], off
	s_waitcnt vmcnt(8)
	s_waitcnt lgkmcnt(0)
	v_mfma_f32_16x16x32_bf16 v[126:129], v[154:157], v[188:191], v[126:129]
	v_mfma_f32_16x16x32_bf16 v[122:125], v[164:167], v[188:191], v[122:125]
	v_mfma_f32_16x16x32_bf16 v[110:113], v[154:157], v[196:199], v[110:113]
	v_mfma_f32_16x16x32_bf16 v[106:109], v[164:167], v[196:199], v[106:109]
	s_barrier
	v_mfma_f32_16x16x32_bf16 v[94:97], v[154:157], v[204:207], v[94:97]
	v_mfma_f32_16x16x32_bf16 v[90:93], v[164:167], v[204:207], v[90:93]
	v_mfma_f32_16x16x32_bf16 v[78:81], v[154:157], v[212:215], v[78:81]
	v_mfma_f32_16x16x32_bf16 v[74:77], v[164:167], v[212:215], v[74:77]
	v_mfma_f32_16x16x32_bf16 v[126:129], v[158:161], v[192:195], v[126:129]
	v_mfma_f32_16x16x32_bf16 v[122:125], v[168:171], v[192:195], v[122:125]
	v_mfma_f32_16x16x32_bf16 v[110:113], v[158:161], v[200:203], v[110:113]
	v_mfma_f32_16x16x32_bf16 v[106:109], v[168:171], v[200:203], v[106:109]
	v_mfma_f32_16x16x32_bf16 v[94:97], v[158:161], v[208:211], v[94:97]
	v_mfma_f32_16x16x32_bf16 v[90:93], v[168:171], v[208:211], v[90:93]
	v_mfma_f32_16x16x32_bf16 v[78:81], v[158:161], v[216:219], v[78:81]
	v_mfma_f32_16x16x32_bf16 v[74:77], v[168:171], v[216:219], v[74:77]
	v_mfma_f32_16x16x32_bf16 v[118:121], v[172:175], v[188:191], v[118:121]
	v_mfma_f32_16x16x32_bf16 v[114:117], v[180:183], v[188:191], v[114:117]
	v_mfma_f32_16x16x32_bf16 v[102:105], v[172:175], v[196:199], v[102:105]
	v_mfma_f32_16x16x32_bf16 v[98:101], v[180:183], v[196:199], v[98:101]
	v_mfma_f32_16x16x32_bf16 v[86:89], v[172:175], v[204:207], v[86:89]
	v_mfma_f32_16x16x32_bf16 v[82:85], v[180:183], v[204:207], v[82:85]
	v_mfma_f32_16x16x32_bf16 v[70:73], v[172:175], v[212:215], v[70:73]
	v_mfma_f32_16x16x32_bf16 v[66:69], v[180:183], v[212:215], v[66:69]
	v_mfma_f32_16x16x32_bf16 v[118:121], v[176:179], v[192:195], v[118:121]
	v_mfma_f32_16x16x32_bf16 v[114:117], v[184:187], v[192:195], v[114:117]
	v_mfma_f32_16x16x32_bf16 v[102:105], v[176:179], v[200:203], v[102:105]
	v_mfma_f32_16x16x32_bf16 v[98:101], v[184:187], v[200:203], v[98:101]
	v_mfma_f32_16x16x32_bf16 v[86:89], v[176:179], v[208:211], v[86:89]
	v_mfma_f32_16x16x32_bf16 v[82:85], v[184:187], v[208:211], v[82:85]
	v_mfma_f32_16x16x32_bf16 v[70:73], v[176:179], v[216:219], v[70:73]
	v_mfma_f32_16x16x32_bf16 v[66:69], v[184:187], v[216:219], v[66:69]
	s_barrier
	s_add_i32 s0, s15, s44
	v_lshl_add_u64 v[146:147], s[36:37], 0, v[134:135]
	s_mov_b32 m0, s0
	ds_read_b128 v[188:191], v153 offset:16384
	ds_read_b128 v[192:195], v153 offset:17408
	ds_read_b128 v[196:199], v153 offset:18432
	ds_read_b128 v[200:203], v153 offset:19456
	ds_read_b128 v[204:207], v153 offset:20480
	ds_read_b128 v[208:211], v153 offset:21504
	ds_read_b128 v[212:215], v153 offset:22528
	ds_read_b128 v[216:219], v153 offset:23552
	global_load_lds_dwordx4 v[146:147], off
	s_add_i32 m0, s0, 0x2000
	s_add_u32 s54, s36, 0x80000
	v_lshl_add_u64 v[220:221], s[36:37], 0, v[130:131]
	s_addc_u32 s55, s37, 0
	s_add_i32 s0, s51, s44
	global_load_lds_dwordx4 v[220:221], off
	v_lshl_add_u64 v[222:223], s[54:55], 0, v[134:135]
	s_mov_b32 m0, s0
	v_lshl_add_u64 v[224:225], s[38:39], 0, v[132:133]
	global_load_lds_dwordx4 v[222:223], off
	v_lshl_add_u64 v[222:223], s[54:55], 0, v[130:131]
	s_add_i32 m0, s0, 0x2000
	s_nop 0
	global_load_lds_dwordx4 v[222:223], off
	v_lshl_add_u64 v[222:223], s[38:39], 0, v[136:137]
	s_mov_b32 m0, s31
	s_nop 0
	global_load_lds_dwordx4 v[222:223], off
	s_mov_b32 m0, s47
	s_nop 0
	global_load_lds_dwordx4 v[224:225], off
	s_waitcnt vmcnt(8)
	s_waitcnt lgkmcnt(0)
	v_mfma_f32_16x16x32_bf16 v[62:65], v[154:157], v[188:191], v[62:65]
	v_mfma_f32_16x16x32_bf16 v[58:61], v[164:167], v[188:191], v[58:61]
	v_mfma_f32_16x16x32_bf16 v[46:49], v[154:157], v[196:199], v[46:49]
	v_mfma_f32_16x16x32_bf16 v[42:45], v[164:167], v[196:199], v[42:45]
	s_barrier
	v_mfma_f32_16x16x32_bf16 v[30:33], v[154:157], v[204:207], v[30:33]
	v_mfma_f32_16x16x32_bf16 v[26:29], v[164:167], v[204:207], v[26:29]
	v_mfma_f32_16x16x32_bf16 v[14:17], v[154:157], v[212:215], v[14:17]
	v_mfma_f32_16x16x32_bf16 v[10:13], v[164:167], v[212:215], v[10:13]
	v_mfma_f32_16x16x32_bf16 v[62:65], v[158:161], v[192:195], v[62:65]
	v_mfma_f32_16x16x32_bf16 v[58:61], v[168:171], v[192:195], v[58:61]
	v_mfma_f32_16x16x32_bf16 v[46:49], v[158:161], v[200:203], v[46:49]
	v_mfma_f32_16x16x32_bf16 v[42:45], v[168:171], v[200:203], v[42:45]
	v_mfma_f32_16x16x32_bf16 v[30:33], v[158:161], v[208:211], v[30:33]
	v_mfma_f32_16x16x32_bf16 v[26:29], v[168:171], v[208:211], v[26:29]
	v_mfma_f32_16x16x32_bf16 v[14:17], v[158:161], v[216:219], v[14:17]
	v_mfma_f32_16x16x32_bf16 v[10:13], v[168:171], v[216:219], v[10:13]
	v_mfma_f32_16x16x32_bf16 v[54:57], v[172:175], v[188:191], v[54:57]
	v_mfma_f32_16x16x32_bf16 v[50:53], v[180:183], v[188:191], v[50:53]
	v_mfma_f32_16x16x32_bf16 v[38:41], v[172:175], v[196:199], v[38:41]
	v_mfma_f32_16x16x32_bf16 v[34:37], v[180:183], v[196:199], v[34:37]
	v_mfma_f32_16x16x32_bf16 v[22:25], v[172:175], v[204:207], v[22:25]
	v_mfma_f32_16x16x32_bf16 v[18:21], v[180:183], v[204:207], v[18:21]
	v_mfma_f32_16x16x32_bf16 v[6:9], v[172:175], v[212:215], v[6:9]
	v_mfma_f32_16x16x32_bf16 v[2:5], v[180:183], v[212:215], v[2:5]
	v_mfma_f32_16x16x32_bf16 v[54:57], v[176:179], v[192:195], v[54:57]
	v_mfma_f32_16x16x32_bf16 v[50:53], v[184:187], v[192:195], v[50:53]
	v_mfma_f32_16x16x32_bf16 v[38:41], v[176:179], v[200:203], v[38:41]
	v_mfma_f32_16x16x32_bf16 v[34:37], v[184:187], v[200:203], v[34:37]
	v_mfma_f32_16x16x32_bf16 v[22:25], v[176:179], v[208:211], v[22:25]
	v_mfma_f32_16x16x32_bf16 v[18:21], v[184:187], v[208:211], v[18:21]
	v_mfma_f32_16x16x32_bf16 v[6:9], v[176:179], v[216:219], v[6:9]
	v_mfma_f32_16x16x32_bf16 v[2:5], v[184:187], v[216:219], v[2:5]
	s_barrier
	s_add_i32 s0, 0, 0x18000
	v_add_u32_e32 v163, s0, v149
	s_add_i32 s1, 0, 0x1c000
	ds_read_b128 v[154:157], v163
	ds_read_b128 v[158:161], v163 offset:1024
	ds_read_b128 v[164:167], v163 offset:2048
	ds_read_b128 v[168:171], v163 offset:3072
	v_add_u32_e32 v163, s1, v149
	ds_read_b128 v[172:175], v163
	ds_read_b128 v[176:179], v163 offset:1024
	ds_read_b128 v[180:183], v163 offset:2048
	ds_read_b128 v[184:187], v163 offset:3072
	s_add_u32 s38, s38, 0x80000
	s_addc_u32 s39, s39, 0
	s_mov_b32 m0, s48
	v_lshl_add_u64 v[226:227], s[38:39], 0, v[136:137]
	ds_read_b128 v[188:191], v153 offset:32768
	ds_read_b128 v[192:195], v153 offset:33792
	ds_read_b128 v[196:199], v153 offset:34816
	ds_read_b128 v[200:203], v153 offset:35840
	ds_read_b128 v[204:207], v153 offset:36864
	ds_read_b128 v[208:211], v153 offset:37888
	ds_read_b128 v[212:215], v153 offset:38912
	ds_read_b128 v[216:219], v153 offset:39936
	global_load_lds_dwordx4 v[226:227], off
	v_lshl_add_u64 v[226:227], s[38:39], 0, v[132:133]
	s_mov_b32 m0, s49
	s_nop 0
	global_load_lds_dwordx4 v[226:227], off
	s_waitcnt vmcnt(8)
	s_waitcnt lgkmcnt(0)
	v_mfma_f32_16x16x32_bf16 v[126:129], v[154:157], v[188:191], v[126:129]
	v_mfma_f32_16x16x32_bf16 v[122:125], v[164:167], v[188:191], v[122:125]
	v_mfma_f32_16x16x32_bf16 v[110:113], v[154:157], v[196:199], v[110:113]
	v_mfma_f32_16x16x32_bf16 v[106:109], v[164:167], v[196:199], v[106:109]
	s_barrier
	v_mfma_f32_16x16x32_bf16 v[94:97], v[154:157], v[204:207], v[94:97]
	v_mfma_f32_16x16x32_bf16 v[90:93], v[164:167], v[204:207], v[90:93]
	v_mfma_f32_16x16x32_bf16 v[78:81], v[154:157], v[212:215], v[78:81]
	v_mfma_f32_16x16x32_bf16 v[74:77], v[164:167], v[212:215], v[74:77]
	v_mfma_f32_16x16x32_bf16 v[126:129], v[158:161], v[192:195], v[126:129]
	v_mfma_f32_16x16x32_bf16 v[122:125], v[168:171], v[192:195], v[122:125]
	v_mfma_f32_16x16x32_bf16 v[110:113], v[158:161], v[200:203], v[110:113]
	v_mfma_f32_16x16x32_bf16 v[106:109], v[168:171], v[200:203], v[106:109]
	v_mfma_f32_16x16x32_bf16 v[94:97], v[158:161], v[208:211], v[94:97]
	v_mfma_f32_16x16x32_bf16 v[90:93], v[168:171], v[208:211], v[90:93]
	v_mfma_f32_16x16x32_bf16 v[78:81], v[158:161], v[216:219], v[78:81]
	v_mfma_f32_16x16x32_bf16 v[74:77], v[168:171], v[216:219], v[74:77]
	v_mfma_f32_16x16x32_bf16 v[118:121], v[172:175], v[188:191], v[118:121]
	v_mfma_f32_16x16x32_bf16 v[114:117], v[180:183], v[188:191], v[114:117]
	v_mfma_f32_16x16x32_bf16 v[102:105], v[172:175], v[196:199], v[102:105]
	v_mfma_f32_16x16x32_bf16 v[98:101], v[180:183], v[196:199], v[98:101]
	v_mfma_f32_16x16x32_bf16 v[86:89], v[172:175], v[204:207], v[86:89]
	v_mfma_f32_16x16x32_bf16 v[82:85], v[180:183], v[204:207], v[82:85]
	v_mfma_f32_16x16x32_bf16 v[70:73], v[172:175], v[212:215], v[70:73]
	v_mfma_f32_16x16x32_bf16 v[66:69], v[180:183], v[212:215], v[66:69]
	v_mfma_f32_16x16x32_bf16 v[118:121], v[176:179], v[192:195], v[118:121]
	v_mfma_f32_16x16x32_bf16 v[114:117], v[184:187], v[192:195], v[114:117]
	v_mfma_f32_16x16x32_bf16 v[102:105], v[176:179], v[200:203], v[102:105]
	v_mfma_f32_16x16x32_bf16 v[98:101], v[184:187], v[200:203], v[98:101]
	v_mfma_f32_16x16x32_bf16 v[86:89], v[176:179], v[208:211], v[86:89]
	v_mfma_f32_16x16x32_bf16 v[82:85], v[184:187], v[208:211], v[82:85]
	v_mfma_f32_16x16x32_bf16 v[70:73], v[176:179], v[216:219], v[70:73]
	v_mfma_f32_16x16x32_bf16 v[66:69], v[184:187], v[216:219], v[66:69]
	s_barrier
	s_add_i32 s0, s0, s44
	v_lshl_add_u64 v[146:147], v[146:147], 0, s[10:11]
	s_mov_b32 m0, s0
	ds_read_b128 v[188:191], v153 offset:49152
	ds_read_b128 v[192:195], v153 offset:50176
	ds_read_b128 v[196:199], v153 offset:51200
	ds_read_b128 v[200:203], v153 offset:52224
	ds_read_b128 v[204:207], v153 offset:53248
	ds_read_b128 v[208:211], v153 offset:54272
	ds_read_b128 v[212:215], v153 offset:55296
	ds_read_b128 v[216:219], v153 offset:56320
	global_load_lds_dwordx4 v[146:147], off
	s_add_i32 m0, s0, 0x2000
	s_add_u32 s36, s36, 0x80080
	v_lshl_add_u64 v[146:147], v[220:221], 0, s[10:11]
	s_addc_u32 s37, s37, 0
	s_add_i32 s0, s1, s44
	global_load_lds_dwordx4 v[146:147], off
	v_lshl_add_u64 v[146:147], s[36:37], 0, v[134:135]
	s_mov_b32 m0, s0
	s_nop 0
	global_load_lds_dwordx4 v[146:147], off
	v_lshl_add_u64 v[146:147], s[36:37], 0, v[130:131]
	s_add_i32 m0, s0, 0x2000
	s_nop 0
	global_load_lds_dwordx4 v[146:147], off
	v_lshl_add_u64 v[146:147], v[222:223], 0, s[10:11]
	s_mov_b32 m0, s20
	s_nop 0
	global_load_lds_dwordx4 v[146:147], off
	v_lshl_add_u64 v[146:147], v[224:225], 0, s[10:11]
	s_mov_b32 m0, s21
	s_nop 0
	global_load_lds_dwordx4 v[146:147], off
	s_waitcnt vmcnt(8)
	s_waitcnt lgkmcnt(0)
	v_mfma_f32_16x16x32_bf16 v[62:65], v[154:157], v[188:191], v[62:65]
	v_mfma_f32_16x16x32_bf16 v[58:61], v[164:167], v[188:191], v[58:61]
	v_mfma_f32_16x16x32_bf16 v[46:49], v[154:157], v[196:199], v[46:49]
	v_mfma_f32_16x16x32_bf16 v[42:45], v[164:167], v[196:199], v[42:45]
	s_barrier
	v_mfma_f32_16x16x32_bf16 v[30:33], v[154:157], v[204:207], v[30:33]
	v_mfma_f32_16x16x32_bf16 v[26:29], v[164:167], v[204:207], v[26:29]
	v_mfma_f32_16x16x32_bf16 v[14:17], v[154:157], v[212:215], v[14:17]
	v_mfma_f32_16x16x32_bf16 v[10:13], v[164:167], v[212:215], v[10:13]
	v_mfma_f32_16x16x32_bf16 v[62:65], v[158:161], v[192:195], v[62:65]
	v_mfma_f32_16x16x32_bf16 v[58:61], v[168:171], v[192:195], v[58:61]
	v_mfma_f32_16x16x32_bf16 v[46:49], v[158:161], v[200:203], v[46:49]
	v_mfma_f32_16x16x32_bf16 v[42:45], v[168:171], v[200:203], v[42:45]
	v_mfma_f32_16x16x32_bf16 v[30:33], v[158:161], v[208:211], v[30:33]
	v_mfma_f32_16x16x32_bf16 v[26:29], v[168:171], v[208:211], v[26:29]
	v_mfma_f32_16x16x32_bf16 v[14:17], v[158:161], v[216:219], v[14:17]
	v_mfma_f32_16x16x32_bf16 v[10:13], v[168:171], v[216:219], v[10:13]
	v_mfma_f32_16x16x32_bf16 v[54:57], v[172:175], v[188:191], v[54:57]
	v_mfma_f32_16x16x32_bf16 v[50:53], v[180:183], v[188:191], v[50:53]
	v_mfma_f32_16x16x32_bf16 v[38:41], v[172:175], v[196:199], v[38:41]
	v_mfma_f32_16x16x32_bf16 v[34:37], v[180:183], v[196:199], v[34:37]
	v_mfma_f32_16x16x32_bf16 v[22:25], v[172:175], v[204:207], v[22:25]
	v_mfma_f32_16x16x32_bf16 v[18:21], v[180:183], v[204:207], v[18:21]
	v_mfma_f32_16x16x32_bf16 v[6:9], v[172:175], v[212:215], v[6:9]
	v_mfma_f32_16x16x32_bf16 v[2:5], v[180:183], v[212:215], v[2:5]
	v_mfma_f32_16x16x32_bf16 v[54:57], v[176:179], v[192:195], v[54:57]
	v_mfma_f32_16x16x32_bf16 v[50:53], v[184:187], v[192:195], v[50:53]
	v_mfma_f32_16x16x32_bf16 v[38:41], v[176:179], v[200:203], v[38:41]
	v_mfma_f32_16x16x32_bf16 v[34:37], v[184:187], v[200:203], v[34:37]
	v_mfma_f32_16x16x32_bf16 v[22:25], v[176:179], v[208:211], v[22:25]
	v_mfma_f32_16x16x32_bf16 v[18:21], v[184:187], v[208:211], v[18:21]
	v_mfma_f32_16x16x32_bf16 v[6:9], v[176:179], v[216:219], v[6:9]
	v_mfma_f32_16x16x32_bf16 v[2:5], v[184:187], v[216:219], v[2:5]
	s_barrier
	s_add_i32 s53, s53, 2
	s_add_u32 s34, s34, 0x100
	s_addc_u32 s35, s35, 0
	s_add_u32 s23, s23, 0x100
	s_addc_u32 s25, s25, 0
	s_cmp_gt_u32 s53, 29
	s_cbranch_scc0 .LBB0_1604
	s_and_b64 vcc, exec, s[12:13]
	s_cbranch_vccz .LBB0_1607
	s_barrier

.LBB0_1675:
	ds_read_b128 v[156:159], v191
	ds_read_b128 v[160:163], v191 offset:1024
	ds_read_b128 v[164:167], v191 offset:2048
	ds_read_b128 v[168:171], v191 offset:3072
	ds_read_b128 v[172:175], v192
	ds_read_b128 v[176:179], v192 offset:1024
	ds_read_b128 v[180:183], v192 offset:2048
	ds_read_b128 v[184:187], v192 offset:3072
	s_add_u32 s36, s30, 0xffea0080
	s_addc_u32 s37, s31, -1
	s_cmpk_eq_i32 s29, 0x54
	s_cselect_b32 s39, s25, s37
	s_cselect_b32 s38, s24, s36
	s_cselect_b32 s37, s5, s35
	s_cselect_b32 s36, s4, s34
	s_mov_b32 m0, s57
	v_lshl_add_u64 v[234:235], s[30:31], 0, v[150:151]
	ds_read_b128 v[202:205], v193
	ds_read_b128 v[206:209], v193 offset:1024
	ds_read_b128 v[210:213], v193 offset:2048
	ds_read_b128 v[214:217], v193 offset:3072
	ds_read_b128 v[218:221], v193 offset:4096
	ds_read_b128 v[222:225], v193 offset:5120
	ds_read_b128 v[226:229], v193 offset:6144
	ds_read_b128 v[230:233], v193 offset:7168
	global_load_lds_dwordx4 v[234:235], off
	v_lshl_add_u64 v[234:235], s[30:31], 0, v[152:153]
	s_mov_b32 m0, s58
	s_nop 0
	global_load_lds_dwordx4 v[234:235], off
	s_waitcnt vmcnt(8)
	s_waitcnt lgkmcnt(0)
	v_mfma_f32_16x16x32_bf16 v[126:129], v[156:159], v[202:205], v[126:129]
	v_mfma_f32_16x16x32_bf16 v[122:125], v[164:167], v[202:205], v[122:125]
	v_mfma_f32_16x16x32_bf16 v[110:113], v[156:159], v[210:213], v[110:113]
	v_mfma_f32_16x16x32_bf16 v[106:109], v[164:167], v[210:213], v[106:109]
	s_barrier
	v_mfma_f32_16x16x32_bf16 v[94:97], v[156:159], v[218:221], v[94:97]
	v_mfma_f32_16x16x32_bf16 v[90:93], v[164:167], v[218:221], v[90:93]
	v_mfma_f32_16x16x32_bf16 v[78:81], v[156:159], v[226:229], v[78:81]
	v_mfma_f32_16x16x32_bf16 v[74:77], v[164:167], v[226:229], v[74:77]
	v_mfma_f32_16x16x32_bf16 v[126:129], v[160:163], v[206:209], v[126:129]
	v_mfma_f32_16x16x32_bf16 v[122:125], v[168:171], v[206:209], v[122:125]
	v_mfma_f32_16x16x32_bf16 v[110:113], v[160:163], v[214:217], v[110:113]
	v_mfma_f32_16x16x32_bf16 v[106:109], v[168:171], v[214:217], v[106:109]
	v_mfma_f32_16x16x32_bf16 v[94:97], v[160:163], v[222:225], v[94:97]
	v_mfma_f32_16x16x32_bf16 v[90:93], v[168:171], v[222:225], v[90:93]
	v_mfma_f32_16x16x32_bf16 v[78:81], v[160:163], v[230:233], v[78:81]
	v_mfma_f32_16x16x32_bf16 v[74:77], v[168:171], v[230:233], v[74:77]
	v_mfma_f32_16x16x32_bf16 v[118:121], v[172:175], v[202:205], v[118:121]
	v_mfma_f32_16x16x32_bf16 v[114:117], v[180:183], v[202:205], v[114:117]
	v_mfma_f32_16x16x32_bf16 v[102:105], v[172:175], v[210:213], v[102:105]
	v_mfma_f32_16x16x32_bf16 v[98:101], v[180:183], v[210:213], v[98:101]
	v_mfma_f32_16x16x32_bf16 v[86:89], v[172:175], v[218:221], v[86:89]
	v_mfma_f32_16x16x32_bf16 v[82:85], v[180:183], v[218:221], v[82:85]
	v_mfma_f32_16x16x32_bf16 v[70:73], v[172:175], v[226:229], v[70:73]
	v_mfma_f32_16x16x32_bf16 v[66:69], v[180:183], v[226:229], v[66:69]
	v_mfma_f32_16x16x32_bf16 v[118:121], v[176:179], v[206:209], v[118:121]
	v_mfma_f32_16x16x32_bf16 v[114:117], v[184:187], v[206:209], v[114:117]
	v_mfma_f32_16x16x32_bf16 v[102:105], v[176:179], v[214:217], v[102:105]
	v_mfma_f32_16x16x32_bf16 v[98:101], v[184:187], v[214:217], v[98:101]
	v_mfma_f32_16x16x32_bf16 v[86:89], v[176:179], v[222:225], v[86:89]
	v_mfma_f32_16x16x32_bf16 v[82:85], v[184:187], v[222:225], v[82:85]
	v_mfma_f32_16x16x32_bf16 v[70:73], v[176:179], v[230:233], v[70:73]
	v_mfma_f32_16x16x32_bf16 v[66:69], v[184:187], v[230:233], v[66:69]
	s_barrier
	s_mov_b32 m0, s59
	v_lshl_add_u64 v[234:235], s[36:37], 0, v[134:135]
	s_add_u32 s40, s36, 0x160000
	ds_read_b128 v[202:205], v193 offset:16384
	ds_read_b128 v[206:209], v193 offset:17408
	ds_read_b128 v[210:213], v193 offset:18432
	ds_read_b128 v[214:217], v193 offset:19456
	ds_read_b128 v[218:221], v193 offset:20480
	ds_read_b128 v[222:225], v193 offset:21504
	ds_read_b128 v[226:229], v193 offset:22528
	ds_read_b128 v[230:233], v193 offset:23552
	global_load_lds_dwordx4 v[234:235], off
	v_lshl_add_u64 v[236:237], s[36:37], 0, v[130:131]
	s_mov_b32 m0, s60
	s_addc_u32 s41, s37, 0
	global_load_lds_dwordx4 v[236:237], off
	v_lshl_add_u64 v[238:239], s[40:41], 0, v[134:135]
	s_mov_b32 m0, s61
	v_lshl_add_u64 v[240:241], s[38:39], 0, v[132:133]
	global_load_lds_dwordx4 v[238:239], off
	v_lshl_add_u64 v[238:239], s[40:41], 0, v[130:131]
	s_mov_b32 m0, s62
	s_nop 0
	global_load_lds_dwordx4 v[238:239], off
	v_lshl_add_u64 v[238:239], s[38:39], 0, v[136:137]
	s_mov_b32 m0, s48
	s_nop 0
	global_load_lds_dwordx4 v[238:239], off
	s_mov_b32 m0, s49
	s_nop 0
	global_load_lds_dwordx4 v[240:241], off
	s_waitcnt vmcnt(8)
	s_waitcnt lgkmcnt(0)
	v_mfma_f32_16x16x32_bf16 v[62:65], v[156:159], v[202:205], v[62:65]
	v_mfma_f32_16x16x32_bf16 v[58:61], v[164:167], v[202:205], v[58:61]
	v_mfma_f32_16x16x32_bf16 v[46:49], v[156:159], v[210:213], v[46:49]
	v_mfma_f32_16x16x32_bf16 v[42:45], v[164:167], v[210:213], v[42:45]
	s_barrier
	v_mfma_f32_16x16x32_bf16 v[30:33], v[156:159], v[218:221], v[30:33]
	v_mfma_f32_16x16x32_bf16 v[26:29], v[164:167], v[218:221], v[26:29]
	v_mfma_f32_16x16x32_bf16 v[14:17], v[156:159], v[226:229], v[14:17]
	v_mfma_f32_16x16x32_bf16 v[10:13], v[164:167], v[226:229], v[10:13]
	v_mfma_f32_16x16x32_bf16 v[62:65], v[160:163], v[206:209], v[62:65]
	v_mfma_f32_16x16x32_bf16 v[58:61], v[168:171], v[206:209], v[58:61]
	v_mfma_f32_16x16x32_bf16 v[46:49], v[160:163], v[214:217], v[46:49]
	v_mfma_f32_16x16x32_bf16 v[42:45], v[168:171], v[214:217], v[42:45]
	v_mfma_f32_16x16x32_bf16 v[30:33], v[160:163], v[222:225], v[30:33]
	v_mfma_f32_16x16x32_bf16 v[26:29], v[168:171], v[222:225], v[26:29]
	v_mfma_f32_16x16x32_bf16 v[14:17], v[160:163], v[230:233], v[14:17]
	v_mfma_f32_16x16x32_bf16 v[10:13], v[168:171], v[230:233], v[10:13]
	v_mfma_f32_16x16x32_bf16 v[54:57], v[172:175], v[202:205], v[54:57]
	v_mfma_f32_16x16x32_bf16 v[50:53], v[180:183], v[202:205], v[50:53]
	v_mfma_f32_16x16x32_bf16 v[38:41], v[172:175], v[210:213], v[38:41]
	v_mfma_f32_16x16x32_bf16 v[34:37], v[180:183], v[210:213], v[34:37]
	v_mfma_f32_16x16x32_bf16 v[22:25], v[172:175], v[218:221], v[22:25]
	v_mfma_f32_16x16x32_bf16 v[18:21], v[180:183], v[218:221], v[18:21]
	v_mfma_f32_16x16x32_bf16 v[6:9], v[172:175], v[226:229], v[6:9]
	v_mfma_f32_16x16x32_bf16 v[2:5], v[180:183], v[226:229], v[2:5]
	v_mfma_f32_16x16x32_bf16 v[54:57], v[176:179], v[206:209], v[54:57]
	v_mfma_f32_16x16x32_bf16 v[50:53], v[184:187], v[206:209], v[50:53]
	v_mfma_f32_16x16x32_bf16 v[38:41], v[176:179], v[214:217], v[38:41]
	v_mfma_f32_16x16x32_bf16 v[34:37], v[184:187], v[214:217], v[34:37]
	v_mfma_f32_16x16x32_bf16 v[22:25], v[176:179], v[222:225], v[22:25]
	v_mfma_f32_16x16x32_bf16 v[18:21], v[184:187], v[222:225], v[18:21]
	v_mfma_f32_16x16x32_bf16 v[6:9], v[176:179], v[230:233], v[6:9]
	v_mfma_f32_16x16x32_bf16 v[2:5], v[184:187], v[230:233], v[2:5]
	s_barrier
	ds_read_b128 v[156:159], v197
	ds_read_b128 v[160:163], v197 offset:1024
	ds_read_b128 v[164:167], v197 offset:2048
	ds_read_b128 v[168:171], v197 offset:3072
	ds_read_b128 v[172:175], v198
	ds_read_b128 v[176:179], v198 offset:1024
	ds_read_b128 v[180:183], v198 offset:2048
	ds_read_b128 v[184:187], v198 offset:3072
	s_add_u32 s38, s38, 0x160000
	s_addc_u32 s39, s39, 0
	s_mov_b32 m0, s50
	v_lshl_add_u64 v[242:243], s[38:39], 0, v[136:137]
	ds_read_b128 v[202:205], v193 offset:32768
	ds_read_b128 v[206:209], v193 offset:33792
	ds_read_b128 v[210:213], v193 offset:34816
	ds_read_b128 v[214:217], v193 offset:35840
	ds_read_b128 v[218:221], v193 offset:36864
	ds_read_b128 v[222:225], v193 offset:37888
	ds_read_b128 v[226:229], v193 offset:38912
	ds_read_b128 v[230:233], v193 offset:39936
	global_load_lds_dwordx4 v[242:243], off
	v_lshl_add_u64 v[242:243], s[38:39], 0, v[132:133]
	s_mov_b32 m0, s51
	s_nop 0
	global_load_lds_dwordx4 v[242:243], off
	s_waitcnt vmcnt(8)
	s_waitcnt lgkmcnt(0)
	v_mfma_f32_16x16x32_bf16 v[126:129], v[156:159], v[202:205], v[126:129]
	v_mfma_f32_16x16x32_bf16 v[122:125], v[164:167], v[202:205], v[122:125]
	v_mfma_f32_16x16x32_bf16 v[110:113], v[156:159], v[210:213], v[110:113]
	v_mfma_f32_16x16x32_bf16 v[106:109], v[164:167], v[210:213], v[106:109]
	s_barrier
	v_mfma_f32_16x16x32_bf16 v[94:97], v[156:159], v[218:221], v[94:97]
	v_mfma_f32_16x16x32_bf16 v[90:93], v[164:167], v[218:221], v[90:93]
	v_mfma_f32_16x16x32_bf16 v[78:81], v[156:159], v[226:229], v[78:81]
	v_mfma_f32_16x16x32_bf16 v[74:77], v[164:167], v[226:229], v[74:77]
	v_mfma_f32_16x16x32_bf16 v[126:129], v[160:163], v[206:209], v[126:129]
	v_mfma_f32_16x16x32_bf16 v[122:125], v[168:171], v[206:209], v[122:125]
	v_mfma_f32_16x16x32_bf16 v[110:113], v[160:163], v[214:217], v[110:113]
	v_mfma_f32_16x16x32_bf16 v[106:109], v[168:171], v[214:217], v[106:109]
	v_mfma_f32_16x16x32_bf16 v[94:97], v[160:163], v[222:225], v[94:97]
	v_mfma_f32_16x16x32_bf16 v[90:93], v[168:171], v[222:225], v[90:93]
	v_mfma_f32_16x16x32_bf16 v[78:81], v[160:163], v[230:233], v[78:81]
	v_mfma_f32_16x16x32_bf16 v[74:77], v[168:171], v[230:233], v[74:77]
	v_mfma_f32_16x16x32_bf16 v[118:121], v[172:175], v[202:205], v[118:121]
	v_mfma_f32_16x16x32_bf16 v[114:117], v[180:183], v[202:205], v[114:117]
	v_mfma_f32_16x16x32_bf16 v[102:105], v[172:175], v[210:213], v[102:105]
	v_mfma_f32_16x16x32_bf16 v[98:101], v[180:183], v[210:213], v[98:101]
	v_mfma_f32_16x16x32_bf16 v[86:89], v[172:175], v[218:221], v[86:89]
	v_mfma_f32_16x16x32_bf16 v[82:85], v[180:183], v[218:221], v[82:85]
	v_mfma_f32_16x16x32_bf16 v[70:73], v[172:175], v[226:229], v[70:73]
	v_mfma_f32_16x16x32_bf16 v[66:69], v[180:183], v[226:229], v[66:69]
	v_mfma_f32_16x16x32_bf16 v[118:121], v[176:179], v[206:209], v[118:121]
	v_mfma_f32_16x16x32_bf16 v[114:117], v[184:187], v[206:209], v[114:117]
	v_mfma_f32_16x16x32_bf16 v[102:105], v[176:179], v[214:217], v[102:105]
	v_mfma_f32_16x16x32_bf16 v[98:101], v[184:187], v[214:217], v[98:101]
	v_mfma_f32_16x16x32_bf16 v[86:89], v[176:179], v[222:225], v[86:89]
	v_mfma_f32_16x16x32_bf16 v[82:85], v[184:187], v[222:225], v[82:85]
	v_mfma_f32_16x16x32_bf16 v[70:73], v[176:179], v[230:233], v[70:73]
	v_mfma_f32_16x16x32_bf16 v[66:69], v[184:187], v[230:233], v[66:69]
	s_barrier
	s_mov_b32 m0, s64
	v_lshl_add_u64 v[234:235], v[234:235], 0, s[12:13]
	s_add_u32 s36, s36, 0x160080
	ds_read_b128 v[202:205], v193 offset:49152
	ds_read_b128 v[206:209], v193 offset:50176
	ds_read_b128 v[210:213], v193 offset:51200
	ds_read_b128 v[214:217], v193 offset:52224
	ds_read_b128 v[218:221], v193 offset:53248
	ds_read_b128 v[222:225], v193 offset:54272
	ds_read_b128 v[226:229], v193 offset:55296
	ds_read_b128 v[230:233], v193 offset:56320
	global_load_lds_dwordx4 v[234:235], off
	v_lshl_add_u64 v[234:235], v[236:237], 0, s[12:13]
	s_mov_b32 m0, s65
	s_addc_u32 s37, s37, 0
	s_add_i32 s38, s63, s47
	global_load_lds_dwordx4 v[234:235], off
	v_lshl_add_u64 v[234:235], s[36:37], 0, v[134:135]
	s_mov_b32 m0, s38
	s_nop 0
	global_load_lds_dwordx4 v[234:235], off
	v_lshl_add_u64 v[234:235], s[36:37], 0, v[130:131]
	s_add_i32 m0, s38, 0x2000
	s_nop 0
	global_load_lds_dwordx4 v[234:235], off
	v_lshl_add_u64 v[234:235], v[238:239], 0, s[12:13]
	s_mov_b32 m0, s55
	s_nop 0
	global_load_lds_dwordx4 v[234:235], off
	v_lshl_add_u64 v[234:235], v[240:241], 0, s[12:13]
	s_mov_b32 m0, s56
	s_nop 0
	global_load_lds_dwordx4 v[234:235], off
	s_waitcnt vmcnt(8)
	s_waitcnt lgkmcnt(0)
	v_mfma_f32_16x16x32_bf16 v[62:65], v[156:159], v[202:205], v[62:65]
	v_mfma_f32_16x16x32_bf16 v[58:61], v[164:167], v[202:205], v[58:61]
	v_mfma_f32_16x16x32_bf16 v[46:49], v[156:159], v[210:213], v[46:49]
	v_mfma_f32_16x16x32_bf16 v[42:45], v[164:167], v[210:213], v[42:45]
	s_barrier
	v_mfma_f32_16x16x32_bf16 v[30:33], v[156:159], v[218:221], v[30:33]
	v_mfma_f32_16x16x32_bf16 v[26:29], v[164:167], v[218:221], v[26:29]
	v_mfma_f32_16x16x32_bf16 v[14:17], v[156:159], v[226:229], v[14:17]
	v_mfma_f32_16x16x32_bf16 v[10:13], v[164:167], v[226:229], v[10:13]
	v_mfma_f32_16x16x32_bf16 v[62:65], v[160:163], v[206:209], v[62:65]
	v_mfma_f32_16x16x32_bf16 v[58:61], v[168:171], v[206:209], v[58:61]
	v_mfma_f32_16x16x32_bf16 v[46:49], v[160:163], v[214:217], v[46:49]
	v_mfma_f32_16x16x32_bf16 v[42:45], v[168:171], v[214:217], v[42:45]
	v_mfma_f32_16x16x32_bf16 v[30:33], v[160:163], v[222:225], v[30:33]
	v_mfma_f32_16x16x32_bf16 v[26:29], v[168:171], v[222:225], v[26:29]
	v_mfma_f32_16x16x32_bf16 v[14:17], v[160:163], v[230:233], v[14:17]
	v_mfma_f32_16x16x32_bf16 v[10:13], v[168:171], v[230:233], v[10:13]
	v_mfma_f32_16x16x32_bf16 v[54:57], v[172:175], v[202:205], v[54:57]
	v_mfma_f32_16x16x32_bf16 v[50:53], v[180:183], v[202:205], v[50:53]
	v_mfma_f32_16x16x32_bf16 v[38:41], v[172:175], v[210:213], v[38:41]
	v_mfma_f32_16x16x32_bf16 v[34:37], v[180:183], v[210:213], v[34:37]
	v_mfma_f32_16x16x32_bf16 v[22:25], v[172:175], v[218:221], v[22:25]
	v_mfma_f32_16x16x32_bf16 v[18:21], v[180:183], v[218:221], v[18:21]
	v_mfma_f32_16x16x32_bf16 v[6:9], v[172:175], v[226:229], v[6:9]
	v_mfma_f32_16x16x32_bf16 v[2:5], v[180:183], v[226:229], v[2:5]
	v_mfma_f32_16x16x32_bf16 v[54:57], v[176:179], v[206:209], v[54:57]
	v_mfma_f32_16x16x32_bf16 v[50:53], v[184:187], v[206:209], v[50:53]
	v_mfma_f32_16x16x32_bf16 v[38:41], v[176:179], v[214:217], v[38:41]
	v_mfma_f32_16x16x32_bf16 v[34:37], v[184:187], v[214:217], v[34:37]
	v_mfma_f32_16x16x32_bf16 v[22:25], v[176:179], v[222:225], v[22:25]
	v_mfma_f32_16x16x32_bf16 v[18:21], v[184:187], v[222:225], v[18:21]
	v_mfma_f32_16x16x32_bf16 v[6:9], v[176:179], v[230:233], v[6:9]
	v_mfma_f32_16x16x32_bf16 v[2:5], v[184:187], v[230:233], v[2:5]
	s_barrier
	s_add_i32 s29, s29, 2
	s_add_u32 s30, s30, 0x100
	s_addc_u32 s31, s31, 0
	s_add_u32 s34, s34, 0x100
	s_addc_u32 s35, s35, 0
	s_cmpk_gt_u32 s29, 0x55
	s_cbranch_scc0 .LBB0_1675
	s_and_b64 vcc, exec, s[14:15]
	s_cbranch_vccz .LBB0_1678
	s_barrier
